# prologue: x->hb fast block, run FIRST by waves 4-7 and after the weight transposes by waves 0-3, so each SIMD overlaps a streaming wave with a latency-bound wave
# speedup vs baseline: 1.0060x; 1.0060x over previous
; __device__ __forceinline__ unsigned pk2(float lo, float hi) { return f2bf(lo) | (f2bf(hi) << 16); }
; #define lane (hw_lane())
; #define ws   (fresh_ptr(a.ws))
; __device__ __forceinline__ void prologue(const Args& a, LAS unsigned char* lds, int gw, int NGW, int lane, int wave) {
;     ...
;     for (int it = gw; it < DEPTH * PER_L; it += NGW) {
;         const int l = it / PER_L; int r = it % PER_L; unsigned char* wl = ws + WS_W + (size_t)l * W_LAYER;
;     ...
;         for (int m = gw; m < M + MMEM; m += NGW) {
;             const bool is_mem = m >= M; const int row = is_mem ? m - M : m;
;             f32x4 v[4]; float s = 0.f;
; #pragma unroll
;             for (int j = 0; j < 4; ++j) v[j] = nv[j];
;             { const int mn = m + NGW; if (mn < M + MMEM) { const f32x4* xr = (const f32x4*)((mn >= M ? a.in[I_MEM] + (size_t)(mn - M) * D : a.in[I_X] + (size_t)mn * D)) + lane;
; #pragma unroll
;                 for (int j = 0; j < 4; ++j) nv[j] = __builtin_nontemporal_load(xr + 64 * j); } }
; #pragma unroll
;             for (int j = 0; j < 4; ++j) s += (v[j].x * v[j].x + v[j].y * v[j].y) + (v[j].z * v[j].z + v[j].w * v[j].w);
;             s = wave_sum(s);
;             float sc = 1.f;
;             if (is_mem) sc = __builtin_amdgcn_rsqf(s * (1.0f / D) + EPS);
;             else if (lane < 16) slots[(size_t)row * 16 + lane] = lane == 0 ? s : 0.f;
;             v2u* o8 = (v2u*)((is_mem ? MEMN : HB) + (size_t)row * D) + lane;
; #pragma unroll
;             for (int j = 0; j < 4; ++j) { v2u o; o.x = pk2(v[j].x * sc, v[j].y * sc); o.y = pk2(v[j].z * sc, v[j].w * sc); o8[64 * j] = o; }
.LBB0_9:
	s_or_b64 exec, exec, s[0:1]
	s_lshr_b32 s0, s14, 6
	v_writelane_b32 v253, s0, 19
	v_writelane_b32 v253, s76, 20
	s_lshl_b32 s61, s92, 3
	s_lshl_b32 s2, s8, 3
	v_writelane_b32 v253, s77, 21
	v_writelane_b32 v253, s78, 22
	v_writelane_b32 v253, s79, 23
	v_writelane_b32 v253, s80, 24
	v_writelane_b32 v253, s81, 25
	v_writelane_b32 v253, s82, 26
	v_writelane_b32 v253, s83, 27
	v_writelane_b32 v253, s84, 28
	v_writelane_b32 v253, s85, 29
	v_writelane_b32 v253, s86, 30
	v_writelane_b32 v253, s87, 31
	v_writelane_b32 v253, s88, 32
	v_writelane_b32 v253, s89, 33
	s_add_i32 s0, s0, s61
	v_writelane_b32 v253, s90, 34
	s_mov_b32 s72, s0
	s_cmpk_lt_i32 s0, 0x3b40
	v_writelane_b32 v253, s91, 35
	v_mbcnt_lo_u32_b32 v36, -1, 0
	v_mbcnt_hi_u32_b32 v36, -1, v36
	s_mov_b32 s98, 0
	s_mov_b32 s99, 0
	s_bitcmp1_b32 s72, 2
	s_cbranch_scc0 .Lxe_skip
	s_cmp_lg_u32 s2, 0x800
	s_cbranch_scc1 .Lxe_skip
	s_cmp_ge_u32 s72, 0x800
	s_cbranch_scc1 .Lxe_skip
	v_readlane_b32 s10, v253, 20
	v_readlane_b32 s11, v253, 21
	s_lshl_b32 s0, s72, 12
	s_lshl_b32 s1, s72, 11
	s_lshl_b32 s3, s72, 6
	v_lshlrev_b32_e32 v104, 4, v36
	v_lshlrev_b32_e32 v105, 3, v36
	v_lshlrev_b32_e32 v106, 2, v36
	s_add_u32 s10, s10, s0
	s_addc_u32 s11, s11, 0
	s_add_u32 s12, s58, 0x7100000
	s_addc_u32 s13, s59, 0
	s_add_u32 s14, s58, 0x5500000
	s_addc_u32 s15, s59, 0
	v_xor_b32_e32 v107, 16, v36
	v_xor_b32_e32 v108, 32, v36
	s_add_u32 s12, s12, s1
	s_addc_u32 s13, s13, 0
	s_add_u32 s14, s14, s3
	s_addc_u32 s15, s15, 0
	v_lshlrev_b32_e32 v107, 2, v107
	v_lshlrev_b32_e32 v108, 2, v108
	v_mov_b32_e32 v109, 0
	v_cmp_gt_u32_e64 s[4:5], 16, v36
	v_cmp_eq_u32_e64 s[16:17], 0, v36
	global_load_dwordx4 v[40:43], v104, s[10:11] nt
	global_load_dwordx4 v[44:47], v104, s[10:11] offset:1024 nt
	global_load_dwordx4 v[48:51], v104, s[10:11] offset:2048 nt
	global_load_dwordx4 v[52:55], v104, s[10:11] offset:3072 nt
	s_add_u32 s10, s10, 0x800000
	s_addc_u32 s11, s11, 0
	global_load_dwordx4 v[56:59], v104, s[10:11] nt
	global_load_dwordx4 v[60:63], v104, s[10:11] offset:1024 nt
	global_load_dwordx4 v[64:67], v104, s[10:11] offset:2048 nt
	global_load_dwordx4 v[68:71], v104, s[10:11] offset:3072 nt
	s_add_u32 s10, s10, 0x800000
	s_addc_u32 s11, s11, 0
	global_load_dwordx4 v[72:75], v104, s[10:11] nt
	global_load_dwordx4 v[76:79], v104, s[10:11] offset:1024 nt
	global_load_dwordx4 v[80:83], v104, s[10:11] offset:2048 nt
	global_load_dwordx4 v[84:87], v104, s[10:11] offset:3072 nt
	s_add_u32 s10, s10, 0x800000
	s_addc_u32 s11, s11, 0
	global_load_dwordx4 v[88:91], v104, s[10:11] nt
	global_load_dwordx4 v[92:95], v104, s[10:11] offset:1024 nt
	global_load_dwordx4 v[96:99], v104, s[10:11] offset:2048 nt
	global_load_dwordx4 v[100:103], v104, s[10:11] offset:3072 nt
	s_add_u32 s10, s10, 0x800000
	s_addc_u32 s11, s11, 0
	global_load_dwordx4 v[176:179], v104, s[10:11] nt
	global_load_dwordx4 v[180:183], v104, s[10:11] offset:1024 nt
	global_load_dwordx4 v[184:187], v104, s[10:11] offset:2048 nt
	global_load_dwordx4 v[188:191], v104, s[10:11] offset:3072 nt
	s_add_u32 s10, s10, 0x800000
	s_addc_u32 s11, s11, 0
	global_load_dwordx4 v[192:195], v104, s[10:11] nt
	global_load_dwordx4 v[196:199], v104, s[10:11] offset:1024 nt
	global_load_dwordx4 v[200:203], v104, s[10:11] offset:2048 nt
	global_load_dwordx4 v[204:207], v104, s[10:11] offset:3072 nt
	s_add_u32 s10, s10, 0x800000
	s_addc_u32 s11, s11, 0
	global_load_dwordx4 v[208:211], v104, s[10:11] nt
	global_load_dwordx4 v[212:215], v104, s[10:11] offset:1024 nt
	global_load_dwordx4 v[216:219], v104, s[10:11] offset:2048 nt
	global_load_dwordx4 v[220:223], v104, s[10:11] offset:3072 nt
	s_add_u32 s10, s10, 0x800000
	s_addc_u32 s11, s11, 0
	global_load_dwordx4 v[224:227], v104, s[10:11] nt
	global_load_dwordx4 v[228:231], v104, s[10:11] offset:1024 nt
	global_load_dwordx4 v[232:235], v104, s[10:11] offset:2048 nt
	global_load_dwordx4 v[236:239], v104, s[10:11] offset:3072 nt
	s_add_u32 s10, s10, 0x800000
	s_addc_u32 s11, s11, 0
	s_waitcnt vmcnt(16)
	v_cvt_pk_bf16_f32 v16, v40, v41
	v_cvt_pk_bf16_f32 v17, v42, v43
	v_cvt_pk_bf16_f32 v18, v44, v45
	v_cvt_pk_bf16_f32 v19, v46, v47
	v_cvt_pk_bf16_f32 v20, v48, v49
	v_cvt_pk_bf16_f32 v21, v50, v51
	v_cvt_pk_bf16_f32 v22, v52, v53
	v_cvt_pk_bf16_f32 v23, v54, v55
	v_mul_f32_e32 v110, v40, v40
	v_fmac_f32_e32 v110, v41, v41
	v_fmac_f32_e32 v110, v42, v42
	v_fmac_f32_e32 v110, v43, v43
	v_fmac_f32_e32 v110, v44, v44
	v_fmac_f32_e32 v110, v45, v45
	v_fmac_f32_e32 v110, v46, v46
	v_fmac_f32_e32 v110, v47, v47
	v_fmac_f32_e32 v110, v48, v48
	v_fmac_f32_e32 v110, v49, v49
	v_fmac_f32_e32 v110, v50, v50
	v_fmac_f32_e32 v110, v51, v51
	v_fmac_f32_e32 v110, v52, v52
	v_fmac_f32_e32 v110, v53, v53
	v_fmac_f32_e32 v110, v54, v54
	v_fmac_f32_e32 v110, v55, v55
	global_store_dwordx2 v105, v[16:17], s[12:13]
	global_store_dwordx2 v105, v[18:19], s[12:13] offset:512
	global_store_dwordx2 v105, v[20:21], s[12:13] offset:1024
	global_store_dwordx2 v105, v[22:23], s[12:13] offset:1536
	s_add_u32 s12, s12, 0x400000
	s_addc_u32 s13, s13, 0
	v_cvt_pk_bf16_f32 v24, v56, v57
	v_cvt_pk_bf16_f32 v25, v58, v59
	v_cvt_pk_bf16_f32 v26, v60, v61
	v_cvt_pk_bf16_f32 v27, v62, v63
	v_cvt_pk_bf16_f32 v28, v64, v65
	v_cvt_pk_bf16_f32 v29, v66, v67
	v_cvt_pk_bf16_f32 v30, v68, v69
	v_cvt_pk_bf16_f32 v31, v70, v71
	v_mul_f32_e32 v111, v56, v56
	v_fmac_f32_e32 v111, v57, v57
	v_fmac_f32_e32 v111, v58, v58
	v_fmac_f32_e32 v111, v59, v59
	v_fmac_f32_e32 v111, v60, v60
	v_fmac_f32_e32 v111, v61, v61
	v_fmac_f32_e32 v111, v62, v62
	v_fmac_f32_e32 v111, v63, v63
	v_fmac_f32_e32 v111, v64, v64
	v_fmac_f32_e32 v111, v65, v65
	v_fmac_f32_e32 v111, v66, v66
; __device__ __forceinline__ unsigned pk2(float lo, float hi) { return f2bf(lo) | (f2bf(hi) << 16); }
; #define lane (hw_lane())
; __device__ __forceinline__ void prologue(const Args& a, LAS unsigned char* lds, int gw, int NGW, int lane, int wave) {
;     ...
;         for (int m = gw; m < M + MMEM; m += NGW) {
;             const bool is_mem = m >= M; const int row = is_mem ? m - M : m;
;             f32x4 v[4]; float s = 0.f;
; #pragma unroll
;             for (int j = 0; j < 4; ++j) v[j] = nv[j];
;             { const int mn = m + NGW; if (mn < M + MMEM) { const f32x4* xr = (const f32x4*)((mn >= M ? a.in[I_MEM] + (size_t)(mn - M) * D : a.in[I_X] + (size_t)mn * D)) + lane;
; #pragma unroll
;                 for (int j = 0; j < 4; ++j) nv[j] = __builtin_nontemporal_load(xr + 64 * j); } }
; #pragma unroll
;             for (int j = 0; j < 4; ++j) s += (v[j].x * v[j].x + v[j].y * v[j].y) + (v[j].z * v[j].z + v[j].w * v[j].w);
;             s = wave_sum(s);
;             float sc = 1.f;
;             if (is_mem) sc = __builtin_amdgcn_rsqf(s * (1.0f / D) + EPS);
;             else if (lane < 16) slots[(size_t)row * 16 + lane] = lane == 0 ? s : 0.f;
;             v2u* o8 = (v2u*)((is_mem ? MEMN : HB) + (size_t)row * D) + lane;
; #pragma unroll
;             for (int j = 0; j < 4; ++j) { v2u o; o.x = pk2(v[j].x * sc, v[j].y * sc); o.y = pk2(v[j].z * sc, v[j].w * sc); o8[64 * j] = o; }
	v_fmac_f32_e32 v111, v67, v67
	v_fmac_f32_e32 v111, v68, v68
	v_fmac_f32_e32 v111, v69, v69
	v_fmac_f32_e32 v111, v70, v70
	v_fmac_f32_e32 v111, v71, v71
	global_store_dwordx2 v105, v[24:25], s[12:13]
	global_store_dwordx2 v105, v[26:27], s[12:13] offset:512
	global_store_dwordx2 v105, v[28:29], s[12:13] offset:1024
	global_store_dwordx2 v105, v[30:31], s[12:13] offset:1536
	s_add_u32 s12, s12, 0x400000
	s_addc_u32 s13, s13, 0
	v_cvt_pk_bf16_f32 v16, v72, v73
	v_cvt_pk_bf16_f32 v17, v74, v75
	v_cvt_pk_bf16_f32 v18, v76, v77
	v_cvt_pk_bf16_f32 v19, v78, v79
	v_cvt_pk_bf16_f32 v20, v80, v81
	v_cvt_pk_bf16_f32 v21, v82, v83
	v_cvt_pk_bf16_f32 v22, v84, v85
	v_cvt_pk_bf16_f32 v23, v86, v87
	v_mul_f32_e32 v112, v72, v72
	v_fmac_f32_e32 v112, v73, v73
	v_fmac_f32_e32 v112, v74, v74
	v_fmac_f32_e32 v112, v75, v75
	v_fmac_f32_e32 v112, v76, v76
	v_fmac_f32_e32 v112, v77, v77
	v_fmac_f32_e32 v112, v78, v78
	v_fmac_f32_e32 v112, v79, v79
	v_fmac_f32_e32 v112, v80, v80
	v_fmac_f32_e32 v112, v81, v81
	v_fmac_f32_e32 v112, v82, v82
	v_fmac_f32_e32 v112, v83, v83
	v_fmac_f32_e32 v112, v84, v84
	v_fmac_f32_e32 v112, v85, v85
	v_fmac_f32_e32 v112, v86, v86
	v_fmac_f32_e32 v112, v87, v87
	global_store_dwordx2 v105, v[16:17], s[12:13]
	global_store_dwordx2 v105, v[18:19], s[12:13] offset:512
	global_store_dwordx2 v105, v[20:21], s[12:13] offset:1024
	global_store_dwordx2 v105, v[22:23], s[12:13] offset:1536
	s_add_u32 s12, s12, 0x400000
	s_addc_u32 s13, s13, 0
	v_cvt_pk_bf16_f32 v24, v88, v89
	v_cvt_pk_bf16_f32 v25, v90, v91
	v_cvt_pk_bf16_f32 v26, v92, v93
	v_cvt_pk_bf16_f32 v27, v94, v95
	v_cvt_pk_bf16_f32 v28, v96, v97
	v_cvt_pk_bf16_f32 v29, v98, v99
	v_cvt_pk_bf16_f32 v30, v100, v101
	v_cvt_pk_bf16_f32 v31, v102, v103
	v_mul_f32_e32 v113, v88, v88
	v_fmac_f32_e32 v113, v89, v89
	v_fmac_f32_e32 v113, v90, v90
	v_fmac_f32_e32 v113, v91, v91
	v_fmac_f32_e32 v113, v92, v92
	v_fmac_f32_e32 v113, v93, v93
	v_fmac_f32_e32 v113, v94, v94
	v_fmac_f32_e32 v113, v95, v95
	v_fmac_f32_e32 v113, v96, v96
	v_fmac_f32_e32 v113, v97, v97
	v_fmac_f32_e32 v113, v98, v98
	v_fmac_f32_e32 v113, v99, v99
	v_fmac_f32_e32 v113, v100, v100
	v_fmac_f32_e32 v113, v101, v101
	v_fmac_f32_e32 v113, v102, v102
	v_fmac_f32_e32 v113, v103, v103
	global_store_dwordx2 v105, v[24:25], s[12:13]
	global_store_dwordx2 v105, v[26:27], s[12:13] offset:512
	global_store_dwordx2 v105, v[28:29], s[12:13] offset:1024
	global_store_dwordx2 v105, v[30:31], s[12:13] offset:1536
	s_add_u32 s12, s12, 0x400000
	s_addc_u32 s13, s13, 0
	v_add_f32_dpp v114, v110, v110 row_ror:8 row_mask:0xf bank_mask:0xf
	v_add_f32_dpp v115, v111, v111 row_ror:8 row_mask:0xf bank_mask:0xf
	v_add_f32_dpp v116, v112, v112 row_ror:8 row_mask:0xf bank_mask:0xf
	v_add_f32_dpp v117, v113, v113 row_ror:8 row_mask:0xf bank_mask:0xf
	v_add_f32_dpp v110, v114, v114 row_ror:4 row_mask:0xf bank_mask:0xf
	v_add_f32_dpp v111, v115, v115 row_ror:4 row_mask:0xf bank_mask:0xf
	v_add_f32_dpp v112, v116, v116 row_ror:4 row_mask:0xf bank_mask:0xf
	v_add_f32_dpp v113, v117, v117 row_ror:4 row_mask:0xf bank_mask:0xf
	v_add_f32_dpp v114, v110, v110 row_ror:2 row_mask:0xf bank_mask:0xf
	v_add_f32_dpp v115, v111, v111 row_ror:2 row_mask:0xf bank_mask:0xf
	v_add_f32_dpp v116, v112, v112 row_ror:2 row_mask:0xf bank_mask:0xf
	v_add_f32_dpp v117, v113, v113 row_ror:2 row_mask:0xf bank_mask:0xf
	v_add_f32_dpp v110, v114, v114 row_ror:1 row_mask:0xf bank_mask:0xf
	v_add_f32_dpp v111, v115, v115 row_ror:1 row_mask:0xf bank_mask:0xf
	v_add_f32_dpp v112, v116, v116 row_ror:1 row_mask:0xf bank_mask:0xf
	v_add_f32_dpp v113, v117, v117 row_ror:1 row_mask:0xf bank_mask:0xf
	ds_bpermute_b32 v114, v107, v110
	ds_bpermute_b32 v115, v107, v111
	ds_bpermute_b32 v116, v107, v112
	ds_bpermute_b32 v117, v107, v113
	s_waitcnt lgkmcnt(0)
	v_add_f32_e32 v110, v110, v114
	v_add_f32_e32 v111, v111, v115
	v_add_f32_e32 v112, v112, v116
	v_add_f32_e32 v113, v113, v117
	ds_bpermute_b32 v114, v108, v110
	ds_bpermute_b32 v115, v108, v111
	ds_bpermute_b32 v116, v108, v112
	ds_bpermute_b32 v117, v108, v113
	s_waitcnt lgkmcnt(0)
	v_add_f32_e32 v110, v110, v114
	v_add_f32_e32 v111, v111, v115
	v_add_f32_e32 v112, v112, v116
	v_add_f32_e32 v113, v113, v117
	v_cndmask_b32_e64 v110, v109, v110, s[16:17]
	v_cndmask_b32_e64 v111, v109, v111, s[16:17]
	v_cndmask_b32_e64 v112, v109, v112, s[16:17]
	v_cndmask_b32_e64 v113, v109, v113, s[16:17]
	s_and_saveexec_b64 s[18:19], s[4:5]
	global_store_dword v106, v110, s[14:15]
	s_add_u32 s14, s14, 0x20000
	s_addc_u32 s15, s15, 0
	global_store_dword v106, v111, s[14:15]
	s_add_u32 s14, s14, 0x20000
	s_addc_u32 s15, s15, 0
	global_store_dword v106, v112, s[14:15]
	s_add_u32 s14, s14, 0x20000
	s_addc_u32 s15, s15, 0
	global_store_dword v106, v113, s[14:15]
	s_add_u32 s14, s14, 0x20000
	s_addc_u32 s15, s15, 0
	s_mov_b64 exec, s[18:19]
	global_load_dwordx4 v[40:43], v104, s[10:11] nt
	global_load_dwordx4 v[44:47], v104, s[10:11] offset:1024 nt
	global_load_dwordx4 v[48:51], v104, s[10:11] offset:2048 nt
	global_load_dwordx4 v[52:55], v104, s[10:11] offset:3072 nt
	s_add_u32 s10, s10, 0x800000
	s_addc_u32 s11, s11, 0
	global_load_dwordx4 v[56:59], v104, s[10:11] nt
	global_load_dwordx4 v[60:63], v104, s[10:11] offset:1024 nt
	global_load_dwordx4 v[64:67], v104, s[10:11] offset:2048 nt
	global_load_dwordx4 v[68:71], v104, s[10:11] offset:3072 nt
	s_add_u32 s10, s10, 0x800000
	s_addc_u32 s11, s11, 0
	global_load_dwordx4 v[72:75], v104, s[10:11] nt
	global_load_dwordx4 v[76:79], v104, s[10:11] offset:1024 nt
	global_load_dwordx4 v[80:83], v104, s[10:11] offset:2048 nt
	global_load_dwordx4 v[84:87], v104, s[10:11] offset:3072 nt
	s_add_u32 s10, s10, 0x800000
	s_addc_u32 s11, s11, 0
	global_load_dwordx4 v[88:91], v104, s[10:11] nt
	global_load_dwordx4 v[92:95], v104, s[10:11] offset:1024 nt
	global_load_dwordx4 v[96:99], v104, s[10:11] offset:2048 nt
	global_load_dwordx4 v[100:103], v104, s[10:11] offset:3072 nt
	s_add_u32 s10, s10, 0x800000
	s_addc_u32 s11, s11, 0
	s_waitcnt vmcnt(36)
; __device__ __forceinline__ unsigned pk2(float lo, float hi) { return f2bf(lo) | (f2bf(hi) << 16); }
; #define lane (hw_lane())
; __device__ __forceinline__ float wave_sum(float v) {
; #pragma unroll
;     for (int o = 1; o < 64; o <<= 1) v += __shfl_xor(v, o);
;     return v;
; __device__ __forceinline__ void prologue(const Args& a, LAS unsigned char* lds, int gw, int NGW, int lane, int wave) {
;     ...
;         for (int m = gw; m < M + MMEM; m += NGW) {
;             const bool is_mem = m >= M; const int row = is_mem ? m - M : m;
;             f32x4 v[4]; float s = 0.f;
; #pragma unroll
;             for (int j = 0; j < 4; ++j) v[j] = nv[j];
;             { const int mn = m + NGW; if (mn < M + MMEM) { const f32x4* xr = (const f32x4*)((mn >= M ? a.in[I_MEM] + (size_t)(mn - M) * D : a.in[I_X] + (size_t)mn * D)) + lane;
; #pragma unroll
;                 for (int j = 0; j < 4; ++j) nv[j] = __builtin_nontemporal_load(xr + 64 * j); } }
; #pragma unroll
;             for (int j = 0; j < 4; ++j) s += (v[j].x * v[j].x + v[j].y * v[j].y) + (v[j].z * v[j].z + v[j].w * v[j].w);
;             s = wave_sum(s);
;             float sc = 1.f;
;             if (is_mem) sc = __builtin_amdgcn_rsqf(s * (1.0f / D) + EPS);
;             else if (lane < 16) slots[(size_t)row * 16 + lane] = lane == 0 ? s : 0.f;
;             v2u* o8 = (v2u*)((is_mem ? MEMN : HB) + (size_t)row * D) + lane;
; #pragma unroll
;             for (int j = 0; j < 4; ++j) { v2u o; o.x = pk2(v[j].x * sc, v[j].y * sc); o.y = pk2(v[j].z * sc, v[j].w * sc); o8[64 * j] = o; }
	v_cvt_pk_bf16_f32 v16, v176, v177
	v_cvt_pk_bf16_f32 v17, v178, v179
	v_cvt_pk_bf16_f32 v18, v180, v181
	v_cvt_pk_bf16_f32 v19, v182, v183
	v_cvt_pk_bf16_f32 v20, v184, v185
	v_cvt_pk_bf16_f32 v21, v186, v187
	v_cvt_pk_bf16_f32 v22, v188, v189
	v_cvt_pk_bf16_f32 v23, v190, v191
	v_mul_f32_e32 v110, v176, v176
	v_fmac_f32_e32 v110, v177, v177
	v_fmac_f32_e32 v110, v178, v178
	v_fmac_f32_e32 v110, v179, v179
	v_fmac_f32_e32 v110, v180, v180
	v_fmac_f32_e32 v110, v181, v181
	v_fmac_f32_e32 v110, v182, v182
	v_fmac_f32_e32 v110, v183, v183
	v_fmac_f32_e32 v110, v184, v184
	v_fmac_f32_e32 v110, v185, v185
	v_fmac_f32_e32 v110, v186, v186
	v_fmac_f32_e32 v110, v187, v187
	v_fmac_f32_e32 v110, v188, v188
	v_fmac_f32_e32 v110, v189, v189
	v_fmac_f32_e32 v110, v190, v190
	v_fmac_f32_e32 v110, v191, v191
	global_store_dwordx2 v105, v[16:17], s[12:13]
	global_store_dwordx2 v105, v[18:19], s[12:13] offset:512
	global_store_dwordx2 v105, v[20:21], s[12:13] offset:1024
	global_store_dwordx2 v105, v[22:23], s[12:13] offset:1536
	s_add_u32 s12, s12, 0x400000
	s_addc_u32 s13, s13, 0
	v_cvt_pk_bf16_f32 v24, v192, v193
	v_cvt_pk_bf16_f32 v25, v194, v195
	v_cvt_pk_bf16_f32 v26, v196, v197
	v_cvt_pk_bf16_f32 v27, v198, v199
	v_cvt_pk_bf16_f32 v28, v200, v201
	v_cvt_pk_bf16_f32 v29, v202, v203
	v_cvt_pk_bf16_f32 v30, v204, v205
	v_cvt_pk_bf16_f32 v31, v206, v207
	v_mul_f32_e32 v111, v192, v192
	v_fmac_f32_e32 v111, v193, v193
	v_fmac_f32_e32 v111, v194, v194
	v_fmac_f32_e32 v111, v195, v195
	v_fmac_f32_e32 v111, v196, v196
	v_fmac_f32_e32 v111, v197, v197
	v_fmac_f32_e32 v111, v198, v198
	v_fmac_f32_e32 v111, v199, v199
	v_fmac_f32_e32 v111, v200, v200
	v_fmac_f32_e32 v111, v201, v201
	v_fmac_f32_e32 v111, v202, v202
	v_fmac_f32_e32 v111, v203, v203
	v_fmac_f32_e32 v111, v204, v204
	v_fmac_f32_e32 v111, v205, v205
	v_fmac_f32_e32 v111, v206, v206
	v_fmac_f32_e32 v111, v207, v207
	global_store_dwordx2 v105, v[24:25], s[12:13]
	global_store_dwordx2 v105, v[26:27], s[12:13] offset:512
	global_store_dwordx2 v105, v[28:29], s[12:13] offset:1024
	global_store_dwordx2 v105, v[30:31], s[12:13] offset:1536
	s_add_u32 s12, s12, 0x400000
	s_addc_u32 s13, s13, 0
	v_cvt_pk_bf16_f32 v16, v208, v209
	v_cvt_pk_bf16_f32 v17, v210, v211
	v_cvt_pk_bf16_f32 v18, v212, v213
	v_cvt_pk_bf16_f32 v19, v214, v215
	v_cvt_pk_bf16_f32 v20, v216, v217
	v_cvt_pk_bf16_f32 v21, v218, v219
	v_cvt_pk_bf16_f32 v22, v220, v221
	v_cvt_pk_bf16_f32 v23, v222, v223
	v_mul_f32_e32 v112, v208, v208
	v_fmac_f32_e32 v112, v209, v209
	v_fmac_f32_e32 v112, v210, v210
	v_fmac_f32_e32 v112, v211, v211
	v_fmac_f32_e32 v112, v212, v212
	v_fmac_f32_e32 v112, v213, v213
	v_fmac_f32_e32 v112, v214, v214
	v_fmac_f32_e32 v112, v215, v215
	v_fmac_f32_e32 v112, v216, v216
	v_fmac_f32_e32 v112, v217, v217
	v_fmac_f32_e32 v112, v218, v218
	v_fmac_f32_e32 v112, v219, v219
	v_fmac_f32_e32 v112, v220, v220
	v_fmac_f32_e32 v112, v221, v221
	v_fmac_f32_e32 v112, v222, v222
	v_fmac_f32_e32 v112, v223, v223
	global_store_dwordx2 v105, v[16:17], s[12:13]
	global_store_dwordx2 v105, v[18:19], s[12:13] offset:512
	global_store_dwordx2 v105, v[20:21], s[12:13] offset:1024
	global_store_dwordx2 v105, v[22:23], s[12:13] offset:1536
	s_add_u32 s12, s12, 0x400000
	s_addc_u32 s13, s13, 0
	v_cvt_pk_bf16_f32 v24, v224, v225
	v_cvt_pk_bf16_f32 v25, v226, v227
	v_cvt_pk_bf16_f32 v26, v228, v229
	v_cvt_pk_bf16_f32 v27, v230, v231
	v_cvt_pk_bf16_f32 v28, v232, v233
	v_cvt_pk_bf16_f32 v29, v234, v235
	v_cvt_pk_bf16_f32 v30, v236, v237
	v_cvt_pk_bf16_f32 v31, v238, v239
	v_mul_f32_e32 v113, v224, v224
	v_fmac_f32_e32 v113, v225, v225
	v_fmac_f32_e32 v113, v226, v226
	v_fmac_f32_e32 v113, v227, v227
	v_fmac_f32_e32 v113, v228, v228
	v_fmac_f32_e32 v113, v229, v229
	v_fmac_f32_e32 v113, v230, v230
	v_fmac_f32_e32 v113, v231, v231
	v_fmac_f32_e32 v113, v232, v232
	v_fmac_f32_e32 v113, v233, v233
	v_fmac_f32_e32 v113, v234, v234
	v_fmac_f32_e32 v113, v235, v235
	v_fmac_f32_e32 v113, v236, v236
	v_fmac_f32_e32 v113, v237, v237
	v_fmac_f32_e32 v113, v238, v238
	v_fmac_f32_e32 v113, v239, v239
	global_store_dwordx2 v105, v[24:25], s[12:13]
	global_store_dwordx2 v105, v[26:27], s[12:13] offset:512
	global_store_dwordx2 v105, v[28:29], s[12:13] offset:1024
	global_store_dwordx2 v105, v[30:31], s[12:13] offset:1536
	s_add_u32 s12, s12, 0x400000
	s_addc_u32 s13, s13, 0
	v_add_f32_dpp v114, v110, v110 row_ror:8 row_mask:0xf bank_mask:0xf
	v_add_f32_dpp v115, v111, v111 row_ror:8 row_mask:0xf bank_mask:0xf
	v_add_f32_dpp v116, v112, v112 row_ror:8 row_mask:0xf bank_mask:0xf
	v_add_f32_dpp v117, v113, v113 row_ror:8 row_mask:0xf bank_mask:0xf
	v_add_f32_dpp v110, v114, v114 row_ror:4 row_mask:0xf bank_mask:0xf
	v_add_f32_dpp v111, v115, v115 row_ror:4 row_mask:0xf bank_mask:0xf
	v_add_f32_dpp v112, v116, v116 row_ror:4 row_mask:0xf bank_mask:0xf
	v_add_f32_dpp v113, v117, v117 row_ror:4 row_mask:0xf bank_mask:0xf
	v_add_f32_dpp v114, v110, v110 row_ror:2 row_mask:0xf bank_mask:0xf
	v_add_f32_dpp v115, v111, v111 row_ror:2 row_mask:0xf bank_mask:0xf
	v_add_f32_dpp v116, v112, v112 row_ror:2 row_mask:0xf bank_mask:0xf
	v_add_f32_dpp v117, v113, v113 row_ror:2 row_mask:0xf bank_mask:0xf
	v_add_f32_dpp v110, v114, v114 row_ror:1 row_mask:0xf bank_mask:0xf
	v_add_f32_dpp v111, v115, v115 row_ror:1 row_mask:0xf bank_mask:0xf
	v_add_f32_dpp v112, v116, v116 row_ror:1 row_mask:0xf bank_mask:0xf
	v_add_f32_dpp v113, v117, v117 row_ror:1 row_mask:0xf bank_mask:0xf
	ds_bpermute_b32 v114, v107, v110
	ds_bpermute_b32 v115, v107, v111
	ds_bpermute_b32 v116, v107, v112
	ds_bpermute_b32 v117, v107, v113
	s_waitcnt lgkmcnt(0)
; __device__ __forceinline__ unsigned pk2(float lo, float hi) { return f2bf(lo) | (f2bf(hi) << 16); }
; #define lane (hw_lane())
; __device__ __forceinline__ float wave_sum(float v) {
; #pragma unroll
;     for (int o = 1; o < 64; o <<= 1) v += __shfl_xor(v, o);
;     return v;
; __device__ __forceinline__ void prologue(const Args& a, LAS unsigned char* lds, int gw, int NGW, int lane, int wave) {
;     ...
;         for (int m = gw; m < M + MMEM; m += NGW) {
;             const bool is_mem = m >= M; const int row = is_mem ? m - M : m;
;             f32x4 v[4]; float s = 0.f;
; #pragma unroll
;             for (int j = 0; j < 4; ++j) v[j] = nv[j];
;             { const int mn = m + NGW; if (mn < M + MMEM) { const f32x4* xr = (const f32x4*)((mn >= M ? a.in[I_MEM] + (size_t)(mn - M) * D : a.in[I_X] + (size_t)mn * D)) + lane;
; #pragma unroll
;                 for (int j = 0; j < 4; ++j) nv[j] = __builtin_nontemporal_load(xr + 64 * j); } }
; #pragma unroll
;             for (int j = 0; j < 4; ++j) s += (v[j].x * v[j].x + v[j].y * v[j].y) + (v[j].z * v[j].z + v[j].w * v[j].w);
;             s = wave_sum(s);
;             float sc = 1.f;
;             if (is_mem) sc = __builtin_amdgcn_rsqf(s * (1.0f / D) + EPS);
;             else if (lane < 16) slots[(size_t)row * 16 + lane] = lane == 0 ? s : 0.f;
;             v2u* o8 = (v2u*)((is_mem ? MEMN : HB) + (size_t)row * D) + lane;
; #pragma unroll
;             for (int j = 0; j < 4; ++j) { v2u o; o.x = pk2(v[j].x * sc, v[j].y * sc); o.y = pk2(v[j].z * sc, v[j].w * sc); o8[64 * j] = o; }
	v_add_f32_e32 v110, v110, v114
	v_add_f32_e32 v111, v111, v115
	v_add_f32_e32 v112, v112, v116
	v_add_f32_e32 v113, v113, v117
	ds_bpermute_b32 v114, v108, v110
	ds_bpermute_b32 v115, v108, v111
	ds_bpermute_b32 v116, v108, v112
	ds_bpermute_b32 v117, v108, v113
	s_waitcnt lgkmcnt(0)
	v_add_f32_e32 v110, v110, v114
	v_add_f32_e32 v111, v111, v115
	v_add_f32_e32 v112, v112, v116
	v_add_f32_e32 v113, v113, v117
	v_cndmask_b32_e64 v110, v109, v110, s[16:17]
	v_cndmask_b32_e64 v111, v109, v111, s[16:17]
	v_cndmask_b32_e64 v112, v109, v112, s[16:17]
	v_cndmask_b32_e64 v113, v109, v113, s[16:17]
	s_and_saveexec_b64 s[18:19], s[4:5]
	global_store_dword v106, v110, s[14:15]
	s_add_u32 s14, s14, 0x20000
	s_addc_u32 s15, s15, 0
	global_store_dword v106, v111, s[14:15]
	s_add_u32 s14, s14, 0x20000
	s_addc_u32 s15, s15, 0
	global_store_dword v106, v112, s[14:15]
	s_add_u32 s14, s14, 0x20000
	s_addc_u32 s15, s15, 0
	global_store_dword v106, v113, s[14:15]
	s_add_u32 s14, s14, 0x20000
	s_addc_u32 s15, s15, 0
	s_mov_b64 exec, s[18:19]
	global_load_dwordx4 v[176:179], v104, s[10:11] nt
	global_load_dwordx4 v[180:183], v104, s[10:11] offset:1024 nt
	global_load_dwordx4 v[184:187], v104, s[10:11] offset:2048 nt
	global_load_dwordx4 v[188:191], v104, s[10:11] offset:3072 nt
	s_add_u32 s10, s10, 0x800000
	s_addc_u32 s11, s11, 0
	global_load_dwordx4 v[192:195], v104, s[10:11] nt
	global_load_dwordx4 v[196:199], v104, s[10:11] offset:1024 nt
	global_load_dwordx4 v[200:203], v104, s[10:11] offset:2048 nt
	global_load_dwordx4 v[204:207], v104, s[10:11] offset:3072 nt
	s_add_u32 s10, s10, 0x800000
	s_addc_u32 s11, s11, 0
	global_load_dwordx4 v[208:211], v104, s[10:11] nt
	global_load_dwordx4 v[212:215], v104, s[10:11] offset:1024 nt
	global_load_dwordx4 v[216:219], v104, s[10:11] offset:2048 nt
	global_load_dwordx4 v[220:223], v104, s[10:11] offset:3072 nt
	s_add_u32 s10, s10, 0x800000
	s_addc_u32 s11, s11, 0
	global_load_dwordx4 v[224:227], v104, s[10:11] nt
	global_load_dwordx4 v[228:231], v104, s[10:11] offset:1024 nt
	global_load_dwordx4 v[232:235], v104, s[10:11] offset:2048 nt
	global_load_dwordx4 v[236:239], v104, s[10:11] offset:3072 nt
	s_add_u32 s10, s10, 0x800000
	s_addc_u32 s11, s11, 0
	s_waitcnt vmcnt(36)
	v_cvt_pk_bf16_f32 v16, v40, v41
	v_cvt_pk_bf16_f32 v17, v42, v43
	v_cvt_pk_bf16_f32 v18, v44, v45
	v_cvt_pk_bf16_f32 v19, v46, v47
	v_cvt_pk_bf16_f32 v20, v48, v49
	v_cvt_pk_bf16_f32 v21, v50, v51
	v_cvt_pk_bf16_f32 v22, v52, v53
	v_cvt_pk_bf16_f32 v23, v54, v55
	v_mul_f32_e32 v110, v40, v40
	v_fmac_f32_e32 v110, v41, v41
	v_fmac_f32_e32 v110, v42, v42
	v_fmac_f32_e32 v110, v43, v43
	v_fmac_f32_e32 v110, v44, v44
	v_fmac_f32_e32 v110, v45, v45
	v_fmac_f32_e32 v110, v46, v46
	v_fmac_f32_e32 v110, v47, v47
	v_fmac_f32_e32 v110, v48, v48
	v_fmac_f32_e32 v110, v49, v49
	v_fmac_f32_e32 v110, v50, v50
	v_fmac_f32_e32 v110, v51, v51
	v_fmac_f32_e32 v110, v52, v52
	v_fmac_f32_e32 v110, v53, v53
	v_fmac_f32_e32 v110, v54, v54
	v_fmac_f32_e32 v110, v55, v55
	global_store_dwordx2 v105, v[16:17], s[12:13]
	global_store_dwordx2 v105, v[18:19], s[12:13] offset:512
	global_store_dwordx2 v105, v[20:21], s[12:13] offset:1024
	global_store_dwordx2 v105, v[22:23], s[12:13] offset:1536
	s_add_u32 s12, s12, 0x400000
	s_addc_u32 s13, s13, 0
	v_cvt_pk_bf16_f32 v24, v56, v57
	v_cvt_pk_bf16_f32 v25, v58, v59
	v_cvt_pk_bf16_f32 v26, v60, v61
	v_cvt_pk_bf16_f32 v27, v62, v63
	v_cvt_pk_bf16_f32 v28, v64, v65
	v_cvt_pk_bf16_f32 v29, v66, v67
	v_cvt_pk_bf16_f32 v30, v68, v69
	v_cvt_pk_bf16_f32 v31, v70, v71
	v_mul_f32_e32 v111, v56, v56
	v_fmac_f32_e32 v111, v57, v57
	v_fmac_f32_e32 v111, v58, v58
	v_fmac_f32_e32 v111, v59, v59
	v_fmac_f32_e32 v111, v60, v60
	v_fmac_f32_e32 v111, v61, v61
	v_fmac_f32_e32 v111, v62, v62
	v_fmac_f32_e32 v111, v63, v63
	v_fmac_f32_e32 v111, v64, v64
	v_fmac_f32_e32 v111, v65, v65
	v_fmac_f32_e32 v111, v66, v66
	v_fmac_f32_e32 v111, v67, v67
	v_fmac_f32_e32 v111, v68, v68
	v_fmac_f32_e32 v111, v69, v69
	v_fmac_f32_e32 v111, v70, v70
	v_fmac_f32_e32 v111, v71, v71
	global_store_dwordx2 v105, v[24:25], s[12:13]
	global_store_dwordx2 v105, v[26:27], s[12:13] offset:512
	global_store_dwordx2 v105, v[28:29], s[12:13] offset:1024
	global_store_dwordx2 v105, v[30:31], s[12:13] offset:1536
	s_add_u32 s12, s12, 0x400000
	s_addc_u32 s13, s13, 0
	v_cvt_pk_bf16_f32 v16, v72, v73
	v_cvt_pk_bf16_f32 v17, v74, v75
	v_cvt_pk_bf16_f32 v18, v76, v77
	v_cvt_pk_bf16_f32 v19, v78, v79
	v_cvt_pk_bf16_f32 v20, v80, v81
	v_cvt_pk_bf16_f32 v21, v82, v83
	v_cvt_pk_bf16_f32 v22, v84, v85
	v_cvt_pk_bf16_f32 v23, v86, v87
	v_mul_f32_e32 v112, v72, v72
	v_fmac_f32_e32 v112, v73, v73
	v_fmac_f32_e32 v112, v74, v74
	v_fmac_f32_e32 v112, v75, v75
	v_fmac_f32_e32 v112, v76, v76
	v_fmac_f32_e32 v112, v77, v77
	v_fmac_f32_e32 v112, v78, v78
	v_fmac_f32_e32 v112, v79, v79
	v_fmac_f32_e32 v112, v80, v80
	v_fmac_f32_e32 v112, v81, v81
	v_fmac_f32_e32 v112, v82, v82
	v_fmac_f32_e32 v112, v83, v83
	v_fmac_f32_e32 v112, v84, v84
	v_fmac_f32_e32 v112, v85, v85
	v_fmac_f32_e32 v112, v86, v86
	v_fmac_f32_e32 v112, v87, v87
	global_store_dwordx2 v105, v[16:17], s[12:13]
	global_store_dwordx2 v105, v[18:19], s[12:13] offset:512
	global_store_dwordx2 v105, v[20:21], s[12:13] offset:1024
	global_store_dwordx2 v105, v[22:23], s[12:13] offset:1536
	s_add_u32 s12, s12, 0x400000
	s_addc_u32 s13, s13, 0
	v_cvt_pk_bf16_f32 v24, v88, v89
	v_cvt_pk_bf16_f32 v25, v90, v91
	v_cvt_pk_bf16_f32 v26, v92, v93
	v_cvt_pk_bf16_f32 v27, v94, v95
	v_cvt_pk_bf16_f32 v28, v96, v97
	v_cvt_pk_bf16_f32 v29, v98, v99
	v_cvt_pk_bf16_f32 v30, v100, v101
	v_cvt_pk_bf16_f32 v31, v102, v103
	v_mul_f32_e32 v113, v88, v88
; __device__ __forceinline__ unsigned pk2(float lo, float hi) { return f2bf(lo) | (f2bf(hi) << 16); }
; #define lane (hw_lane())
; __device__ __forceinline__ float wave_sum(float v) {
; #pragma unroll
;     for (int o = 1; o < 64; o <<= 1) v += __shfl_xor(v, o);
;     return v;
; __device__ __forceinline__ void prologue(const Args& a, LAS unsigned char* lds, int gw, int NGW, int lane, int wave) {
;     ...
;         for (int m = gw; m < M + MMEM; m += NGW) {
;             const bool is_mem = m >= M; const int row = is_mem ? m - M : m;
;             f32x4 v[4]; float s = 0.f;
; #pragma unroll
;             for (int j = 0; j < 4; ++j) v[j] = nv[j];
;             { const int mn = m + NGW; if (mn < M + MMEM) { const f32x4* xr = (const f32x4*)((mn >= M ? a.in[I_MEM] + (size_t)(mn - M) * D : a.in[I_X] + (size_t)mn * D)) + lane;
; #pragma unroll
;                 for (int j = 0; j < 4; ++j) nv[j] = __builtin_nontemporal_load(xr + 64 * j); } }
; #pragma unroll
;             for (int j = 0; j < 4; ++j) s += (v[j].x * v[j].x + v[j].y * v[j].y) + (v[j].z * v[j].z + v[j].w * v[j].w);
;             s = wave_sum(s);
;             float sc = 1.f;
;             if (is_mem) sc = __builtin_amdgcn_rsqf(s * (1.0f / D) + EPS);
;             else if (lane < 16) slots[(size_t)row * 16 + lane] = lane == 0 ? s : 0.f;
;             v2u* o8 = (v2u*)((is_mem ? MEMN : HB) + (size_t)row * D) + lane;
; #pragma unroll
;             for (int j = 0; j < 4; ++j) { v2u o; o.x = pk2(v[j].x * sc, v[j].y * sc); o.y = pk2(v[j].z * sc, v[j].w * sc); o8[64 * j] = o; }
	v_fmac_f32_e32 v113, v89, v89
	v_fmac_f32_e32 v113, v90, v90
	v_fmac_f32_e32 v113, v91, v91
	v_fmac_f32_e32 v113, v92, v92
	v_fmac_f32_e32 v113, v93, v93
	v_fmac_f32_e32 v113, v94, v94
	v_fmac_f32_e32 v113, v95, v95
	v_fmac_f32_e32 v113, v96, v96
	v_fmac_f32_e32 v113, v97, v97
	v_fmac_f32_e32 v113, v98, v98
	v_fmac_f32_e32 v113, v99, v99
	v_fmac_f32_e32 v113, v100, v100
	v_fmac_f32_e32 v113, v101, v101
	v_fmac_f32_e32 v113, v102, v102
	v_fmac_f32_e32 v113, v103, v103
	global_store_dwordx2 v105, v[24:25], s[12:13]
	global_store_dwordx2 v105, v[26:27], s[12:13] offset:512
	global_store_dwordx2 v105, v[28:29], s[12:13] offset:1024
	global_store_dwordx2 v105, v[30:31], s[12:13] offset:1536
	s_add_u32 s12, s12, 0x400000
	s_addc_u32 s13, s13, 0
	v_add_f32_dpp v114, v110, v110 row_ror:8 row_mask:0xf bank_mask:0xf
	v_add_f32_dpp v115, v111, v111 row_ror:8 row_mask:0xf bank_mask:0xf
	v_add_f32_dpp v116, v112, v112 row_ror:8 row_mask:0xf bank_mask:0xf
	v_add_f32_dpp v117, v113, v113 row_ror:8 row_mask:0xf bank_mask:0xf
	v_add_f32_dpp v110, v114, v114 row_ror:4 row_mask:0xf bank_mask:0xf
	v_add_f32_dpp v111, v115, v115 row_ror:4 row_mask:0xf bank_mask:0xf
	v_add_f32_dpp v112, v116, v116 row_ror:4 row_mask:0xf bank_mask:0xf
	v_add_f32_dpp v113, v117, v117 row_ror:4 row_mask:0xf bank_mask:0xf
	v_add_f32_dpp v114, v110, v110 row_ror:2 row_mask:0xf bank_mask:0xf
	v_add_f32_dpp v115, v111, v111 row_ror:2 row_mask:0xf bank_mask:0xf
	v_add_f32_dpp v116, v112, v112 row_ror:2 row_mask:0xf bank_mask:0xf
	v_add_f32_dpp v117, v113, v113 row_ror:2 row_mask:0xf bank_mask:0xf
	v_add_f32_dpp v110, v114, v114 row_ror:1 row_mask:0xf bank_mask:0xf
	v_add_f32_dpp v111, v115, v115 row_ror:1 row_mask:0xf bank_mask:0xf
	v_add_f32_dpp v112, v116, v116 row_ror:1 row_mask:0xf bank_mask:0xf
	v_add_f32_dpp v113, v117, v117 row_ror:1 row_mask:0xf bank_mask:0xf
	ds_bpermute_b32 v114, v107, v110
	ds_bpermute_b32 v115, v107, v111
	ds_bpermute_b32 v116, v107, v112
	ds_bpermute_b32 v117, v107, v113
	s_waitcnt lgkmcnt(0)
	v_add_f32_e32 v110, v110, v114
	v_add_f32_e32 v111, v111, v115
	v_add_f32_e32 v112, v112, v116
	v_add_f32_e32 v113, v113, v117
	ds_bpermute_b32 v114, v108, v110
	ds_bpermute_b32 v115, v108, v111
	ds_bpermute_b32 v116, v108, v112
	ds_bpermute_b32 v117, v108, v113
	s_waitcnt lgkmcnt(0)
	v_add_f32_e32 v110, v110, v114
	v_add_f32_e32 v111, v111, v115
	v_add_f32_e32 v112, v112, v116
	v_add_f32_e32 v113, v113, v117
	v_cndmask_b32_e64 v110, v109, v110, s[16:17]
	v_cndmask_b32_e64 v111, v109, v111, s[16:17]
	v_cndmask_b32_e64 v112, v109, v112, s[16:17]
	v_cndmask_b32_e64 v113, v109, v113, s[16:17]
	s_and_saveexec_b64 s[18:19], s[4:5]
	global_store_dword v106, v110, s[14:15]
	s_add_u32 s14, s14, 0x20000
	s_addc_u32 s15, s15, 0
	global_store_dword v106, v111, s[14:15]
	s_add_u32 s14, s14, 0x20000
	s_addc_u32 s15, s15, 0
	global_store_dword v106, v112, s[14:15]
	s_add_u32 s14, s14, 0x20000
	s_addc_u32 s15, s15, 0
	global_store_dword v106, v113, s[14:15]
	s_add_u32 s14, s14, 0x20000
	s_addc_u32 s15, s15, 0
	s_mov_b64 exec, s[18:19]
	global_load_dwordx4 v[40:43], v104, s[10:11] nt
	global_load_dwordx4 v[44:47], v104, s[10:11] offset:1024 nt
	global_load_dwordx4 v[48:51], v104, s[10:11] offset:2048 nt
	global_load_dwordx4 v[52:55], v104, s[10:11] offset:3072 nt
	s_add_u32 s10, s10, 0x800000
	s_addc_u32 s11, s11, 0
	global_load_dwordx4 v[56:59], v104, s[10:11] nt
	global_load_dwordx4 v[60:63], v104, s[10:11] offset:1024 nt
	global_load_dwordx4 v[64:67], v104, s[10:11] offset:2048 nt
	global_load_dwordx4 v[68:71], v104, s[10:11] offset:3072 nt
	s_add_u32 s10, s10, 0x800000
	s_addc_u32 s11, s11, 0
	global_load_dwordx4 v[72:75], v104, s[10:11] nt
	global_load_dwordx4 v[76:79], v104, s[10:11] offset:1024 nt
	global_load_dwordx4 v[80:83], v104, s[10:11] offset:2048 nt
	global_load_dwordx4 v[84:87], v104, s[10:11] offset:3072 nt
	s_add_u32 s10, s10, 0x800000
	s_addc_u32 s11, s11, 0
	global_load_dwordx4 v[88:91], v104, s[10:11] nt
	global_load_dwordx4 v[92:95], v104, s[10:11] offset:1024 nt
	global_load_dwordx4 v[96:99], v104, s[10:11] offset:2048 nt
	global_load_dwordx4 v[100:103], v104, s[10:11] offset:3072 nt
	s_add_u32 s10, s10, 0x800000
	s_addc_u32 s11, s11, 0
	s_waitcnt vmcnt(36)
	v_cvt_pk_bf16_f32 v16, v176, v177
	v_cvt_pk_bf16_f32 v17, v178, v179
	v_cvt_pk_bf16_f32 v18, v180, v181
	v_cvt_pk_bf16_f32 v19, v182, v183
	v_cvt_pk_bf16_f32 v20, v184, v185
	v_cvt_pk_bf16_f32 v21, v186, v187
	v_cvt_pk_bf16_f32 v22, v188, v189
	v_cvt_pk_bf16_f32 v23, v190, v191
	v_mul_f32_e32 v110, v176, v176
	v_fmac_f32_e32 v110, v177, v177
	v_fmac_f32_e32 v110, v178, v178
	v_fmac_f32_e32 v110, v179, v179
	v_fmac_f32_e32 v110, v180, v180
	v_fmac_f32_e32 v110, v181, v181
	v_fmac_f32_e32 v110, v182, v182
	v_fmac_f32_e32 v110, v183, v183
	v_fmac_f32_e32 v110, v184, v184
	v_fmac_f32_e32 v110, v185, v185
	v_fmac_f32_e32 v110, v186, v186
	v_fmac_f32_e32 v110, v187, v187
	v_fmac_f32_e32 v110, v188, v188
	v_fmac_f32_e32 v110, v189, v189
	v_fmac_f32_e32 v110, v190, v190
	v_fmac_f32_e32 v110, v191, v191
	global_store_dwordx2 v105, v[16:17], s[12:13]
	global_store_dwordx2 v105, v[18:19], s[12:13] offset:512
	global_store_dwordx2 v105, v[20:21], s[12:13] offset:1024
	global_store_dwordx2 v105, v[22:23], s[12:13] offset:1536
	s_add_u32 s12, s12, 0x400000
	s_addc_u32 s13, s13, 0
	v_cvt_pk_bf16_f32 v24, v192, v193
	v_cvt_pk_bf16_f32 v25, v194, v195
	v_cvt_pk_bf16_f32 v26, v196, v197
	v_cvt_pk_bf16_f32 v27, v198, v199
	v_cvt_pk_bf16_f32 v28, v200, v201
	v_cvt_pk_bf16_f32 v29, v202, v203
	v_cvt_pk_bf16_f32 v30, v204, v205
	v_cvt_pk_bf16_f32 v31, v206, v207
	v_mul_f32_e32 v111, v192, v192
	v_fmac_f32_e32 v111, v193, v193
; __device__ __forceinline__ unsigned pk2(float lo, float hi) { return f2bf(lo) | (f2bf(hi) << 16); }
; #define lane (hw_lane())
; __device__ __forceinline__ float wave_sum(float v) {
; #pragma unroll
;     for (int o = 1; o < 64; o <<= 1) v += __shfl_xor(v, o);
;     return v;
; __device__ __forceinline__ void prologue(const Args& a, LAS unsigned char* lds, int gw, int NGW, int lane, int wave) {
;     ...
;         for (int m = gw; m < M + MMEM; m += NGW) {
;             const bool is_mem = m >= M; const int row = is_mem ? m - M : m;
;             f32x4 v[4]; float s = 0.f;
; #pragma unroll
;             for (int j = 0; j < 4; ++j) v[j] = nv[j];
;             { const int mn = m + NGW; if (mn < M + MMEM) { const f32x4* xr = (const f32x4*)((mn >= M ? a.in[I_MEM] + (size_t)(mn - M) * D : a.in[I_X] + (size_t)mn * D)) + lane;
; #pragma unroll
;                 for (int j = 0; j < 4; ++j) nv[j] = __builtin_nontemporal_load(xr + 64 * j); } }
; #pragma unroll
;             for (int j = 0; j < 4; ++j) s += (v[j].x * v[j].x + v[j].y * v[j].y) + (v[j].z * v[j].z + v[j].w * v[j].w);
;             s = wave_sum(s);
;             float sc = 1.f;
;             if (is_mem) sc = __builtin_amdgcn_rsqf(s * (1.0f / D) + EPS);
;             else if (lane < 16) slots[(size_t)row * 16 + lane] = lane == 0 ? s : 0.f;
;             v2u* o8 = (v2u*)((is_mem ? MEMN : HB) + (size_t)row * D) + lane;
; #pragma unroll
;             for (int j = 0; j < 4; ++j) { v2u o; o.x = pk2(v[j].x * sc, v[j].y * sc); o.y = pk2(v[j].z * sc, v[j].w * sc); o8[64 * j] = o; }
	v_fmac_f32_e32 v111, v194, v194
	v_fmac_f32_e32 v111, v195, v195
	v_fmac_f32_e32 v111, v196, v196
	v_fmac_f32_e32 v111, v197, v197
	v_fmac_f32_e32 v111, v198, v198
	v_fmac_f32_e32 v111, v199, v199
	v_fmac_f32_e32 v111, v200, v200
	v_fmac_f32_e32 v111, v201, v201
	v_fmac_f32_e32 v111, v202, v202
	v_fmac_f32_e32 v111, v203, v203
	v_fmac_f32_e32 v111, v204, v204
	v_fmac_f32_e32 v111, v205, v205
	v_fmac_f32_e32 v111, v206, v206
	v_fmac_f32_e32 v111, v207, v207
	global_store_dwordx2 v105, v[24:25], s[12:13]
	global_store_dwordx2 v105, v[26:27], s[12:13] offset:512
	global_store_dwordx2 v105, v[28:29], s[12:13] offset:1024
	global_store_dwordx2 v105, v[30:31], s[12:13] offset:1536
	s_add_u32 s12, s12, 0x400000
	s_addc_u32 s13, s13, 0
	v_cvt_pk_bf16_f32 v16, v208, v209
	v_cvt_pk_bf16_f32 v17, v210, v211
	v_cvt_pk_bf16_f32 v18, v212, v213
	v_cvt_pk_bf16_f32 v19, v214, v215
	v_cvt_pk_bf16_f32 v20, v216, v217
	v_cvt_pk_bf16_f32 v21, v218, v219
	v_cvt_pk_bf16_f32 v22, v220, v221
	v_cvt_pk_bf16_f32 v23, v222, v223
	v_mul_f32_e32 v112, v208, v208
	v_fmac_f32_e32 v112, v209, v209
	v_fmac_f32_e32 v112, v210, v210
	v_fmac_f32_e32 v112, v211, v211
	v_fmac_f32_e32 v112, v212, v212
	v_fmac_f32_e32 v112, v213, v213
	v_fmac_f32_e32 v112, v214, v214
	v_fmac_f32_e32 v112, v215, v215
	v_fmac_f32_e32 v112, v216, v216
	v_fmac_f32_e32 v112, v217, v217
	v_fmac_f32_e32 v112, v218, v218
	v_fmac_f32_e32 v112, v219, v219
	v_fmac_f32_e32 v112, v220, v220
	v_fmac_f32_e32 v112, v221, v221
	v_fmac_f32_e32 v112, v222, v222
	v_fmac_f32_e32 v112, v223, v223
	global_store_dwordx2 v105, v[16:17], s[12:13]
	global_store_dwordx2 v105, v[18:19], s[12:13] offset:512
	global_store_dwordx2 v105, v[20:21], s[12:13] offset:1024
	global_store_dwordx2 v105, v[22:23], s[12:13] offset:1536
	s_add_u32 s12, s12, 0x400000
	s_addc_u32 s13, s13, 0
	v_cvt_pk_bf16_f32 v24, v224, v225
	v_cvt_pk_bf16_f32 v25, v226, v227
	v_cvt_pk_bf16_f32 v26, v228, v229
	v_cvt_pk_bf16_f32 v27, v230, v231
	v_cvt_pk_bf16_f32 v28, v232, v233
	v_cvt_pk_bf16_f32 v29, v234, v235
	v_cvt_pk_bf16_f32 v30, v236, v237
	v_cvt_pk_bf16_f32 v31, v238, v239
	v_mul_f32_e32 v113, v224, v224
	v_fmac_f32_e32 v113, v225, v225
	v_fmac_f32_e32 v113, v226, v226
	v_fmac_f32_e32 v113, v227, v227
	v_fmac_f32_e32 v113, v228, v228
	v_fmac_f32_e32 v113, v229, v229
	v_fmac_f32_e32 v113, v230, v230
	v_fmac_f32_e32 v113, v231, v231
	v_fmac_f32_e32 v113, v232, v232
	v_fmac_f32_e32 v113, v233, v233
	v_fmac_f32_e32 v113, v234, v234
	v_fmac_f32_e32 v113, v235, v235
	v_fmac_f32_e32 v113, v236, v236
	v_fmac_f32_e32 v113, v237, v237
	v_fmac_f32_e32 v113, v238, v238
	v_fmac_f32_e32 v113, v239, v239
	global_store_dwordx2 v105, v[24:25], s[12:13]
	global_store_dwordx2 v105, v[26:27], s[12:13] offset:512
	global_store_dwordx2 v105, v[28:29], s[12:13] offset:1024
	global_store_dwordx2 v105, v[30:31], s[12:13] offset:1536
	s_add_u32 s12, s12, 0x400000
	s_addc_u32 s13, s13, 0
	v_add_f32_dpp v114, v110, v110 row_ror:8 row_mask:0xf bank_mask:0xf
	v_add_f32_dpp v115, v111, v111 row_ror:8 row_mask:0xf bank_mask:0xf
	v_add_f32_dpp v116, v112, v112 row_ror:8 row_mask:0xf bank_mask:0xf
	v_add_f32_dpp v117, v113, v113 row_ror:8 row_mask:0xf bank_mask:0xf
	v_add_f32_dpp v110, v114, v114 row_ror:4 row_mask:0xf bank_mask:0xf
	v_add_f32_dpp v111, v115, v115 row_ror:4 row_mask:0xf bank_mask:0xf
	v_add_f32_dpp v112, v116, v116 row_ror:4 row_mask:0xf bank_mask:0xf
	v_add_f32_dpp v113, v117, v117 row_ror:4 row_mask:0xf bank_mask:0xf
	v_add_f32_dpp v114, v110, v110 row_ror:2 row_mask:0xf bank_mask:0xf
	v_add_f32_dpp v115, v111, v111 row_ror:2 row_mask:0xf bank_mask:0xf
	v_add_f32_dpp v116, v112, v112 row_ror:2 row_mask:0xf bank_mask:0xf
	v_add_f32_dpp v117, v113, v113 row_ror:2 row_mask:0xf bank_mask:0xf
	v_add_f32_dpp v110, v114, v114 row_ror:1 row_mask:0xf bank_mask:0xf
	v_add_f32_dpp v111, v115, v115 row_ror:1 row_mask:0xf bank_mask:0xf
	v_add_f32_dpp v112, v116, v116 row_ror:1 row_mask:0xf bank_mask:0xf
	v_add_f32_dpp v113, v117, v117 row_ror:1 row_mask:0xf bank_mask:0xf
	ds_bpermute_b32 v114, v107, v110
	ds_bpermute_b32 v115, v107, v111
	ds_bpermute_b32 v116, v107, v112
	ds_bpermute_b32 v117, v107, v113
	s_waitcnt lgkmcnt(0)
	v_add_f32_e32 v110, v110, v114
	v_add_f32_e32 v111, v111, v115
	v_add_f32_e32 v112, v112, v116
	v_add_f32_e32 v113, v113, v117
	ds_bpermute_b32 v114, v108, v110
	ds_bpermute_b32 v115, v108, v111
	ds_bpermute_b32 v116, v108, v112
	ds_bpermute_b32 v117, v108, v113
	s_waitcnt lgkmcnt(0)
	v_add_f32_e32 v110, v110, v114
	v_add_f32_e32 v111, v111, v115
	v_add_f32_e32 v112, v112, v116
	v_add_f32_e32 v113, v113, v117
	v_cndmask_b32_e64 v110, v109, v110, s[16:17]
	v_cndmask_b32_e64 v111, v109, v111, s[16:17]
	v_cndmask_b32_e64 v112, v109, v112, s[16:17]
	v_cndmask_b32_e64 v113, v109, v113, s[16:17]
	s_and_saveexec_b64 s[18:19], s[4:5]
	global_store_dword v106, v110, s[14:15]
	s_add_u32 s14, s14, 0x20000
	s_addc_u32 s15, s15, 0
	global_store_dword v106, v111, s[14:15]
	s_add_u32 s14, s14, 0x20000
	s_addc_u32 s15, s15, 0
	global_store_dword v106, v112, s[14:15]
	s_add_u32 s14, s14, 0x20000
	s_addc_u32 s15, s15, 0
	global_store_dword v106, v113, s[14:15]
	s_add_u32 s14, s14, 0x20000
	s_addc_u32 s15, s15, 0
	s_mov_b64 exec, s[18:19]
	global_load_dwordx4 v[176:179], v104, s[10:11] nt
	global_load_dwordx4 v[180:183], v104, s[10:11] offset:1024 nt
	global_load_dwordx4 v[184:187], v104, s[10:11] offset:2048 nt
	global_load_dwordx4 v[188:191], v104, s[10:11] offset:3072 nt
	s_add_u32 s10, s10, 0x800000
	s_addc_u32 s11, s11, 0
	global_load_dwordx4 v[192:195], v104, s[10:11] nt
	global_load_dwordx4 v[196:199], v104, s[10:11] offset:1024 nt
	global_load_dwordx4 v[200:203], v104, s[10:11] offset:2048 nt
	global_load_dwordx4 v[204:207], v104, s[10:11] offset:3072 nt
	s_add_u32 s10, s10, 0x800000
	s_addc_u32 s11, s11, 0
	global_load_dwordx4 v[208:211], v104, s[10:11] nt
	global_load_dwordx4 v[212:215], v104, s[10:11] offset:1024 nt
	global_load_dwordx4 v[216:219], v104, s[10:11] offset:2048 nt
	global_load_dwordx4 v[220:223], v104, s[10:11] offset:3072 nt
	s_add_u32 s10, s10, 0x800000
	s_addc_u32 s11, s11, 0
	global_load_dwordx4 v[224:227], v104, s[10:11] nt
	global_load_dwordx4 v[228:231], v104, s[10:11] offset:1024 nt
	global_load_dwordx4 v[232:235], v104, s[10:11] offset:2048 nt
	global_load_dwordx4 v[236:239], v104, s[10:11] offset:3072 nt
	s_add_u32 s10, s10, 0x800000
	s_addc_u32 s11, s11, 0
	s_waitcnt vmcnt(36)
; __device__ __forceinline__ unsigned pk2(float lo, float hi) { return f2bf(lo) | (f2bf(hi) << 16); }
; #define lane (hw_lane())
; __device__ __forceinline__ float wave_sum(float v) {
; #pragma unroll
;     for (int o = 1; o < 64; o <<= 1) v += __shfl_xor(v, o);
;     return v;
; __device__ __forceinline__ void prologue(const Args& a, LAS unsigned char* lds, int gw, int NGW, int lane, int wave) {
;     ...
;         for (int m = gw; m < M + MMEM; m += NGW) {
;             const bool is_mem = m >= M; const int row = is_mem ? m - M : m;
;             f32x4 v[4]; float s = 0.f;
; #pragma unroll
;             for (int j = 0; j < 4; ++j) v[j] = nv[j];
;             { const int mn = m + NGW; if (mn < M + MMEM) { const f32x4* xr = (const f32x4*)((mn >= M ? a.in[I_MEM] + (size_t)(mn - M) * D : a.in[I_X] + (size_t)mn * D)) + lane;
; #pragma unroll
;                 for (int j = 0; j < 4; ++j) nv[j] = __builtin_nontemporal_load(xr + 64 * j); } }
; #pragma unroll
;             for (int j = 0; j < 4; ++j) s += (v[j].x * v[j].x + v[j].y * v[j].y) + (v[j].z * v[j].z + v[j].w * v[j].w);
;             s = wave_sum(s);
;             float sc = 1.f;
;             if (is_mem) sc = __builtin_amdgcn_rsqf(s * (1.0f / D) + EPS);
;             else if (lane < 16) slots[(size_t)row * 16 + lane] = lane == 0 ? s : 0.f;
;             v2u* o8 = (v2u*)((is_mem ? MEMN : HB) + (size_t)row * D) + lane;
; #pragma unroll
;             for (int j = 0; j < 4; ++j) { v2u o; o.x = pk2(v[j].x * sc, v[j].y * sc); o.y = pk2(v[j].z * sc, v[j].w * sc); o8[64 * j] = o; }
	v_cvt_pk_bf16_f32 v16, v40, v41
	v_cvt_pk_bf16_f32 v17, v42, v43
	v_cvt_pk_bf16_f32 v18, v44, v45
	v_cvt_pk_bf16_f32 v19, v46, v47
	v_cvt_pk_bf16_f32 v20, v48, v49
	v_cvt_pk_bf16_f32 v21, v50, v51
	v_cvt_pk_bf16_f32 v22, v52, v53
	v_cvt_pk_bf16_f32 v23, v54, v55
	v_mul_f32_e32 v110, v40, v40
	v_fmac_f32_e32 v110, v41, v41
	v_fmac_f32_e32 v110, v42, v42
	v_fmac_f32_e32 v110, v43, v43
	v_fmac_f32_e32 v110, v44, v44
	v_fmac_f32_e32 v110, v45, v45
	v_fmac_f32_e32 v110, v46, v46
	v_fmac_f32_e32 v110, v47, v47
	v_fmac_f32_e32 v110, v48, v48
	v_fmac_f32_e32 v110, v49, v49
	v_fmac_f32_e32 v110, v50, v50
	v_fmac_f32_e32 v110, v51, v51
	v_fmac_f32_e32 v110, v52, v52
	v_fmac_f32_e32 v110, v53, v53
	v_fmac_f32_e32 v110, v54, v54
	v_fmac_f32_e32 v110, v55, v55
	global_store_dwordx2 v105, v[16:17], s[12:13]
	global_store_dwordx2 v105, v[18:19], s[12:13] offset:512
	global_store_dwordx2 v105, v[20:21], s[12:13] offset:1024
	global_store_dwordx2 v105, v[22:23], s[12:13] offset:1536
	s_add_u32 s12, s12, 0x400000
	s_addc_u32 s13, s13, 0
	v_cvt_pk_bf16_f32 v24, v56, v57
	v_cvt_pk_bf16_f32 v25, v58, v59
	v_cvt_pk_bf16_f32 v26, v60, v61
	v_cvt_pk_bf16_f32 v27, v62, v63
	v_cvt_pk_bf16_f32 v28, v64, v65
	v_cvt_pk_bf16_f32 v29, v66, v67
	v_cvt_pk_bf16_f32 v30, v68, v69
	v_cvt_pk_bf16_f32 v31, v70, v71
	v_mul_f32_e32 v111, v56, v56
	v_fmac_f32_e32 v111, v57, v57
	v_fmac_f32_e32 v111, v58, v58
	v_fmac_f32_e32 v111, v59, v59
	v_fmac_f32_e32 v111, v60, v60
	v_fmac_f32_e32 v111, v61, v61
	v_fmac_f32_e32 v111, v62, v62
	v_fmac_f32_e32 v111, v63, v63
	v_fmac_f32_e32 v111, v64, v64
	v_fmac_f32_e32 v111, v65, v65
	v_fmac_f32_e32 v111, v66, v66
	v_fmac_f32_e32 v111, v67, v67
	v_fmac_f32_e32 v111, v68, v68
	v_fmac_f32_e32 v111, v69, v69
	v_fmac_f32_e32 v111, v70, v70
	v_fmac_f32_e32 v111, v71, v71
	global_store_dwordx2 v105, v[24:25], s[12:13]
	global_store_dwordx2 v105, v[26:27], s[12:13] offset:512
	global_store_dwordx2 v105, v[28:29], s[12:13] offset:1024
	global_store_dwordx2 v105, v[30:31], s[12:13] offset:1536
	s_add_u32 s12, s12, 0x400000
	s_addc_u32 s13, s13, 0
	v_cvt_pk_bf16_f32 v16, v72, v73
	v_cvt_pk_bf16_f32 v17, v74, v75
	v_cvt_pk_bf16_f32 v18, v76, v77
	v_cvt_pk_bf16_f32 v19, v78, v79
	v_cvt_pk_bf16_f32 v20, v80, v81
	v_cvt_pk_bf16_f32 v21, v82, v83
	v_cvt_pk_bf16_f32 v22, v84, v85
	v_cvt_pk_bf16_f32 v23, v86, v87
	v_mul_f32_e32 v112, v72, v72
	v_fmac_f32_e32 v112, v73, v73
	v_fmac_f32_e32 v112, v74, v74
	v_fmac_f32_e32 v112, v75, v75
	v_fmac_f32_e32 v112, v76, v76
	v_fmac_f32_e32 v112, v77, v77
	v_fmac_f32_e32 v112, v78, v78
	v_fmac_f32_e32 v112, v79, v79
	v_fmac_f32_e32 v112, v80, v80
	v_fmac_f32_e32 v112, v81, v81
	v_fmac_f32_e32 v112, v82, v82
	v_fmac_f32_e32 v112, v83, v83
	v_fmac_f32_e32 v112, v84, v84
	v_fmac_f32_e32 v112, v85, v85
	v_fmac_f32_e32 v112, v86, v86
	v_fmac_f32_e32 v112, v87, v87
	global_store_dwordx2 v105, v[16:17], s[12:13]
	global_store_dwordx2 v105, v[18:19], s[12:13] offset:512
	global_store_dwordx2 v105, v[20:21], s[12:13] offset:1024
	global_store_dwordx2 v105, v[22:23], s[12:13] offset:1536
	s_add_u32 s12, s12, 0x400000
	s_addc_u32 s13, s13, 0
	v_cvt_pk_bf16_f32 v24, v88, v89
	v_cvt_pk_bf16_f32 v25, v90, v91
	v_cvt_pk_bf16_f32 v26, v92, v93
	v_cvt_pk_bf16_f32 v27, v94, v95
	v_cvt_pk_bf16_f32 v28, v96, v97
	v_cvt_pk_bf16_f32 v29, v98, v99
	v_cvt_pk_bf16_f32 v30, v100, v101
	v_cvt_pk_bf16_f32 v31, v102, v103
	v_mul_f32_e32 v113, v88, v88
	v_fmac_f32_e32 v113, v89, v89
	v_fmac_f32_e32 v113, v90, v90
	v_fmac_f32_e32 v113, v91, v91
	v_fmac_f32_e32 v113, v92, v92
	v_fmac_f32_e32 v113, v93, v93
	v_fmac_f32_e32 v113, v94, v94
	v_fmac_f32_e32 v113, v95, v95
	v_fmac_f32_e32 v113, v96, v96
	v_fmac_f32_e32 v113, v97, v97
	v_fmac_f32_e32 v113, v98, v98
	v_fmac_f32_e32 v113, v99, v99
	v_fmac_f32_e32 v113, v100, v100
	v_fmac_f32_e32 v113, v101, v101
	v_fmac_f32_e32 v113, v102, v102
	v_fmac_f32_e32 v113, v103, v103
	global_store_dwordx2 v105, v[24:25], s[12:13]
	global_store_dwordx2 v105, v[26:27], s[12:13] offset:512
	global_store_dwordx2 v105, v[28:29], s[12:13] offset:1024
	global_store_dwordx2 v105, v[30:31], s[12:13] offset:1536
	s_add_u32 s12, s12, 0x400000
	s_addc_u32 s13, s13, 0
	v_add_f32_dpp v114, v110, v110 row_ror:8 row_mask:0xf bank_mask:0xf
	v_add_f32_dpp v115, v111, v111 row_ror:8 row_mask:0xf bank_mask:0xf
	v_add_f32_dpp v116, v112, v112 row_ror:8 row_mask:0xf bank_mask:0xf
	v_add_f32_dpp v117, v113, v113 row_ror:8 row_mask:0xf bank_mask:0xf
	v_add_f32_dpp v110, v114, v114 row_ror:4 row_mask:0xf bank_mask:0xf
	v_add_f32_dpp v111, v115, v115 row_ror:4 row_mask:0xf bank_mask:0xf
	v_add_f32_dpp v112, v116, v116 row_ror:4 row_mask:0xf bank_mask:0xf
	v_add_f32_dpp v113, v117, v117 row_ror:4 row_mask:0xf bank_mask:0xf
	v_add_f32_dpp v114, v110, v110 row_ror:2 row_mask:0xf bank_mask:0xf
	v_add_f32_dpp v115, v111, v111 row_ror:2 row_mask:0xf bank_mask:0xf
	v_add_f32_dpp v116, v112, v112 row_ror:2 row_mask:0xf bank_mask:0xf
	v_add_f32_dpp v117, v113, v113 row_ror:2 row_mask:0xf bank_mask:0xf
	v_add_f32_dpp v110, v114, v114 row_ror:1 row_mask:0xf bank_mask:0xf
	v_add_f32_dpp v111, v115, v115 row_ror:1 row_mask:0xf bank_mask:0xf
	v_add_f32_dpp v112, v116, v116 row_ror:1 row_mask:0xf bank_mask:0xf
	v_add_f32_dpp v113, v117, v117 row_ror:1 row_mask:0xf bank_mask:0xf
	ds_bpermute_b32 v114, v107, v110
	ds_bpermute_b32 v115, v107, v111
	ds_bpermute_b32 v116, v107, v112
	ds_bpermute_b32 v117, v107, v113
	s_waitcnt lgkmcnt(0)
	v_add_f32_e32 v110, v110, v114
	v_add_f32_e32 v111, v111, v115
	v_add_f32_e32 v112, v112, v116
	v_add_f32_e32 v113, v113, v117
	ds_bpermute_b32 v114, v108, v110
	ds_bpermute_b32 v115, v108, v111
	ds_bpermute_b32 v116, v108, v112
	ds_bpermute_b32 v117, v108, v113
	s_waitcnt lgkmcnt(0)
; __device__ __forceinline__ unsigned pk2(float lo, float hi) { return f2bf(lo) | (f2bf(hi) << 16); }
; #define lane (hw_lane())
; __device__ __forceinline__ float wave_sum(float v) {
; #pragma unroll
;     for (int o = 1; o < 64; o <<= 1) v += __shfl_xor(v, o);
;     return v;
; __device__ __forceinline__ void prologue(const Args& a, LAS unsigned char* lds, int gw, int NGW, int lane, int wave) {
;     ...
;         for (int m = gw; m < M + MMEM; m += NGW) {
;             const bool is_mem = m >= M; const int row = is_mem ? m - M : m;
;             f32x4 v[4]; float s = 0.f;
; #pragma unroll
;             for (int j = 0; j < 4; ++j) v[j] = nv[j];
;             { const int mn = m + NGW; if (mn < M + MMEM) { const f32x4* xr = (const f32x4*)((mn >= M ? a.in[I_MEM] + (size_t)(mn - M) * D : a.in[I_X] + (size_t)mn * D)) + lane;
; #pragma unroll
;                 for (int j = 0; j < 4; ++j) nv[j] = __builtin_nontemporal_load(xr + 64 * j); } }
; #pragma unroll
;             for (int j = 0; j < 4; ++j) s += (v[j].x * v[j].x + v[j].y * v[j].y) + (v[j].z * v[j].z + v[j].w * v[j].w);
;             s = wave_sum(s);
;             float sc = 1.f;
;             if (is_mem) sc = __builtin_amdgcn_rsqf(s * (1.0f / D) + EPS);
;             else if (lane < 16) slots[(size_t)row * 16 + lane] = lane == 0 ? s : 0.f;
;             v2u* o8 = (v2u*)((is_mem ? MEMN : HB) + (size_t)row * D) + lane;
; #pragma unroll
;             for (int j = 0; j < 4; ++j) { v2u o; o.x = pk2(v[j].x * sc, v[j].y * sc); o.y = pk2(v[j].z * sc, v[j].w * sc); o8[64 * j] = o; }
	v_add_f32_e32 v110, v110, v114
	v_add_f32_e32 v111, v111, v115
	v_add_f32_e32 v112, v112, v116
	v_add_f32_e32 v113, v113, v117
	v_cndmask_b32_e64 v110, v109, v110, s[16:17]
	v_cndmask_b32_e64 v111, v109, v111, s[16:17]
	v_cndmask_b32_e64 v112, v109, v112, s[16:17]
	v_cndmask_b32_e64 v113, v109, v113, s[16:17]
	s_and_saveexec_b64 s[18:19], s[4:5]
	global_store_dword v106, v110, s[14:15]
	s_add_u32 s14, s14, 0x20000
	s_addc_u32 s15, s15, 0
	global_store_dword v106, v111, s[14:15]
	s_add_u32 s14, s14, 0x20000
	s_addc_u32 s15, s15, 0
	global_store_dword v106, v112, s[14:15]
	s_add_u32 s14, s14, 0x20000
	s_addc_u32 s15, s15, 0
	global_store_dword v106, v113, s[14:15]
	s_add_u32 s14, s14, 0x20000
	s_addc_u32 s15, s15, 0
	s_mov_b64 exec, s[18:19]
	global_load_dwordx4 v[40:43], v104, s[10:11] nt
	global_load_dwordx4 v[44:47], v104, s[10:11] offset:1024 nt
	global_load_dwordx4 v[48:51], v104, s[10:11] offset:2048 nt
	global_load_dwordx4 v[52:55], v104, s[10:11] offset:3072 nt
	s_add_u32 s10, s10, 0x800000
	s_addc_u32 s11, s11, 0
	global_load_dwordx4 v[56:59], v104, s[10:11] nt
	global_load_dwordx4 v[60:63], v104, s[10:11] offset:1024 nt
	global_load_dwordx4 v[64:67], v104, s[10:11] offset:2048 nt
	global_load_dwordx4 v[68:71], v104, s[10:11] offset:3072 nt
	s_add_u32 s10, s10, 0x800000
	s_addc_u32 s11, s11, 0
	global_load_dwordx4 v[72:75], v104, s[10:11] nt
	global_load_dwordx4 v[76:79], v104, s[10:11] offset:1024 nt
	global_load_dwordx4 v[80:83], v104, s[10:11] offset:2048 nt
	global_load_dwordx4 v[84:87], v104, s[10:11] offset:3072 nt
	s_add_u32 s10, s10, 0x800000
	s_addc_u32 s11, s11, 0
	global_load_dwordx4 v[88:91], v104, s[10:11] nt
	global_load_dwordx4 v[92:95], v104, s[10:11] offset:1024 nt
	global_load_dwordx4 v[96:99], v104, s[10:11] offset:2048 nt
	global_load_dwordx4 v[100:103], v104, s[10:11] offset:3072 nt
	s_add_u32 s10, s10, 0x800000
	s_addc_u32 s11, s11, 0
	s_waitcnt vmcnt(36)
	v_cvt_pk_bf16_f32 v16, v176, v177
	v_cvt_pk_bf16_f32 v17, v178, v179
	v_cvt_pk_bf16_f32 v18, v180, v181
	v_cvt_pk_bf16_f32 v19, v182, v183
	v_cvt_pk_bf16_f32 v20, v184, v185
	v_cvt_pk_bf16_f32 v21, v186, v187
	v_cvt_pk_bf16_f32 v22, v188, v189
	v_cvt_pk_bf16_f32 v23, v190, v191
	v_mul_f32_e32 v110, v176, v176
	v_fmac_f32_e32 v110, v177, v177
	v_fmac_f32_e32 v110, v178, v178
	v_fmac_f32_e32 v110, v179, v179
	v_fmac_f32_e32 v110, v180, v180
	v_fmac_f32_e32 v110, v181, v181
	v_fmac_f32_e32 v110, v182, v182
	v_fmac_f32_e32 v110, v183, v183
	v_fmac_f32_e32 v110, v184, v184
	v_fmac_f32_e32 v110, v185, v185
	v_fmac_f32_e32 v110, v186, v186
	v_fmac_f32_e32 v110, v187, v187
	v_fmac_f32_e32 v110, v188, v188
	v_fmac_f32_e32 v110, v189, v189
	v_fmac_f32_e32 v110, v190, v190
	v_fmac_f32_e32 v110, v191, v191
	global_store_dwordx2 v105, v[16:17], s[12:13]
	global_store_dwordx2 v105, v[18:19], s[12:13] offset:512
	global_store_dwordx2 v105, v[20:21], s[12:13] offset:1024
	global_store_dwordx2 v105, v[22:23], s[12:13] offset:1536
	s_add_u32 s12, s12, 0x400000
	s_addc_u32 s13, s13, 0
	v_cvt_pk_bf16_f32 v24, v192, v193
	v_cvt_pk_bf16_f32 v25, v194, v195
	v_cvt_pk_bf16_f32 v26, v196, v197
	v_cvt_pk_bf16_f32 v27, v198, v199
	v_cvt_pk_bf16_f32 v28, v200, v201
	v_cvt_pk_bf16_f32 v29, v202, v203
	v_cvt_pk_bf16_f32 v30, v204, v205
	v_cvt_pk_bf16_f32 v31, v206, v207
	v_mul_f32_e32 v111, v192, v192
	v_fmac_f32_e32 v111, v193, v193
	v_fmac_f32_e32 v111, v194, v194
	v_fmac_f32_e32 v111, v195, v195
	v_fmac_f32_e32 v111, v196, v196
	v_fmac_f32_e32 v111, v197, v197
	v_fmac_f32_e32 v111, v198, v198
	v_fmac_f32_e32 v111, v199, v199
	v_fmac_f32_e32 v111, v200, v200
	v_fmac_f32_e32 v111, v201, v201
	v_fmac_f32_e32 v111, v202, v202
	v_fmac_f32_e32 v111, v203, v203
	v_fmac_f32_e32 v111, v204, v204
	v_fmac_f32_e32 v111, v205, v205
	v_fmac_f32_e32 v111, v206, v206
	v_fmac_f32_e32 v111, v207, v207
	global_store_dwordx2 v105, v[24:25], s[12:13]
	global_store_dwordx2 v105, v[26:27], s[12:13] offset:512
	global_store_dwordx2 v105, v[28:29], s[12:13] offset:1024
	global_store_dwordx2 v105, v[30:31], s[12:13] offset:1536
	s_add_u32 s12, s12, 0x400000
	s_addc_u32 s13, s13, 0
	v_cvt_pk_bf16_f32 v16, v208, v209
	v_cvt_pk_bf16_f32 v17, v210, v211
	v_cvt_pk_bf16_f32 v18, v212, v213
	v_cvt_pk_bf16_f32 v19, v214, v215
	v_cvt_pk_bf16_f32 v20, v216, v217
	v_cvt_pk_bf16_f32 v21, v218, v219
	v_cvt_pk_bf16_f32 v22, v220, v221
	v_cvt_pk_bf16_f32 v23, v222, v223
	v_mul_f32_e32 v112, v208, v208
	v_fmac_f32_e32 v112, v209, v209
	v_fmac_f32_e32 v112, v210, v210
	v_fmac_f32_e32 v112, v211, v211
	v_fmac_f32_e32 v112, v212, v212
	v_fmac_f32_e32 v112, v213, v213
	v_fmac_f32_e32 v112, v214, v214
	v_fmac_f32_e32 v112, v215, v215
	v_fmac_f32_e32 v112, v216, v216
	v_fmac_f32_e32 v112, v217, v217
	v_fmac_f32_e32 v112, v218, v218
	v_fmac_f32_e32 v112, v219, v219
	v_fmac_f32_e32 v112, v220, v220
	v_fmac_f32_e32 v112, v221, v221
	v_fmac_f32_e32 v112, v222, v222
	v_fmac_f32_e32 v112, v223, v223
	global_store_dwordx2 v105, v[16:17], s[12:13]
	global_store_dwordx2 v105, v[18:19], s[12:13] offset:512
	global_store_dwordx2 v105, v[20:21], s[12:13] offset:1024
	global_store_dwordx2 v105, v[22:23], s[12:13] offset:1536
	s_add_u32 s12, s12, 0x400000
	s_addc_u32 s13, s13, 0
	v_cvt_pk_bf16_f32 v24, v224, v225
	v_cvt_pk_bf16_f32 v25, v226, v227
	v_cvt_pk_bf16_f32 v26, v228, v229
	v_cvt_pk_bf16_f32 v27, v230, v231
	v_cvt_pk_bf16_f32 v28, v232, v233
	v_cvt_pk_bf16_f32 v29, v234, v235
	v_cvt_pk_bf16_f32 v30, v236, v237
	v_cvt_pk_bf16_f32 v31, v238, v239
	v_mul_f32_e32 v113, v224, v224
	v_fmac_f32_e32 v113, v225, v225
	v_fmac_f32_e32 v113, v226, v226
	v_fmac_f32_e32 v113, v227, v227
	v_fmac_f32_e32 v113, v228, v228
	v_fmac_f32_e32 v113, v229, v229
; __device__ __forceinline__ unsigned pk2(float lo, float hi) { return f2bf(lo) | (f2bf(hi) << 16); }
; #define lane (hw_lane())
; __device__ __forceinline__ float wave_sum(float v) {
; #pragma unroll
;     for (int o = 1; o < 64; o <<= 1) v += __shfl_xor(v, o);
;     return v;
; __device__ __forceinline__ void prologue(const Args& a, LAS unsigned char* lds, int gw, int NGW, int lane, int wave) {
;     ...
;         for (int m = gw; m < M + MMEM; m += NGW) {
;             const bool is_mem = m >= M; const int row = is_mem ? m - M : m;
;             f32x4 v[4]; float s = 0.f;
; #pragma unroll
;             for (int j = 0; j < 4; ++j) v[j] = nv[j];
;             { const int mn = m + NGW; if (mn < M + MMEM) { const f32x4* xr = (const f32x4*)((mn >= M ? a.in[I_MEM] + (size_t)(mn - M) * D : a.in[I_X] + (size_t)mn * D)) + lane;
; #pragma unroll
;                 for (int j = 0; j < 4; ++j) nv[j] = __builtin_nontemporal_load(xr + 64 * j); } }
; #pragma unroll
;             for (int j = 0; j < 4; ++j) s += (v[j].x * v[j].x + v[j].y * v[j].y) + (v[j].z * v[j].z + v[j].w * v[j].w);
;             s = wave_sum(s);
;             float sc = 1.f;
;             if (is_mem) sc = __builtin_amdgcn_rsqf(s * (1.0f / D) + EPS);
;             else if (lane < 16) slots[(size_t)row * 16 + lane] = lane == 0 ? s : 0.f;
;             v2u* o8 = (v2u*)((is_mem ? MEMN : HB) + (size_t)row * D) + lane;
; #pragma unroll
;             for (int j = 0; j < 4; ++j) { v2u o; o.x = pk2(v[j].x * sc, v[j].y * sc); o.y = pk2(v[j].z * sc, v[j].w * sc); o8[64 * j] = o; }
	v_fmac_f32_e32 v113, v230, v230
	v_fmac_f32_e32 v113, v231, v231
	v_fmac_f32_e32 v113, v232, v232
	v_fmac_f32_e32 v113, v233, v233
	v_fmac_f32_e32 v113, v234, v234
	v_fmac_f32_e32 v113, v235, v235
	v_fmac_f32_e32 v113, v236, v236
	v_fmac_f32_e32 v113, v237, v237
	v_fmac_f32_e32 v113, v238, v238
	v_fmac_f32_e32 v113, v239, v239
	global_store_dwordx2 v105, v[24:25], s[12:13]
	global_store_dwordx2 v105, v[26:27], s[12:13] offset:512
	global_store_dwordx2 v105, v[28:29], s[12:13] offset:1024
	global_store_dwordx2 v105, v[30:31], s[12:13] offset:1536
	s_add_u32 s12, s12, 0x400000
	s_addc_u32 s13, s13, 0
	v_add_f32_dpp v114, v110, v110 row_ror:8 row_mask:0xf bank_mask:0xf
	v_add_f32_dpp v115, v111, v111 row_ror:8 row_mask:0xf bank_mask:0xf
	v_add_f32_dpp v116, v112, v112 row_ror:8 row_mask:0xf bank_mask:0xf
	v_add_f32_dpp v117, v113, v113 row_ror:8 row_mask:0xf bank_mask:0xf
	v_add_f32_dpp v110, v114, v114 row_ror:4 row_mask:0xf bank_mask:0xf
	v_add_f32_dpp v111, v115, v115 row_ror:4 row_mask:0xf bank_mask:0xf
	v_add_f32_dpp v112, v116, v116 row_ror:4 row_mask:0xf bank_mask:0xf
	v_add_f32_dpp v113, v117, v117 row_ror:4 row_mask:0xf bank_mask:0xf
	v_add_f32_dpp v114, v110, v110 row_ror:2 row_mask:0xf bank_mask:0xf
	v_add_f32_dpp v115, v111, v111 row_ror:2 row_mask:0xf bank_mask:0xf
	v_add_f32_dpp v116, v112, v112 row_ror:2 row_mask:0xf bank_mask:0xf
	v_add_f32_dpp v117, v113, v113 row_ror:2 row_mask:0xf bank_mask:0xf
	v_add_f32_dpp v110, v114, v114 row_ror:1 row_mask:0xf bank_mask:0xf
	v_add_f32_dpp v111, v115, v115 row_ror:1 row_mask:0xf bank_mask:0xf
	v_add_f32_dpp v112, v116, v116 row_ror:1 row_mask:0xf bank_mask:0xf
	v_add_f32_dpp v113, v117, v117 row_ror:1 row_mask:0xf bank_mask:0xf
	ds_bpermute_b32 v114, v107, v110
	ds_bpermute_b32 v115, v107, v111
	ds_bpermute_b32 v116, v107, v112
	ds_bpermute_b32 v117, v107, v113
	s_waitcnt lgkmcnt(0)
	v_add_f32_e32 v110, v110, v114
	v_add_f32_e32 v111, v111, v115
	v_add_f32_e32 v112, v112, v116
	v_add_f32_e32 v113, v113, v117
	ds_bpermute_b32 v114, v108, v110
	ds_bpermute_b32 v115, v108, v111
	ds_bpermute_b32 v116, v108, v112
	ds_bpermute_b32 v117, v108, v113
	s_waitcnt lgkmcnt(0)
	v_add_f32_e32 v110, v110, v114
	v_add_f32_e32 v111, v111, v115
	v_add_f32_e32 v112, v112, v116
	v_add_f32_e32 v113, v113, v117
	v_cndmask_b32_e64 v110, v109, v110, s[16:17]
	v_cndmask_b32_e64 v111, v109, v111, s[16:17]
	v_cndmask_b32_e64 v112, v109, v112, s[16:17]
	v_cndmask_b32_e64 v113, v109, v113, s[16:17]
	s_and_saveexec_b64 s[18:19], s[4:5]
	global_store_dword v106, v110, s[14:15]
	s_add_u32 s14, s14, 0x20000
	s_addc_u32 s15, s15, 0
	global_store_dword v106, v111, s[14:15]
	s_add_u32 s14, s14, 0x20000
	s_addc_u32 s15, s15, 0
	global_store_dword v106, v112, s[14:15]
	s_add_u32 s14, s14, 0x20000
	s_addc_u32 s15, s15, 0
	global_store_dword v106, v113, s[14:15]
	s_add_u32 s14, s14, 0x20000
	s_addc_u32 s15, s15, 0
	s_mov_b64 exec, s[18:19]
	global_load_dwordx4 v[176:179], v104, s[10:11] nt
	global_load_dwordx4 v[180:183], v104, s[10:11] offset:1024 nt
	global_load_dwordx4 v[184:187], v104, s[10:11] offset:2048 nt
	global_load_dwordx4 v[188:191], v104, s[10:11] offset:3072 nt
	s_add_u32 s10, s10, 0x800000
	s_addc_u32 s11, s11, 0
	global_load_dwordx4 v[192:195], v104, s[10:11] nt
	global_load_dwordx4 v[196:199], v104, s[10:11] offset:1024 nt
	global_load_dwordx4 v[200:203], v104, s[10:11] offset:2048 nt
	global_load_dwordx4 v[204:207], v104, s[10:11] offset:3072 nt
	s_add_u32 s10, s10, 0x800000
	s_addc_u32 s11, s11, 0
	global_load_dwordx4 v[208:211], v104, s[10:11] nt
	global_load_dwordx4 v[212:215], v104, s[10:11] offset:1024 nt
	global_load_dwordx4 v[216:219], v104, s[10:11] offset:2048 nt
	global_load_dwordx4 v[220:223], v104, s[10:11] offset:3072 nt
	s_add_u32 s10, s10, 0x800000
	s_addc_u32 s11, s11, 0
	global_load_dwordx4 v[224:227], v104, s[10:11] nt
	global_load_dwordx4 v[228:231], v104, s[10:11] offset:1024 nt
	global_load_dwordx4 v[232:235], v104, s[10:11] offset:2048 nt
	global_load_dwordx4 v[236:239], v104, s[10:11] offset:3072 nt
	s_add_u32 s10, s10, 0x800000
	s_addc_u32 s11, s11, 0
	s_waitcnt vmcnt(36)
	v_cvt_pk_bf16_f32 v16, v40, v41
	v_cvt_pk_bf16_f32 v17, v42, v43
	v_cvt_pk_bf16_f32 v18, v44, v45
	v_cvt_pk_bf16_f32 v19, v46, v47
	v_cvt_pk_bf16_f32 v20, v48, v49
	v_cvt_pk_bf16_f32 v21, v50, v51
	v_cvt_pk_bf16_f32 v22, v52, v53
	v_cvt_pk_bf16_f32 v23, v54, v55
	v_mul_f32_e32 v110, v40, v40
	v_fmac_f32_e32 v110, v41, v41
	v_fmac_f32_e32 v110, v42, v42
	v_fmac_f32_e32 v110, v43, v43
	v_fmac_f32_e32 v110, v44, v44
	v_fmac_f32_e32 v110, v45, v45
	v_fmac_f32_e32 v110, v46, v46
	v_fmac_f32_e32 v110, v47, v47
	v_fmac_f32_e32 v110, v48, v48
	v_fmac_f32_e32 v110, v49, v49
	v_fmac_f32_e32 v110, v50, v50
	v_fmac_f32_e32 v110, v51, v51
	v_fmac_f32_e32 v110, v52, v52
	v_fmac_f32_e32 v110, v53, v53
	v_fmac_f32_e32 v110, v54, v54
	v_fmac_f32_e32 v110, v55, v55
	global_store_dwordx2 v105, v[16:17], s[12:13]
	global_store_dwordx2 v105, v[18:19], s[12:13] offset:512
	global_store_dwordx2 v105, v[20:21], s[12:13] offset:1024
	global_store_dwordx2 v105, v[22:23], s[12:13] offset:1536
	s_add_u32 s12, s12, 0x400000
	s_addc_u32 s13, s13, 0
	v_cvt_pk_bf16_f32 v24, v56, v57
	v_cvt_pk_bf16_f32 v25, v58, v59
	v_cvt_pk_bf16_f32 v26, v60, v61
	v_cvt_pk_bf16_f32 v27, v62, v63
	v_cvt_pk_bf16_f32 v28, v64, v65
	v_cvt_pk_bf16_f32 v29, v66, v67
	v_cvt_pk_bf16_f32 v30, v68, v69
	v_cvt_pk_bf16_f32 v31, v70, v71
	v_mul_f32_e32 v111, v56, v56
	v_fmac_f32_e32 v111, v57, v57
	v_fmac_f32_e32 v111, v58, v58
	v_fmac_f32_e32 v111, v59, v59
	v_fmac_f32_e32 v111, v60, v60
	v_fmac_f32_e32 v111, v61, v61
	v_fmac_f32_e32 v111, v62, v62
	v_fmac_f32_e32 v111, v63, v63
; __device__ __forceinline__ unsigned pk2(float lo, float hi) { return f2bf(lo) | (f2bf(hi) << 16); }
; #define lane (hw_lane())
; __device__ __forceinline__ float wave_sum(float v) {
; #pragma unroll
;     for (int o = 1; o < 64; o <<= 1) v += __shfl_xor(v, o);
;     return v;
; __device__ __forceinline__ void prologue(const Args& a, LAS unsigned char* lds, int gw, int NGW, int lane, int wave) {
;     ...
;         for (int m = gw; m < M + MMEM; m += NGW) {
;             const bool is_mem = m >= M; const int row = is_mem ? m - M : m;
;             f32x4 v[4]; float s = 0.f;
; #pragma unroll
;             for (int j = 0; j < 4; ++j) v[j] = nv[j];
;             { const int mn = m + NGW; if (mn < M + MMEM) { const f32x4* xr = (const f32x4*)((mn >= M ? a.in[I_MEM] + (size_t)(mn - M) * D : a.in[I_X] + (size_t)mn * D)) + lane;
; #pragma unroll
;                 for (int j = 0; j < 4; ++j) nv[j] = __builtin_nontemporal_load(xr + 64 * j); } }
; #pragma unroll
;             for (int j = 0; j < 4; ++j) s += (v[j].x * v[j].x + v[j].y * v[j].y) + (v[j].z * v[j].z + v[j].w * v[j].w);
;             s = wave_sum(s);
;             float sc = 1.f;
;             if (is_mem) sc = __builtin_amdgcn_rsqf(s * (1.0f / D) + EPS);
;             else if (lane < 16) slots[(size_t)row * 16 + lane] = lane == 0 ? s : 0.f;
;             v2u* o8 = (v2u*)((is_mem ? MEMN : HB) + (size_t)row * D) + lane;
; #pragma unroll
;             for (int j = 0; j < 4; ++j) { v2u o; o.x = pk2(v[j].x * sc, v[j].y * sc); o.y = pk2(v[j].z * sc, v[j].w * sc); o8[64 * j] = o; }
	v_fmac_f32_e32 v111, v64, v64
	v_fmac_f32_e32 v111, v65, v65
	v_fmac_f32_e32 v111, v66, v66
	v_fmac_f32_e32 v111, v67, v67
	v_fmac_f32_e32 v111, v68, v68
	v_fmac_f32_e32 v111, v69, v69
	v_fmac_f32_e32 v111, v70, v70
	v_fmac_f32_e32 v111, v71, v71
	global_store_dwordx2 v105, v[24:25], s[12:13]
	global_store_dwordx2 v105, v[26:27], s[12:13] offset:512
	global_store_dwordx2 v105, v[28:29], s[12:13] offset:1024
	global_store_dwordx2 v105, v[30:31], s[12:13] offset:1536
	s_add_u32 s12, s12, 0x400000
	s_addc_u32 s13, s13, 0
	v_cvt_pk_bf16_f32 v16, v72, v73
	v_cvt_pk_bf16_f32 v17, v74, v75
	v_cvt_pk_bf16_f32 v18, v76, v77
	v_cvt_pk_bf16_f32 v19, v78, v79
	v_cvt_pk_bf16_f32 v20, v80, v81
	v_cvt_pk_bf16_f32 v21, v82, v83
	v_cvt_pk_bf16_f32 v22, v84, v85
	v_cvt_pk_bf16_f32 v23, v86, v87
	v_mul_f32_e32 v112, v72, v72
	v_fmac_f32_e32 v112, v73, v73
	v_fmac_f32_e32 v112, v74, v74
	v_fmac_f32_e32 v112, v75, v75
	v_fmac_f32_e32 v112, v76, v76
	v_fmac_f32_e32 v112, v77, v77
	v_fmac_f32_e32 v112, v78, v78
	v_fmac_f32_e32 v112, v79, v79
	v_fmac_f32_e32 v112, v80, v80
	v_fmac_f32_e32 v112, v81, v81
	v_fmac_f32_e32 v112, v82, v82
	v_fmac_f32_e32 v112, v83, v83
	v_fmac_f32_e32 v112, v84, v84
	v_fmac_f32_e32 v112, v85, v85
	v_fmac_f32_e32 v112, v86, v86
	v_fmac_f32_e32 v112, v87, v87
	global_store_dwordx2 v105, v[16:17], s[12:13]
	global_store_dwordx2 v105, v[18:19], s[12:13] offset:512
	global_store_dwordx2 v105, v[20:21], s[12:13] offset:1024
	global_store_dwordx2 v105, v[22:23], s[12:13] offset:1536
	s_add_u32 s12, s12, 0x400000
	s_addc_u32 s13, s13, 0
	v_cvt_pk_bf16_f32 v24, v88, v89
	v_cvt_pk_bf16_f32 v25, v90, v91
	v_cvt_pk_bf16_f32 v26, v92, v93
	v_cvt_pk_bf16_f32 v27, v94, v95
	v_cvt_pk_bf16_f32 v28, v96, v97
	v_cvt_pk_bf16_f32 v29, v98, v99
	v_cvt_pk_bf16_f32 v30, v100, v101
	v_cvt_pk_bf16_f32 v31, v102, v103
	v_mul_f32_e32 v113, v88, v88
	v_fmac_f32_e32 v113, v89, v89
	v_fmac_f32_e32 v113, v90, v90
	v_fmac_f32_e32 v113, v91, v91
	v_fmac_f32_e32 v113, v92, v92
	v_fmac_f32_e32 v113, v93, v93
	v_fmac_f32_e32 v113, v94, v94
	v_fmac_f32_e32 v113, v95, v95
	v_fmac_f32_e32 v113, v96, v96
	v_fmac_f32_e32 v113, v97, v97
	v_fmac_f32_e32 v113, v98, v98
	v_fmac_f32_e32 v113, v99, v99
	v_fmac_f32_e32 v113, v100, v100
	v_fmac_f32_e32 v113, v101, v101
	v_fmac_f32_e32 v113, v102, v102
	v_fmac_f32_e32 v113, v103, v103
	global_store_dwordx2 v105, v[24:25], s[12:13]
	global_store_dwordx2 v105, v[26:27], s[12:13] offset:512
	global_store_dwordx2 v105, v[28:29], s[12:13] offset:1024
	global_store_dwordx2 v105, v[30:31], s[12:13] offset:1536
	s_add_u32 s12, s12, 0x400000
	s_addc_u32 s13, s13, 0
	v_add_f32_dpp v114, v110, v110 row_ror:8 row_mask:0xf bank_mask:0xf
	v_add_f32_dpp v115, v111, v111 row_ror:8 row_mask:0xf bank_mask:0xf
	v_add_f32_dpp v116, v112, v112 row_ror:8 row_mask:0xf bank_mask:0xf
	v_add_f32_dpp v117, v113, v113 row_ror:8 row_mask:0xf bank_mask:0xf
	v_add_f32_dpp v110, v114, v114 row_ror:4 row_mask:0xf bank_mask:0xf
	v_add_f32_dpp v111, v115, v115 row_ror:4 row_mask:0xf bank_mask:0xf
	v_add_f32_dpp v112, v116, v116 row_ror:4 row_mask:0xf bank_mask:0xf
	v_add_f32_dpp v113, v117, v117 row_ror:4 row_mask:0xf bank_mask:0xf
	v_add_f32_dpp v114, v110, v110 row_ror:2 row_mask:0xf bank_mask:0xf
	v_add_f32_dpp v115, v111, v111 row_ror:2 row_mask:0xf bank_mask:0xf
	v_add_f32_dpp v116, v112, v112 row_ror:2 row_mask:0xf bank_mask:0xf
	v_add_f32_dpp v117, v113, v113 row_ror:2 row_mask:0xf bank_mask:0xf
	v_add_f32_dpp v110, v114, v114 row_ror:1 row_mask:0xf bank_mask:0xf
	v_add_f32_dpp v111, v115, v115 row_ror:1 row_mask:0xf bank_mask:0xf
	v_add_f32_dpp v112, v116, v116 row_ror:1 row_mask:0xf bank_mask:0xf
	v_add_f32_dpp v113, v117, v117 row_ror:1 row_mask:0xf bank_mask:0xf
	ds_bpermute_b32 v114, v107, v110
	ds_bpermute_b32 v115, v107, v111
	ds_bpermute_b32 v116, v107, v112
	ds_bpermute_b32 v117, v107, v113
	s_waitcnt lgkmcnt(0)
	v_add_f32_e32 v110, v110, v114
	v_add_f32_e32 v111, v111, v115
	v_add_f32_e32 v112, v112, v116
	v_add_f32_e32 v113, v113, v117
	ds_bpermute_b32 v114, v108, v110
	ds_bpermute_b32 v115, v108, v111
	ds_bpermute_b32 v116, v108, v112
	ds_bpermute_b32 v117, v108, v113
	s_waitcnt lgkmcnt(0)
	v_add_f32_e32 v110, v110, v114
	v_add_f32_e32 v111, v111, v115
	v_add_f32_e32 v112, v112, v116
	v_add_f32_e32 v113, v113, v117
	v_cndmask_b32_e64 v110, v109, v110, s[16:17]
	v_cndmask_b32_e64 v111, v109, v111, s[16:17]
	v_cndmask_b32_e64 v112, v109, v112, s[16:17]
	v_cndmask_b32_e64 v113, v109, v113, s[16:17]
	s_and_saveexec_b64 s[18:19], s[4:5]
	global_store_dword v106, v110, s[14:15]
	s_add_u32 s14, s14, 0x20000
	s_addc_u32 s15, s15, 0
	global_store_dword v106, v111, s[14:15]
	s_add_u32 s14, s14, 0x20000
	s_addc_u32 s15, s15, 0
	global_store_dword v106, v112, s[14:15]
	s_add_u32 s14, s14, 0x20000
	s_addc_u32 s15, s15, 0
	global_store_dword v106, v113, s[14:15]
	s_add_u32 s14, s14, 0x20000
	s_addc_u32 s15, s15, 0
	s_mov_b64 exec, s[18:19]
	s_waitcnt vmcnt(20)
; __device__ __forceinline__ unsigned pk2(float lo, float hi) { return f2bf(lo) | (f2bf(hi) << 16); }
; #define lane (hw_lane())
; __device__ __forceinline__ float wave_sum(float v) {
; #pragma unroll
;     for (int o = 1; o < 64; o <<= 1) v += __shfl_xor(v, o);
;     return v;
; __device__ __forceinline__ void prologue(const Args& a, LAS unsigned char* lds, int gw, int NGW, int lane, int wave) {
;     ...
;         for (int m = gw; m < M + MMEM; m += NGW) {
;             const bool is_mem = m >= M; const int row = is_mem ? m - M : m;
;             f32x4 v[4]; float s = 0.f;
; #pragma unroll
;             for (int j = 0; j < 4; ++j) v[j] = nv[j];
;             { const int mn = m + NGW; if (mn < M + MMEM) { const f32x4* xr = (const f32x4*)((mn >= M ? a.in[I_MEM] + (size_t)(mn - M) * D : a.in[I_X] + (size_t)mn * D)) + lane;
; #pragma unroll
;                 for (int j = 0; j < 4; ++j) nv[j] = __builtin_nontemporal_load(xr + 64 * j); } }
; #pragma unroll
;             for (int j = 0; j < 4; ++j) s += (v[j].x * v[j].x + v[j].y * v[j].y) + (v[j].z * v[j].z + v[j].w * v[j].w);
;             s = wave_sum(s);
;             float sc = 1.f;
;             if (is_mem) sc = __builtin_amdgcn_rsqf(s * (1.0f / D) + EPS);
;             else if (lane < 16) slots[(size_t)row * 16 + lane] = lane == 0 ? s : 0.f;
;             v2u* o8 = (v2u*)((is_mem ? MEMN : HB) + (size_t)row * D) + lane;
; #pragma unroll
;             for (int j = 0; j < 4; ++j) { v2u o; o.x = pk2(v[j].x * sc, v[j].y * sc); o.y = pk2(v[j].z * sc, v[j].w * sc); o8[64 * j] = o; }
	v_cvt_pk_bf16_f32 v16, v176, v177
	v_cvt_pk_bf16_f32 v17, v178, v179
	v_cvt_pk_bf16_f32 v18, v180, v181
	v_cvt_pk_bf16_f32 v19, v182, v183
	v_cvt_pk_bf16_f32 v20, v184, v185
	v_cvt_pk_bf16_f32 v21, v186, v187
	v_cvt_pk_bf16_f32 v22, v188, v189
	v_cvt_pk_bf16_f32 v23, v190, v191
	v_mul_f32_e32 v110, v176, v176
	v_fmac_f32_e32 v110, v177, v177
	v_fmac_f32_e32 v110, v178, v178
	v_fmac_f32_e32 v110, v179, v179
	v_fmac_f32_e32 v110, v180, v180
	v_fmac_f32_e32 v110, v181, v181
	v_fmac_f32_e32 v110, v182, v182
	v_fmac_f32_e32 v110, v183, v183
	v_fmac_f32_e32 v110, v184, v184
	v_fmac_f32_e32 v110, v185, v185
	v_fmac_f32_e32 v110, v186, v186
	v_fmac_f32_e32 v110, v187, v187
	v_fmac_f32_e32 v110, v188, v188
	v_fmac_f32_e32 v110, v189, v189
	v_fmac_f32_e32 v110, v190, v190
	v_fmac_f32_e32 v110, v191, v191
	global_store_dwordx2 v105, v[16:17], s[12:13]
	global_store_dwordx2 v105, v[18:19], s[12:13] offset:512
	global_store_dwordx2 v105, v[20:21], s[12:13] offset:1024
	global_store_dwordx2 v105, v[22:23], s[12:13] offset:1536
	s_add_u32 s12, s12, 0x400000
	s_addc_u32 s13, s13, 0
	v_cvt_pk_bf16_f32 v24, v192, v193
	v_cvt_pk_bf16_f32 v25, v194, v195
	v_cvt_pk_bf16_f32 v26, v196, v197
	v_cvt_pk_bf16_f32 v27, v198, v199
	v_cvt_pk_bf16_f32 v28, v200, v201
	v_cvt_pk_bf16_f32 v29, v202, v203
	v_cvt_pk_bf16_f32 v30, v204, v205
	v_cvt_pk_bf16_f32 v31, v206, v207
	v_mul_f32_e32 v111, v192, v192
	v_fmac_f32_e32 v111, v193, v193
	v_fmac_f32_e32 v111, v194, v194
	v_fmac_f32_e32 v111, v195, v195
	v_fmac_f32_e32 v111, v196, v196
	v_fmac_f32_e32 v111, v197, v197
	v_fmac_f32_e32 v111, v198, v198
	v_fmac_f32_e32 v111, v199, v199
	v_fmac_f32_e32 v111, v200, v200
	v_fmac_f32_e32 v111, v201, v201
	v_fmac_f32_e32 v111, v202, v202
	v_fmac_f32_e32 v111, v203, v203
	v_fmac_f32_e32 v111, v204, v204
	v_fmac_f32_e32 v111, v205, v205
	v_fmac_f32_e32 v111, v206, v206
	v_fmac_f32_e32 v111, v207, v207
	global_store_dwordx2 v105, v[24:25], s[12:13]
	global_store_dwordx2 v105, v[26:27], s[12:13] offset:512
	global_store_dwordx2 v105, v[28:29], s[12:13] offset:1024
	global_store_dwordx2 v105, v[30:31], s[12:13] offset:1536
	s_add_u32 s12, s12, 0x400000
	s_addc_u32 s13, s13, 0
	v_cvt_pk_bf16_f32 v16, v208, v209
	v_cvt_pk_bf16_f32 v17, v210, v211
	v_cvt_pk_bf16_f32 v18, v212, v213
	v_cvt_pk_bf16_f32 v19, v214, v215
	v_cvt_pk_bf16_f32 v20, v216, v217
	v_cvt_pk_bf16_f32 v21, v218, v219
	v_cvt_pk_bf16_f32 v22, v220, v221
	v_cvt_pk_bf16_f32 v23, v222, v223
	v_mul_f32_e32 v112, v208, v208
	v_fmac_f32_e32 v112, v209, v209
	v_fmac_f32_e32 v112, v210, v210
	v_fmac_f32_e32 v112, v211, v211
	v_fmac_f32_e32 v112, v212, v212
	v_fmac_f32_e32 v112, v213, v213
	v_fmac_f32_e32 v112, v214, v214
	v_fmac_f32_e32 v112, v215, v215
	v_fmac_f32_e32 v112, v216, v216
	v_fmac_f32_e32 v112, v217, v217
	v_fmac_f32_e32 v112, v218, v218
	v_fmac_f32_e32 v112, v219, v219
	v_fmac_f32_e32 v112, v220, v220
	v_fmac_f32_e32 v112, v221, v221
	v_fmac_f32_e32 v112, v222, v222
	v_fmac_f32_e32 v112, v223, v223
	global_store_dwordx2 v105, v[16:17], s[12:13]
	global_store_dwordx2 v105, v[18:19], s[12:13] offset:512
	global_store_dwordx2 v105, v[20:21], s[12:13] offset:1024
	global_store_dwordx2 v105, v[22:23], s[12:13] offset:1536
	s_add_u32 s12, s12, 0x400000
	s_addc_u32 s13, s13, 0
	v_cvt_pk_bf16_f32 v24, v224, v225
	v_cvt_pk_bf16_f32 v25, v226, v227
	v_cvt_pk_bf16_f32 v26, v228, v229
	v_cvt_pk_bf16_f32 v27, v230, v231
	v_cvt_pk_bf16_f32 v28, v232, v233
	v_cvt_pk_bf16_f32 v29, v234, v235
	v_cvt_pk_bf16_f32 v30, v236, v237
	v_cvt_pk_bf16_f32 v31, v238, v239
	v_mul_f32_e32 v113, v224, v224
	v_fmac_f32_e32 v113, v225, v225
	v_fmac_f32_e32 v113, v226, v226
	v_fmac_f32_e32 v113, v227, v227
	v_fmac_f32_e32 v113, v228, v228
	v_fmac_f32_e32 v113, v229, v229
	v_fmac_f32_e32 v113, v230, v230
	v_fmac_f32_e32 v113, v231, v231
	v_fmac_f32_e32 v113, v232, v232
	v_fmac_f32_e32 v113, v233, v233
	v_fmac_f32_e32 v113, v234, v234
	v_fmac_f32_e32 v113, v235, v235
	v_fmac_f32_e32 v113, v236, v236
	v_fmac_f32_e32 v113, v237, v237
	v_fmac_f32_e32 v113, v238, v238
	v_fmac_f32_e32 v113, v239, v239
	global_store_dwordx2 v105, v[24:25], s[12:13]
	global_store_dwordx2 v105, v[26:27], s[12:13] offset:512
	global_store_dwordx2 v105, v[28:29], s[12:13] offset:1024
	global_store_dwordx2 v105, v[30:31], s[12:13] offset:1536
	s_add_u32 s12, s12, 0x400000
	s_addc_u32 s13, s13, 0
	v_add_f32_dpp v114, v110, v110 row_ror:8 row_mask:0xf bank_mask:0xf
	v_add_f32_dpp v115, v111, v111 row_ror:8 row_mask:0xf bank_mask:0xf
	v_add_f32_dpp v116, v112, v112 row_ror:8 row_mask:0xf bank_mask:0xf
	v_add_f32_dpp v117, v113, v113 row_ror:8 row_mask:0xf bank_mask:0xf
	v_add_f32_dpp v110, v114, v114 row_ror:4 row_mask:0xf bank_mask:0xf
	v_add_f32_dpp v111, v115, v115 row_ror:4 row_mask:0xf bank_mask:0xf
	v_add_f32_dpp v112, v116, v116 row_ror:4 row_mask:0xf bank_mask:0xf
	v_add_f32_dpp v113, v117, v117 row_ror:4 row_mask:0xf bank_mask:0xf
	v_add_f32_dpp v114, v110, v110 row_ror:2 row_mask:0xf bank_mask:0xf
	v_add_f32_dpp v115, v111, v111 row_ror:2 row_mask:0xf bank_mask:0xf
	v_add_f32_dpp v116, v112, v112 row_ror:2 row_mask:0xf bank_mask:0xf
	v_add_f32_dpp v117, v113, v113 row_ror:2 row_mask:0xf bank_mask:0xf
	v_add_f32_dpp v110, v114, v114 row_ror:1 row_mask:0xf bank_mask:0xf
	v_add_f32_dpp v111, v115, v115 row_ror:1 row_mask:0xf bank_mask:0xf
	v_add_f32_dpp v112, v116, v116 row_ror:1 row_mask:0xf bank_mask:0xf
	v_add_f32_dpp v113, v117, v117 row_ror:1 row_mask:0xf bank_mask:0xf
	ds_bpermute_b32 v114, v107, v110
	ds_bpermute_b32 v115, v107, v111
	ds_bpermute_b32 v116, v107, v112
	ds_bpermute_b32 v117, v107, v113
	s_waitcnt lgkmcnt(0)
	v_add_f32_e32 v110, v110, v114
	v_add_f32_e32 v111, v111, v115
	v_add_f32_e32 v112, v112, v116
	v_add_f32_e32 v113, v113, v117
	ds_bpermute_b32 v114, v108, v110
	ds_bpermute_b32 v115, v108, v111
	ds_bpermute_b32 v116, v108, v112
	ds_bpermute_b32 v117, v108, v113
	s_waitcnt lgkmcnt(0)
	v_add_f32_e32 v110, v110, v114
	v_add_f32_e32 v111, v111, v115
	v_add_f32_e32 v112, v112, v116
	v_add_f32_e32 v113, v113, v117
	v_cndmask_b32_e64 v110, v109, v110, s[16:17]
	v_cndmask_b32_e64 v111, v109, v111, s[16:17]
	v_cndmask_b32_e64 v112, v109, v112, s[16:17]
	v_cndmask_b32_e64 v113, v109, v113, s[16:17]
	s_and_saveexec_b64 s[18:19], s[4:5]
	global_store_dword v106, v110, s[14:15]
	s_add_u32 s14, s14, 0x20000
	s_addc_u32 s15, s15, 0
	global_store_dword v106, v111, s[14:15]
	s_add_u32 s14, s14, 0x20000
	s_addc_u32 s15, s15, 0
	global_store_dword v106, v112, s[14:15]
	s_add_u32 s14, s14, 0x20000
	s_addc_u32 s15, s15, 0
	global_store_dword v106, v113, s[14:15]
	s_add_u32 s14, s14, 0x20000
	s_addc_u32 s15, s15, 0
	s_mov_b64 exec, s[18:19]
	s_mov_b32 s99, 1
; #define LAS __attribute__((address_space(3)))
; #define LDS_WAIT() asm volatile("s_waitcnt lgkmcnt(0)" ::: "memory")
; #define lane (hw_lane())
; #define ws   (fresh_ptr(a.ws))
; __device__ __forceinline__ void transpose_item(const float* W, int K, int N, const float* gk, bf16* WT, bool up_perm, LAS float* scr, int item, int lane) {
;     const int nblk = N / 32, kb = item / nblk, nb = item % nblk, k0 = 64 * kb, n0 = 32 * nb;
; #pragma unroll 16
;     for (int i = 0; i < 32; ++i) { const int kk = 2 * i + (lane >> 5); float w = __builtin_nontemporal_load(W + (size_t)(k0 + kk) * N + n0 + (lane & 31)); if (gk) w *= gk[k0 + kk]; scr[kk * 33 + (lane & 31)] = w; }
;     LDS_WAIT(); asm volatile("" ::: "memory");
;     int nrow0 = n0; if (up_perm) { const int bj = n0 / FF, i = n0 % FF; nrow0 = 256 * (i / 128) + 128 * bj + (i % 128); }
;     const int c = lane & 7;
; #pragma unroll
;     for (int j = 0; j < 4; ++j) { const int n = (lane >> 3) + 8 * j; const LAS float* s = scr + (8 * c) * 33 + n;
; __device__ __forceinline__ void prologue(const Args& a, LAS unsigned char* lds, int gw, int NGW, int lane, int wave) {
;     LAS float* scr = (LAS float*)(lds + wave * 8448);
;     unsigned char* ws = a.ws;
;     constexpr int N_IN = 16 * 48, N_SQ = 16 * 32, N_UP = 16 * 176, N_DN = 44 * 32, N_POOL = 32, PER_L = N_IN + 5 * N_SQ + N_UP + N_DN + N_POOL;
;     for (int it = gw; it < DEPTH * PER_L; it += NGW) {
;         const int l = it / PER_L; int r = it % PER_L; unsigned char* wl = ws + WS_W + (size_t)l * W_LAYER;
;         if (r < N_IN) { transpose_item(a.in[I_WIN] + (size_t)l * D * DIN, D, DIN, a.in[I_NMIXG] + l * D, (bf16*)(wl + W_IN), false, scr, r, lane); continue; } r -= N_IN;
.Lxe_skip:
	s_cmpk_lt_i32 s72, 0x3b40
	s_cbranch_scc0 .LBB0_189
	s_add_u32 s3, s58, 0x100000
	s_addc_u32 s63, s59, 0
	v_readlane_b32 s16, v253, 3
	s_cmp_lg_u64 s[44:45], 0
	v_readlane_b32 s22, v253, 9
	v_readlane_b32 s23, v253, 10
	s_cselect_b64 s[4:5], -1, 0
	s_cmp_lg_u64 s[22:23], 0
	v_readlane_b32 s0, v253, 19
	v_lshlrev_b32_e32 v38, 3, v36
	s_cselect_b64 s[10:11], -1, 0
	s_cmp_lg_u64 s[80:81], 0
	s_mulk_i32 s0, 0x2100
	v_ashrrev_i32_e32 v1, 3, v36
	v_and_b32_e32 v4, 56, v38
	s_cselect_b64 s[12:13], -1, 0
	s_add_i32 s14, s0, 0x100
	v_ashrrev_i32_e32 v2, 5, v36
	s_movk_i32 s15, 0x84
	v_mul_u32_u24_e32 v3, 0x84, v4
	v_lshlrev_b32_e32 v5, 2, v1
	v_add3_u32 v5, s14, v3, v5
	v_add_u32_e32 v3, 0x200, v38
	v_mul_lo_u32 v6, v2, s15
	v_bfe_i32 v8, v36, 5, 24
	v_ashrrev_i32_e32 v10, 8, v3
	v_ashrrev_i32_e32 v3, 31, v2
	v_add_u32_e32 v12, s0, v6
	v_lshlrev_b32_e32 v6, 2, v36
	v_readlane_b32 s17, v253, 4
	v_readlane_b32 s18, v253, 5
	v_readlane_b32 s19, v253, 6
	v_readlane_b32 s20, v253, 7
	v_readlane_b32 s21, v253, 8
	v_readlane_b32 s24, v253, 11
	v_readlane_b32 s25, v253, 12
	v_readlane_b32 s26, v253, 13
	v_readlane_b32 s27, v253, 14
	v_readlane_b32 s28, v253, 15
	v_readlane_b32 s29, v253, 16
	v_readlane_b32 s30, v253, 17
	v_readlane_b32 s31, v253, 18
	s_movk_i32 s1, 0x100
	v_mov_b32_e32 v7, 0
	v_and_b32_e32 v32, 0xf8, v38
	v_ashrrev_i32_e32 v39, 31, v38
	v_ashrrev_i32_e32 v9, 31, v8
	v_ashrrev_i32_e32 v11, 31, v10
	v_and_b32_e32 v6, 0x7c, v6
	v_lshlrev_b64 v[24:25], 2, v[2:3]
	v_add_u32_e32 v35, 8, v1
	v_add_u32_e32 v37, 16, v1
	v_add_u32_e32 v78, 24, v1
	v_lshlrev_b64 v[8:9], 19, v[8:9]
	v_lshlrev_b64 v[10:11], 19, v[10:11]
	v_add3_u32 v79, v12, v6, s1
	v_lshl_add_u64 v[12:13], s[84:85], 0, v[6:7]
	v_add_u32_e32 v80, 30, v2
	v_add_u32_e32 v81, 28, v2
	v_add_u32_e32 v82, 26, v2
	v_add_u32_e32 v83, 24, v2
	v_add_u32_e32 v84, 22, v2
	v_add_u32_e32 v85, 20, v2
	v_add_u32_e32 v86, 18, v2
	v_add_u32_e32 v87, 16, v2
	v_add_u32_e32 v88, 14, v2
	v_add_u32_e32 v89, 12, v2
	v_add_u32_e32 v90, 10, v2
	v_add_u32_e32 v91, 8, v2
	v_add_u32_e32 v92, 6, v2
	v_add_u32_e32 v93, 4, v2
	v_add_u32_e32 v94, 2, v2
	v_lshl_add_u64 v[14:15], s[52:53], 0, v[6:7]
	v_lshl_add_u64 v[16:17], s[46:47], 0, v[6:7]
	v_lshl_add_u64 v[18:19], s[44:45], 0, v[24:25]
	v_lshl_add_u64 v[20:21], s[30:31], 0, v[6:7]
	v_lshl_add_u64 v[22:23], s[28:29], 0, v[6:7]
	v_lshl_add_u64 v[24:25], s[22:23], 0, v[24:25]
	v_lshl_add_u64 v[26:27], s[26:27], 0, v[6:7]
	v_lshl_add_u64 v[28:29], s[18:19], 0, v[6:7]
	v_lshl_add_u64 v[30:31], s[82:83], 0, v[6:7]
	s_mov_b32 s15, 0
	s_mov_b64 s[16:17], 0x1e00000
	s_movk_i32 s52, 0x7fff
	s_mov_b32 s53, 0xffff0000
	s_mov_b64 s[18:19], 0x1800000
	s_movk_i32 s64, 0x1600
	s_movk_i32 s65, 0x5800
	s_mov_b64 s[20:21], 0x80
	s_mov_b64 s[22:23], 0xd00000
	s_mov_b64 s[24:25], 0xb00000
	v_lshlrev_b32_e32 v32, 1, v32
	v_lshlrev_b64 v[38:39], 2, v[38:39]
	s_movk_i32 s66, 0x1800
	v_mov_b32_e32 v95, 0xb00000
	s_mov_b32 s67, s72
	s_mov_b64 s[26:27], 0x900000
	s_mov_b64 s[28:29], 0x700000
	s_mov_b64 s[30:31], 0x500000
	s_mov_b64 s[34:35], 0x300000
	s_branch .LBB0_13

; __device__ __forceinline__ unsigned pk2(float lo, float hi) { return f2bf(lo) | (f2bf(hi) << 16); }
; #define lane (hw_lane())
; #define ws   (fresh_ptr(a.ws))
; __device__ __forceinline__ void prologue(const Args& a, LAS unsigned char* lds, int gw, int NGW, int lane, int wave) {
;     ...
;     bf16* HB = (bf16*)(ws + WS_HB); float* slots = (float*)(ws + WS_SLOTS); bf16* MEMN = (bf16*)(ws + WS_MEMN);
;     {
;         f32x4 nv[4];
;         { const int m = gw; if (m < M + MMEM) { const f32x4* xr = (const f32x4*)((m >= M ? a.in[I_MEM] + (size_t)(m - M) * D : a.in[I_X] + (size_t)m * D)) + lane;
; #pragma unroll
;             for (int j = 0; j < 4; ++j) nv[j] = __builtin_nontemporal_load(xr + 64 * j); } }
;         for (int m = gw; m < M + MMEM; m += NGW) {
;             const bool is_mem = m >= M; const int row = is_mem ? m - M : m;
;             f32x4 v[4]; float s = 0.f;
; #pragma unroll
;             for (int j = 0; j < 4; ++j) v[j] = nv[j];
;             { const int mn = m + NGW; if (mn < M + MMEM) { const f32x4* xr = (const f32x4*)((mn >= M ? a.in[I_MEM] + (size_t)(mn - M) * D : a.in[I_X] + (size_t)mn * D)) + lane;
; #pragma unroll
;                 for (int j = 0; j < 4; ++j) nv[j] = __builtin_nontemporal_load(xr + 64 * j); } }
; #pragma unroll
;             for (int j = 0; j < 4; ++j) s += (v[j].x * v[j].x + v[j].y * v[j].y) + (v[j].z * v[j].z + v[j].w * v[j].w);
;             s = wave_sum(s);
;             float sc = 1.f;
;             if (is_mem) sc = __builtin_amdgcn_rsqf(s * (1.0f / D) + EPS);
;             else if (lane < 16) slots[(size_t)row * 16 + lane] = lane == 0 ? s : 0.f;
;             v2u* o8 = (v2u*)((is_mem ? MEMN : HB) + (size_t)row * D) + lane;
; #pragma unroll
;             for (int j = 0; j < 4; ++j) { v2u o; o.x = pk2(v[j].x * sc, v[j].y * sc); o.y = pk2(v[j].z * sc, v[j].w * sc); o8[64 * j] = o; }
.LBB0_199:
	s_or_b64 exec, exec, s[0:1]
	s_cmp_eq_u32 s99, 1
	s_cbranch_scc1 .Lxh_done
	s_cmp_lg_u32 s38, 0x800
	s_cbranch_scc1 .Lxh_skip
	s_cmp_ge_u32 s72, 0x800
	s_cbranch_scc1 .Lxh_skip
	v_readlane_b32 s10, v253, 20
	v_readlane_b32 s11, v253, 21
	s_lshl_b32 s0, s72, 12
	s_lshl_b32 s1, s72, 11
	s_lshl_b32 s3, s72, 6
	v_lshlrev_b32_e32 v104, 4, v36
	v_lshlrev_b32_e32 v105, 3, v36
	v_lshlrev_b32_e32 v106, 2, v36
	s_add_u32 s10, s10, s0
	s_addc_u32 s11, s11, 0
	s_add_u32 s12, s58, 0x7100000
	s_addc_u32 s13, s59, 0
	s_add_u32 s14, s58, 0x5500000
	s_addc_u32 s15, s59, 0
	v_xor_b32_e32 v107, 16, v36
	v_xor_b32_e32 v108, 32, v36
	s_add_u32 s12, s12, s1
	s_addc_u32 s13, s13, 0
	s_add_u32 s14, s14, s3
	s_addc_u32 s15, s15, 0
	v_lshlrev_b32_e32 v107, 2, v107
	v_lshlrev_b32_e32 v108, 2, v108
	v_mov_b32_e32 v109, 0
	v_cmp_gt_u32_e64 s[4:5], 16, v36
	v_cmp_eq_u32_e64 s[16:17], 0, v36
	global_load_dwordx4 v[40:43], v104, s[10:11] nt
	global_load_dwordx4 v[44:47], v104, s[10:11] offset:1024 nt
	global_load_dwordx4 v[48:51], v104, s[10:11] offset:2048 nt
	global_load_dwordx4 v[52:55], v104, s[10:11] offset:3072 nt
	s_add_u32 s10, s10, 0x800000
	s_addc_u32 s11, s11, 0
	global_load_dwordx4 v[56:59], v104, s[10:11] nt
	global_load_dwordx4 v[60:63], v104, s[10:11] offset:1024 nt
	global_load_dwordx4 v[64:67], v104, s[10:11] offset:2048 nt
	global_load_dwordx4 v[68:71], v104, s[10:11] offset:3072 nt
	s_add_u32 s10, s10, 0x800000
	s_addc_u32 s11, s11, 0
	global_load_dwordx4 v[72:75], v104, s[10:11] nt
	global_load_dwordx4 v[76:79], v104, s[10:11] offset:1024 nt
	global_load_dwordx4 v[80:83], v104, s[10:11] offset:2048 nt
	global_load_dwordx4 v[84:87], v104, s[10:11] offset:3072 nt
	s_add_u32 s10, s10, 0x800000
	s_addc_u32 s11, s11, 0
	global_load_dwordx4 v[88:91], v104, s[10:11] nt
	global_load_dwordx4 v[92:95], v104, s[10:11] offset:1024 nt
	global_load_dwordx4 v[96:99], v104, s[10:11] offset:2048 nt
	global_load_dwordx4 v[100:103], v104, s[10:11] offset:3072 nt
	s_add_u32 s10, s10, 0x800000
	s_addc_u32 s11, s11, 0
	global_load_dwordx4 v[176:179], v104, s[10:11] nt
	global_load_dwordx4 v[180:183], v104, s[10:11] offset:1024 nt
	global_load_dwordx4 v[184:187], v104, s[10:11] offset:2048 nt
	global_load_dwordx4 v[188:191], v104, s[10:11] offset:3072 nt
	s_add_u32 s10, s10, 0x800000
	s_addc_u32 s11, s11, 0
	global_load_dwordx4 v[192:195], v104, s[10:11] nt
	global_load_dwordx4 v[196:199], v104, s[10:11] offset:1024 nt
	global_load_dwordx4 v[200:203], v104, s[10:11] offset:2048 nt
	global_load_dwordx4 v[204:207], v104, s[10:11] offset:3072 nt
	s_add_u32 s10, s10, 0x800000
	s_addc_u32 s11, s11, 0
	global_load_dwordx4 v[208:211], v104, s[10:11] nt
	global_load_dwordx4 v[212:215], v104, s[10:11] offset:1024 nt
	global_load_dwordx4 v[216:219], v104, s[10:11] offset:2048 nt
	global_load_dwordx4 v[220:223], v104, s[10:11] offset:3072 nt
	s_add_u32 s10, s10, 0x800000
	s_addc_u32 s11, s11, 0
	global_load_dwordx4 v[224:227], v104, s[10:11] nt
	global_load_dwordx4 v[228:231], v104, s[10:11] offset:1024 nt
	global_load_dwordx4 v[232:235], v104, s[10:11] offset:2048 nt
	global_load_dwordx4 v[236:239], v104, s[10:11] offset:3072 nt
	s_add_u32 s10, s10, 0x800000
	s_addc_u32 s11, s11, 0
	s_waitcnt vmcnt(16)
	v_cvt_pk_bf16_f32 v16, v40, v41
	v_cvt_pk_bf16_f32 v17, v42, v43
	v_cvt_pk_bf16_f32 v18, v44, v45
	v_cvt_pk_bf16_f32 v19, v46, v47
	v_cvt_pk_bf16_f32 v20, v48, v49
	v_cvt_pk_bf16_f32 v21, v50, v51
	v_cvt_pk_bf16_f32 v22, v52, v53
	v_cvt_pk_bf16_f32 v23, v54, v55
	v_mul_f32_e32 v110, v40, v40
	v_fmac_f32_e32 v110, v41, v41
	v_fmac_f32_e32 v110, v42, v42
	v_fmac_f32_e32 v110, v43, v43
	v_fmac_f32_e32 v110, v44, v44
	v_fmac_f32_e32 v110, v45, v45
	v_fmac_f32_e32 v110, v46, v46
	v_fmac_f32_e32 v110, v47, v47
	v_fmac_f32_e32 v110, v48, v48
	v_fmac_f32_e32 v110, v49, v49
	v_fmac_f32_e32 v110, v50, v50
	v_fmac_f32_e32 v110, v51, v51
	v_fmac_f32_e32 v110, v52, v52
	v_fmac_f32_e32 v110, v53, v53
	v_fmac_f32_e32 v110, v54, v54
	v_fmac_f32_e32 v110, v55, v55
	global_store_dwordx2 v105, v[16:17], s[12:13]
	global_store_dwordx2 v105, v[18:19], s[12:13] offset:512
	global_store_dwordx2 v105, v[20:21], s[12:13] offset:1024
	global_store_dwordx2 v105, v[22:23], s[12:13] offset:1536
	s_add_u32 s12, s12, 0x400000
	s_addc_u32 s13, s13, 0
	v_cvt_pk_bf16_f32 v24, v56, v57
	v_cvt_pk_bf16_f32 v25, v58, v59
	v_cvt_pk_bf16_f32 v26, v60, v61
	v_cvt_pk_bf16_f32 v27, v62, v63
	v_cvt_pk_bf16_f32 v28, v64, v65
	v_cvt_pk_bf16_f32 v29, v66, v67
	v_cvt_pk_bf16_f32 v30, v68, v69
	v_cvt_pk_bf16_f32 v31, v70, v71
	v_mul_f32_e32 v111, v56, v56
	v_fmac_f32_e32 v111, v57, v57
	v_fmac_f32_e32 v111, v58, v58
	v_fmac_f32_e32 v111, v59, v59
	v_fmac_f32_e32 v111, v60, v60
	v_fmac_f32_e32 v111, v61, v61
	v_fmac_f32_e32 v111, v62, v62
	v_fmac_f32_e32 v111, v63, v63
	v_fmac_f32_e32 v111, v64, v64
	v_fmac_f32_e32 v111, v65, v65
	v_fmac_f32_e32 v111, v66, v66
	v_fmac_f32_e32 v111, v67, v67
	v_fmac_f32_e32 v111, v68, v68
	v_fmac_f32_e32 v111, v69, v69
	v_fmac_f32_e32 v111, v70, v70
	v_fmac_f32_e32 v111, v71, v71
	global_store_dwordx2 v105, v[24:25], s[12:13]
	global_store_dwordx2 v105, v[26:27], s[12:13] offset:512
	global_store_dwordx2 v105, v[28:29], s[12:13] offset:1024
	global_store_dwordx2 v105, v[30:31], s[12:13] offset:1536
	s_add_u32 s12, s12, 0x400000
	s_addc_u32 s13, s13, 0
	v_cvt_pk_bf16_f32 v16, v72, v73
	v_cvt_pk_bf16_f32 v17, v74, v75
	v_cvt_pk_bf16_f32 v18, v76, v77
	v_cvt_pk_bf16_f32 v19, v78, v79
	v_cvt_pk_bf16_f32 v20, v80, v81
	v_cvt_pk_bf16_f32 v21, v82, v83
	v_cvt_pk_bf16_f32 v22, v84, v85
	v_cvt_pk_bf16_f32 v23, v86, v87
	v_mul_f32_e32 v112, v72, v72
	v_fmac_f32_e32 v112, v73, v73
; __device__ __forceinline__ unsigned pk2(float lo, float hi) { return f2bf(lo) | (f2bf(hi) << 16); }
; #define lane (hw_lane())
; __device__ __forceinline__ float wave_sum(float v) {
; #pragma unroll
;     for (int o = 1; o < 64; o <<= 1) v += __shfl_xor(v, o);
;     return v;
; __device__ __forceinline__ void prologue(const Args& a, LAS unsigned char* lds, int gw, int NGW, int lane, int wave) {
;     ...
;         for (int m = gw; m < M + MMEM; m += NGW) {
;             const bool is_mem = m >= M; const int row = is_mem ? m - M : m;
;             f32x4 v[4]; float s = 0.f;
; #pragma unroll
;             for (int j = 0; j < 4; ++j) v[j] = nv[j];
;             { const int mn = m + NGW; if (mn < M + MMEM) { const f32x4* xr = (const f32x4*)((mn >= M ? a.in[I_MEM] + (size_t)(mn - M) * D : a.in[I_X] + (size_t)mn * D)) + lane;
; #pragma unroll
;                 for (int j = 0; j < 4; ++j) nv[j] = __builtin_nontemporal_load(xr + 64 * j); } }
; #pragma unroll
;             for (int j = 0; j < 4; ++j) s += (v[j].x * v[j].x + v[j].y * v[j].y) + (v[j].z * v[j].z + v[j].w * v[j].w);
;             s = wave_sum(s);
;             float sc = 1.f;
;             if (is_mem) sc = __builtin_amdgcn_rsqf(s * (1.0f / D) + EPS);
;             else if (lane < 16) slots[(size_t)row * 16 + lane] = lane == 0 ? s : 0.f;
;             v2u* o8 = (v2u*)((is_mem ? MEMN : HB) + (size_t)row * D) + lane;
; #pragma unroll
;             for (int j = 0; j < 4; ++j) { v2u o; o.x = pk2(v[j].x * sc, v[j].y * sc); o.y = pk2(v[j].z * sc, v[j].w * sc); o8[64 * j] = o; }
	v_fmac_f32_e32 v112, v74, v74
	v_fmac_f32_e32 v112, v75, v75
	v_fmac_f32_e32 v112, v76, v76
	v_fmac_f32_e32 v112, v77, v77
	v_fmac_f32_e32 v112, v78, v78
	v_fmac_f32_e32 v112, v79, v79
	v_fmac_f32_e32 v112, v80, v80
	v_fmac_f32_e32 v112, v81, v81
	v_fmac_f32_e32 v112, v82, v82
	v_fmac_f32_e32 v112, v83, v83
	v_fmac_f32_e32 v112, v84, v84
	v_fmac_f32_e32 v112, v85, v85
	v_fmac_f32_e32 v112, v86, v86
	v_fmac_f32_e32 v112, v87, v87
	global_store_dwordx2 v105, v[16:17], s[12:13]
	global_store_dwordx2 v105, v[18:19], s[12:13] offset:512
	global_store_dwordx2 v105, v[20:21], s[12:13] offset:1024
	global_store_dwordx2 v105, v[22:23], s[12:13] offset:1536
	s_add_u32 s12, s12, 0x400000
	s_addc_u32 s13, s13, 0
	v_cvt_pk_bf16_f32 v24, v88, v89
	v_cvt_pk_bf16_f32 v25, v90, v91
	v_cvt_pk_bf16_f32 v26, v92, v93
	v_cvt_pk_bf16_f32 v27, v94, v95
	v_cvt_pk_bf16_f32 v28, v96, v97
	v_cvt_pk_bf16_f32 v29, v98, v99
	v_cvt_pk_bf16_f32 v30, v100, v101
	v_cvt_pk_bf16_f32 v31, v102, v103
	v_mul_f32_e32 v113, v88, v88
	v_fmac_f32_e32 v113, v89, v89
	v_fmac_f32_e32 v113, v90, v90
	v_fmac_f32_e32 v113, v91, v91
	v_fmac_f32_e32 v113, v92, v92
	v_fmac_f32_e32 v113, v93, v93
	v_fmac_f32_e32 v113, v94, v94
	v_fmac_f32_e32 v113, v95, v95
	v_fmac_f32_e32 v113, v96, v96
	v_fmac_f32_e32 v113, v97, v97
	v_fmac_f32_e32 v113, v98, v98
	v_fmac_f32_e32 v113, v99, v99
	v_fmac_f32_e32 v113, v100, v100
	v_fmac_f32_e32 v113, v101, v101
	v_fmac_f32_e32 v113, v102, v102
	v_fmac_f32_e32 v113, v103, v103
	global_store_dwordx2 v105, v[24:25], s[12:13]
	global_store_dwordx2 v105, v[26:27], s[12:13] offset:512
	global_store_dwordx2 v105, v[28:29], s[12:13] offset:1024
	global_store_dwordx2 v105, v[30:31], s[12:13] offset:1536
	s_add_u32 s12, s12, 0x400000
	s_addc_u32 s13, s13, 0
	v_add_f32_dpp v114, v110, v110 row_ror:8 row_mask:0xf bank_mask:0xf
	v_add_f32_dpp v115, v111, v111 row_ror:8 row_mask:0xf bank_mask:0xf
	v_add_f32_dpp v116, v112, v112 row_ror:8 row_mask:0xf bank_mask:0xf
	v_add_f32_dpp v117, v113, v113 row_ror:8 row_mask:0xf bank_mask:0xf
	v_add_f32_dpp v110, v114, v114 row_ror:4 row_mask:0xf bank_mask:0xf
	v_add_f32_dpp v111, v115, v115 row_ror:4 row_mask:0xf bank_mask:0xf
	v_add_f32_dpp v112, v116, v116 row_ror:4 row_mask:0xf bank_mask:0xf
	v_add_f32_dpp v113, v117, v117 row_ror:4 row_mask:0xf bank_mask:0xf
	v_add_f32_dpp v114, v110, v110 row_ror:2 row_mask:0xf bank_mask:0xf
	v_add_f32_dpp v115, v111, v111 row_ror:2 row_mask:0xf bank_mask:0xf
	v_add_f32_dpp v116, v112, v112 row_ror:2 row_mask:0xf bank_mask:0xf
	v_add_f32_dpp v117, v113, v113 row_ror:2 row_mask:0xf bank_mask:0xf
	v_add_f32_dpp v110, v114, v114 row_ror:1 row_mask:0xf bank_mask:0xf
	v_add_f32_dpp v111, v115, v115 row_ror:1 row_mask:0xf bank_mask:0xf
	v_add_f32_dpp v112, v116, v116 row_ror:1 row_mask:0xf bank_mask:0xf
	v_add_f32_dpp v113, v117, v117 row_ror:1 row_mask:0xf bank_mask:0xf
	ds_bpermute_b32 v114, v107, v110
	ds_bpermute_b32 v115, v107, v111
	ds_bpermute_b32 v116, v107, v112
	ds_bpermute_b32 v117, v107, v113
	s_waitcnt lgkmcnt(0)
	v_add_f32_e32 v110, v110, v114
	v_add_f32_e32 v111, v111, v115
	v_add_f32_e32 v112, v112, v116
	v_add_f32_e32 v113, v113, v117
	ds_bpermute_b32 v114, v108, v110
	ds_bpermute_b32 v115, v108, v111
	ds_bpermute_b32 v116, v108, v112
	ds_bpermute_b32 v117, v108, v113
	s_waitcnt lgkmcnt(0)
	v_add_f32_e32 v110, v110, v114
	v_add_f32_e32 v111, v111, v115
	v_add_f32_e32 v112, v112, v116
	v_add_f32_e32 v113, v113, v117
	v_cndmask_b32_e64 v110, v109, v110, s[16:17]
	v_cndmask_b32_e64 v111, v109, v111, s[16:17]
	v_cndmask_b32_e64 v112, v109, v112, s[16:17]
	v_cndmask_b32_e64 v113, v109, v113, s[16:17]
	s_and_saveexec_b64 s[18:19], s[4:5]
	global_store_dword v106, v110, s[14:15]
	s_add_u32 s14, s14, 0x20000
	s_addc_u32 s15, s15, 0
	global_store_dword v106, v111, s[14:15]
	s_add_u32 s14, s14, 0x20000
	s_addc_u32 s15, s15, 0
	global_store_dword v106, v112, s[14:15]
	s_add_u32 s14, s14, 0x20000
	s_addc_u32 s15, s15, 0
	global_store_dword v106, v113, s[14:15]
	s_add_u32 s14, s14, 0x20000
	s_addc_u32 s15, s15, 0
	s_mov_b64 exec, s[18:19]
	global_load_dwordx4 v[40:43], v104, s[10:11] nt
	global_load_dwordx4 v[44:47], v104, s[10:11] offset:1024 nt
	global_load_dwordx4 v[48:51], v104, s[10:11] offset:2048 nt
	global_load_dwordx4 v[52:55], v104, s[10:11] offset:3072 nt
	s_add_u32 s10, s10, 0x800000
	s_addc_u32 s11, s11, 0
	global_load_dwordx4 v[56:59], v104, s[10:11] nt
	global_load_dwordx4 v[60:63], v104, s[10:11] offset:1024 nt
	global_load_dwordx4 v[64:67], v104, s[10:11] offset:2048 nt
	global_load_dwordx4 v[68:71], v104, s[10:11] offset:3072 nt
	s_add_u32 s10, s10, 0x800000
	s_addc_u32 s11, s11, 0
	global_load_dwordx4 v[72:75], v104, s[10:11] nt
	global_load_dwordx4 v[76:79], v104, s[10:11] offset:1024 nt
	global_load_dwordx4 v[80:83], v104, s[10:11] offset:2048 nt
	global_load_dwordx4 v[84:87], v104, s[10:11] offset:3072 nt
	s_add_u32 s10, s10, 0x800000
	s_addc_u32 s11, s11, 0
	global_load_dwordx4 v[88:91], v104, s[10:11] nt
	global_load_dwordx4 v[92:95], v104, s[10:11] offset:1024 nt
	global_load_dwordx4 v[96:99], v104, s[10:11] offset:2048 nt
	global_load_dwordx4 v[100:103], v104, s[10:11] offset:3072 nt
	s_add_u32 s10, s10, 0x800000
	s_addc_u32 s11, s11, 0
	s_waitcnt vmcnt(36)
; __device__ __forceinline__ unsigned pk2(float lo, float hi) { return f2bf(lo) | (f2bf(hi) << 16); }
; #define lane (hw_lane())
; __device__ __forceinline__ float wave_sum(float v) {
; #pragma unroll
;     for (int o = 1; o < 64; o <<= 1) v += __shfl_xor(v, o);
;     return v;
; __device__ __forceinline__ void prologue(const Args& a, LAS unsigned char* lds, int gw, int NGW, int lane, int wave) {
;     ...
;         for (int m = gw; m < M + MMEM; m += NGW) {
;             const bool is_mem = m >= M; const int row = is_mem ? m - M : m;
;             f32x4 v[4]; float s = 0.f;
; #pragma unroll
;             for (int j = 0; j < 4; ++j) v[j] = nv[j];
;             { const int mn = m + NGW; if (mn < M + MMEM) { const f32x4* xr = (const f32x4*)((mn >= M ? a.in[I_MEM] + (size_t)(mn - M) * D : a.in[I_X] + (size_t)mn * D)) + lane;
; #pragma unroll
;                 for (int j = 0; j < 4; ++j) nv[j] = __builtin_nontemporal_load(xr + 64 * j); } }
; #pragma unroll
;             for (int j = 0; j < 4; ++j) s += (v[j].x * v[j].x + v[j].y * v[j].y) + (v[j].z * v[j].z + v[j].w * v[j].w);
;             s = wave_sum(s);
;             float sc = 1.f;
;             if (is_mem) sc = __builtin_amdgcn_rsqf(s * (1.0f / D) + EPS);
;             else if (lane < 16) slots[(size_t)row * 16 + lane] = lane == 0 ? s : 0.f;
;             v2u* o8 = (v2u*)((is_mem ? MEMN : HB) + (size_t)row * D) + lane;
; #pragma unroll
;             for (int j = 0; j < 4; ++j) { v2u o; o.x = pk2(v[j].x * sc, v[j].y * sc); o.y = pk2(v[j].z * sc, v[j].w * sc); o8[64 * j] = o; }
	v_cvt_pk_bf16_f32 v16, v176, v177
	v_cvt_pk_bf16_f32 v17, v178, v179
	v_cvt_pk_bf16_f32 v18, v180, v181
	v_cvt_pk_bf16_f32 v19, v182, v183
	v_cvt_pk_bf16_f32 v20, v184, v185
	v_cvt_pk_bf16_f32 v21, v186, v187
	v_cvt_pk_bf16_f32 v22, v188, v189
	v_cvt_pk_bf16_f32 v23, v190, v191
	v_mul_f32_e32 v110, v176, v176
	v_fmac_f32_e32 v110, v177, v177
	v_fmac_f32_e32 v110, v178, v178
	v_fmac_f32_e32 v110, v179, v179
	v_fmac_f32_e32 v110, v180, v180
	v_fmac_f32_e32 v110, v181, v181
	v_fmac_f32_e32 v110, v182, v182
	v_fmac_f32_e32 v110, v183, v183
	v_fmac_f32_e32 v110, v184, v184
	v_fmac_f32_e32 v110, v185, v185
	v_fmac_f32_e32 v110, v186, v186
	v_fmac_f32_e32 v110, v187, v187
	v_fmac_f32_e32 v110, v188, v188
	v_fmac_f32_e32 v110, v189, v189
	v_fmac_f32_e32 v110, v190, v190
	v_fmac_f32_e32 v110, v191, v191
	global_store_dwordx2 v105, v[16:17], s[12:13]
	global_store_dwordx2 v105, v[18:19], s[12:13] offset:512
	global_store_dwordx2 v105, v[20:21], s[12:13] offset:1024
	global_store_dwordx2 v105, v[22:23], s[12:13] offset:1536
	s_add_u32 s12, s12, 0x400000
	s_addc_u32 s13, s13, 0
	v_cvt_pk_bf16_f32 v24, v192, v193
	v_cvt_pk_bf16_f32 v25, v194, v195
	v_cvt_pk_bf16_f32 v26, v196, v197
	v_cvt_pk_bf16_f32 v27, v198, v199
	v_cvt_pk_bf16_f32 v28, v200, v201
	v_cvt_pk_bf16_f32 v29, v202, v203
	v_cvt_pk_bf16_f32 v30, v204, v205
	v_cvt_pk_bf16_f32 v31, v206, v207
	v_mul_f32_e32 v111, v192, v192
	v_fmac_f32_e32 v111, v193, v193
	v_fmac_f32_e32 v111, v194, v194
	v_fmac_f32_e32 v111, v195, v195
	v_fmac_f32_e32 v111, v196, v196
	v_fmac_f32_e32 v111, v197, v197
	v_fmac_f32_e32 v111, v198, v198
	v_fmac_f32_e32 v111, v199, v199
	v_fmac_f32_e32 v111, v200, v200
	v_fmac_f32_e32 v111, v201, v201
	v_fmac_f32_e32 v111, v202, v202
	v_fmac_f32_e32 v111, v203, v203
	v_fmac_f32_e32 v111, v204, v204
	v_fmac_f32_e32 v111, v205, v205
	v_fmac_f32_e32 v111, v206, v206
	v_fmac_f32_e32 v111, v207, v207
	global_store_dwordx2 v105, v[24:25], s[12:13]
	global_store_dwordx2 v105, v[26:27], s[12:13] offset:512
	global_store_dwordx2 v105, v[28:29], s[12:13] offset:1024
	global_store_dwordx2 v105, v[30:31], s[12:13] offset:1536
	s_add_u32 s12, s12, 0x400000
	s_addc_u32 s13, s13, 0
	v_cvt_pk_bf16_f32 v16, v208, v209
	v_cvt_pk_bf16_f32 v17, v210, v211
	v_cvt_pk_bf16_f32 v18, v212, v213
	v_cvt_pk_bf16_f32 v19, v214, v215
	v_cvt_pk_bf16_f32 v20, v216, v217
	v_cvt_pk_bf16_f32 v21, v218, v219
	v_cvt_pk_bf16_f32 v22, v220, v221
	v_cvt_pk_bf16_f32 v23, v222, v223
	v_mul_f32_e32 v112, v208, v208
	v_fmac_f32_e32 v112, v209, v209
	v_fmac_f32_e32 v112, v210, v210
	v_fmac_f32_e32 v112, v211, v211
	v_fmac_f32_e32 v112, v212, v212
	v_fmac_f32_e32 v112, v213, v213
	v_fmac_f32_e32 v112, v214, v214
	v_fmac_f32_e32 v112, v215, v215
	v_fmac_f32_e32 v112, v216, v216
	v_fmac_f32_e32 v112, v217, v217
	v_fmac_f32_e32 v112, v218, v218
	v_fmac_f32_e32 v112, v219, v219
	v_fmac_f32_e32 v112, v220, v220
	v_fmac_f32_e32 v112, v221, v221
	v_fmac_f32_e32 v112, v222, v222
	v_fmac_f32_e32 v112, v223, v223
	global_store_dwordx2 v105, v[16:17], s[12:13]
	global_store_dwordx2 v105, v[18:19], s[12:13] offset:512
	global_store_dwordx2 v105, v[20:21], s[12:13] offset:1024
	global_store_dwordx2 v105, v[22:23], s[12:13] offset:1536
	s_add_u32 s12, s12, 0x400000
	s_addc_u32 s13, s13, 0
	v_cvt_pk_bf16_f32 v24, v224, v225
	v_cvt_pk_bf16_f32 v25, v226, v227
	v_cvt_pk_bf16_f32 v26, v228, v229
	v_cvt_pk_bf16_f32 v27, v230, v231
	v_cvt_pk_bf16_f32 v28, v232, v233
	v_cvt_pk_bf16_f32 v29, v234, v235
	v_cvt_pk_bf16_f32 v30, v236, v237
	v_cvt_pk_bf16_f32 v31, v238, v239
	v_mul_f32_e32 v113, v224, v224
	v_fmac_f32_e32 v113, v225, v225
	v_fmac_f32_e32 v113, v226, v226
	v_fmac_f32_e32 v113, v227, v227
	v_fmac_f32_e32 v113, v228, v228
	v_fmac_f32_e32 v113, v229, v229
	v_fmac_f32_e32 v113, v230, v230
	v_fmac_f32_e32 v113, v231, v231
	v_fmac_f32_e32 v113, v232, v232
	v_fmac_f32_e32 v113, v233, v233
	v_fmac_f32_e32 v113, v234, v234
	v_fmac_f32_e32 v113, v235, v235
	v_fmac_f32_e32 v113, v236, v236
	v_fmac_f32_e32 v113, v237, v237
	v_fmac_f32_e32 v113, v238, v238
	v_fmac_f32_e32 v113, v239, v239
	global_store_dwordx2 v105, v[24:25], s[12:13]
	global_store_dwordx2 v105, v[26:27], s[12:13] offset:512
	global_store_dwordx2 v105, v[28:29], s[12:13] offset:1024
	global_store_dwordx2 v105, v[30:31], s[12:13] offset:1536
	s_add_u32 s12, s12, 0x400000
	s_addc_u32 s13, s13, 0
	v_add_f32_dpp v114, v110, v110 row_ror:8 row_mask:0xf bank_mask:0xf
	v_add_f32_dpp v115, v111, v111 row_ror:8 row_mask:0xf bank_mask:0xf
	v_add_f32_dpp v116, v112, v112 row_ror:8 row_mask:0xf bank_mask:0xf
	v_add_f32_dpp v117, v113, v113 row_ror:8 row_mask:0xf bank_mask:0xf
	v_add_f32_dpp v110, v114, v114 row_ror:4 row_mask:0xf bank_mask:0xf
	v_add_f32_dpp v111, v115, v115 row_ror:4 row_mask:0xf bank_mask:0xf
	v_add_f32_dpp v112, v116, v116 row_ror:4 row_mask:0xf bank_mask:0xf
	v_add_f32_dpp v113, v117, v117 row_ror:4 row_mask:0xf bank_mask:0xf
	v_add_f32_dpp v114, v110, v110 row_ror:2 row_mask:0xf bank_mask:0xf
	v_add_f32_dpp v115, v111, v111 row_ror:2 row_mask:0xf bank_mask:0xf
	v_add_f32_dpp v116, v112, v112 row_ror:2 row_mask:0xf bank_mask:0xf
	v_add_f32_dpp v117, v113, v113 row_ror:2 row_mask:0xf bank_mask:0xf
	v_add_f32_dpp v110, v114, v114 row_ror:1 row_mask:0xf bank_mask:0xf
	v_add_f32_dpp v111, v115, v115 row_ror:1 row_mask:0xf bank_mask:0xf
	v_add_f32_dpp v112, v116, v116 row_ror:1 row_mask:0xf bank_mask:0xf
	v_add_f32_dpp v113, v117, v117 row_ror:1 row_mask:0xf bank_mask:0xf
	ds_bpermute_b32 v114, v107, v110
	ds_bpermute_b32 v115, v107, v111
	ds_bpermute_b32 v116, v107, v112
	ds_bpermute_b32 v117, v107, v113
	s_waitcnt lgkmcnt(0)
; __device__ __forceinline__ unsigned pk2(float lo, float hi) { return f2bf(lo) | (f2bf(hi) << 16); }
; #define lane (hw_lane())
; __device__ __forceinline__ float wave_sum(float v) {
; #pragma unroll
;     for (int o = 1; o < 64; o <<= 1) v += __shfl_xor(v, o);
;     return v;
; __device__ __forceinline__ void prologue(const Args& a, LAS unsigned char* lds, int gw, int NGW, int lane, int wave) {
;     ...
;         for (int m = gw; m < M + MMEM; m += NGW) {
;             const bool is_mem = m >= M; const int row = is_mem ? m - M : m;
;             f32x4 v[4]; float s = 0.f;
; #pragma unroll
;             for (int j = 0; j < 4; ++j) v[j] = nv[j];
;             { const int mn = m + NGW; if (mn < M + MMEM) { const f32x4* xr = (const f32x4*)((mn >= M ? a.in[I_MEM] + (size_t)(mn - M) * D : a.in[I_X] + (size_t)mn * D)) + lane;
; #pragma unroll
;                 for (int j = 0; j < 4; ++j) nv[j] = __builtin_nontemporal_load(xr + 64 * j); } }
; #pragma unroll
;             for (int j = 0; j < 4; ++j) s += (v[j].x * v[j].x + v[j].y * v[j].y) + (v[j].z * v[j].z + v[j].w * v[j].w);
;             s = wave_sum(s);
;             float sc = 1.f;
;             if (is_mem) sc = __builtin_amdgcn_rsqf(s * (1.0f / D) + EPS);
;             else if (lane < 16) slots[(size_t)row * 16 + lane] = lane == 0 ? s : 0.f;
;             v2u* o8 = (v2u*)((is_mem ? MEMN : HB) + (size_t)row * D) + lane;
; #pragma unroll
;             for (int j = 0; j < 4; ++j) { v2u o; o.x = pk2(v[j].x * sc, v[j].y * sc); o.y = pk2(v[j].z * sc, v[j].w * sc); o8[64 * j] = o; }
	v_add_f32_e32 v110, v110, v114
	v_add_f32_e32 v111, v111, v115
	v_add_f32_e32 v112, v112, v116
	v_add_f32_e32 v113, v113, v117
	ds_bpermute_b32 v114, v108, v110
	ds_bpermute_b32 v115, v108, v111
	ds_bpermute_b32 v116, v108, v112
	ds_bpermute_b32 v117, v108, v113
	s_waitcnt lgkmcnt(0)
	v_add_f32_e32 v110, v110, v114
	v_add_f32_e32 v111, v111, v115
	v_add_f32_e32 v112, v112, v116
	v_add_f32_e32 v113, v113, v117
	v_cndmask_b32_e64 v110, v109, v110, s[16:17]
	v_cndmask_b32_e64 v111, v109, v111, s[16:17]
	v_cndmask_b32_e64 v112, v109, v112, s[16:17]
	v_cndmask_b32_e64 v113, v109, v113, s[16:17]
	s_and_saveexec_b64 s[18:19], s[4:5]
	global_store_dword v106, v110, s[14:15]
	s_add_u32 s14, s14, 0x20000
	s_addc_u32 s15, s15, 0
	global_store_dword v106, v111, s[14:15]
	s_add_u32 s14, s14, 0x20000
	s_addc_u32 s15, s15, 0
	global_store_dword v106, v112, s[14:15]
	s_add_u32 s14, s14, 0x20000
	s_addc_u32 s15, s15, 0
	global_store_dword v106, v113, s[14:15]
	s_add_u32 s14, s14, 0x20000
	s_addc_u32 s15, s15, 0
	s_mov_b64 exec, s[18:19]
	global_load_dwordx4 v[176:179], v104, s[10:11] nt
	global_load_dwordx4 v[180:183], v104, s[10:11] offset:1024 nt
	global_load_dwordx4 v[184:187], v104, s[10:11] offset:2048 nt
	global_load_dwordx4 v[188:191], v104, s[10:11] offset:3072 nt
	s_add_u32 s10, s10, 0x800000
	s_addc_u32 s11, s11, 0
	global_load_dwordx4 v[192:195], v104, s[10:11] nt
	global_load_dwordx4 v[196:199], v104, s[10:11] offset:1024 nt
	global_load_dwordx4 v[200:203], v104, s[10:11] offset:2048 nt
	global_load_dwordx4 v[204:207], v104, s[10:11] offset:3072 nt
	s_add_u32 s10, s10, 0x800000
	s_addc_u32 s11, s11, 0
	global_load_dwordx4 v[208:211], v104, s[10:11] nt
	global_load_dwordx4 v[212:215], v104, s[10:11] offset:1024 nt
	global_load_dwordx4 v[216:219], v104, s[10:11] offset:2048 nt
	global_load_dwordx4 v[220:223], v104, s[10:11] offset:3072 nt
	s_add_u32 s10, s10, 0x800000
	s_addc_u32 s11, s11, 0
	global_load_dwordx4 v[224:227], v104, s[10:11] nt
	global_load_dwordx4 v[228:231], v104, s[10:11] offset:1024 nt
	global_load_dwordx4 v[232:235], v104, s[10:11] offset:2048 nt
	global_load_dwordx4 v[236:239], v104, s[10:11] offset:3072 nt
	s_add_u32 s10, s10, 0x800000
	s_addc_u32 s11, s11, 0
	s_waitcnt vmcnt(36)
	v_cvt_pk_bf16_f32 v16, v40, v41
	v_cvt_pk_bf16_f32 v17, v42, v43
	v_cvt_pk_bf16_f32 v18, v44, v45
	v_cvt_pk_bf16_f32 v19, v46, v47
	v_cvt_pk_bf16_f32 v20, v48, v49
	v_cvt_pk_bf16_f32 v21, v50, v51
	v_cvt_pk_bf16_f32 v22, v52, v53
	v_cvt_pk_bf16_f32 v23, v54, v55
	v_mul_f32_e32 v110, v40, v40
	v_fmac_f32_e32 v110, v41, v41
	v_fmac_f32_e32 v110, v42, v42
	v_fmac_f32_e32 v110, v43, v43
	v_fmac_f32_e32 v110, v44, v44
	v_fmac_f32_e32 v110, v45, v45
	v_fmac_f32_e32 v110, v46, v46
	v_fmac_f32_e32 v110, v47, v47
	v_fmac_f32_e32 v110, v48, v48
	v_fmac_f32_e32 v110, v49, v49
	v_fmac_f32_e32 v110, v50, v50
	v_fmac_f32_e32 v110, v51, v51
	v_fmac_f32_e32 v110, v52, v52
	v_fmac_f32_e32 v110, v53, v53
	v_fmac_f32_e32 v110, v54, v54
	v_fmac_f32_e32 v110, v55, v55
	global_store_dwordx2 v105, v[16:17], s[12:13]
	global_store_dwordx2 v105, v[18:19], s[12:13] offset:512
	global_store_dwordx2 v105, v[20:21], s[12:13] offset:1024
	global_store_dwordx2 v105, v[22:23], s[12:13] offset:1536
	s_add_u32 s12, s12, 0x400000
	s_addc_u32 s13, s13, 0
	v_cvt_pk_bf16_f32 v24, v56, v57
	v_cvt_pk_bf16_f32 v25, v58, v59
	v_cvt_pk_bf16_f32 v26, v60, v61
	v_cvt_pk_bf16_f32 v27, v62, v63
	v_cvt_pk_bf16_f32 v28, v64, v65
	v_cvt_pk_bf16_f32 v29, v66, v67
	v_cvt_pk_bf16_f32 v30, v68, v69
	v_cvt_pk_bf16_f32 v31, v70, v71
	v_mul_f32_e32 v111, v56, v56
	v_fmac_f32_e32 v111, v57, v57
	v_fmac_f32_e32 v111, v58, v58
	v_fmac_f32_e32 v111, v59, v59
	v_fmac_f32_e32 v111, v60, v60
	v_fmac_f32_e32 v111, v61, v61
	v_fmac_f32_e32 v111, v62, v62
	v_fmac_f32_e32 v111, v63, v63
	v_fmac_f32_e32 v111, v64, v64
	v_fmac_f32_e32 v111, v65, v65
	v_fmac_f32_e32 v111, v66, v66
	v_fmac_f32_e32 v111, v67, v67
	v_fmac_f32_e32 v111, v68, v68
	v_fmac_f32_e32 v111, v69, v69
	v_fmac_f32_e32 v111, v70, v70
	v_fmac_f32_e32 v111, v71, v71
	global_store_dwordx2 v105, v[24:25], s[12:13]
	global_store_dwordx2 v105, v[26:27], s[12:13] offset:512
	global_store_dwordx2 v105, v[28:29], s[12:13] offset:1024
	global_store_dwordx2 v105, v[30:31], s[12:13] offset:1536
	s_add_u32 s12, s12, 0x400000
	s_addc_u32 s13, s13, 0
	v_cvt_pk_bf16_f32 v16, v72, v73
	v_cvt_pk_bf16_f32 v17, v74, v75
	v_cvt_pk_bf16_f32 v18, v76, v77
	v_cvt_pk_bf16_f32 v19, v78, v79
	v_cvt_pk_bf16_f32 v20, v80, v81
	v_cvt_pk_bf16_f32 v21, v82, v83
	v_cvt_pk_bf16_f32 v22, v84, v85
	v_cvt_pk_bf16_f32 v23, v86, v87
	v_mul_f32_e32 v112, v72, v72
	v_fmac_f32_e32 v112, v73, v73
	v_fmac_f32_e32 v112, v74, v74
	v_fmac_f32_e32 v112, v75, v75
	v_fmac_f32_e32 v112, v76, v76
	v_fmac_f32_e32 v112, v77, v77
	v_fmac_f32_e32 v112, v78, v78
	v_fmac_f32_e32 v112, v79, v79
	v_fmac_f32_e32 v112, v80, v80
	v_fmac_f32_e32 v112, v81, v81
	v_fmac_f32_e32 v112, v82, v82
	v_fmac_f32_e32 v112, v83, v83
	v_fmac_f32_e32 v112, v84, v84
	v_fmac_f32_e32 v112, v85, v85
	v_fmac_f32_e32 v112, v86, v86
	v_fmac_f32_e32 v112, v87, v87
	global_store_dwordx2 v105, v[16:17], s[12:13]
	global_store_dwordx2 v105, v[18:19], s[12:13] offset:512
	global_store_dwordx2 v105, v[20:21], s[12:13] offset:1024
	global_store_dwordx2 v105, v[22:23], s[12:13] offset:1536
	s_add_u32 s12, s12, 0x400000
	s_addc_u32 s13, s13, 0
	v_cvt_pk_bf16_f32 v24, v88, v89
	v_cvt_pk_bf16_f32 v25, v90, v91
	v_cvt_pk_bf16_f32 v26, v92, v93
	v_cvt_pk_bf16_f32 v27, v94, v95
	v_cvt_pk_bf16_f32 v28, v96, v97
	v_cvt_pk_bf16_f32 v29, v98, v99
	v_cvt_pk_bf16_f32 v30, v100, v101
	v_cvt_pk_bf16_f32 v31, v102, v103
	v_mul_f32_e32 v113, v88, v88
; __device__ __forceinline__ unsigned pk2(float lo, float hi) { return f2bf(lo) | (f2bf(hi) << 16); }
; #define lane (hw_lane())
; __device__ __forceinline__ float wave_sum(float v) {
; #pragma unroll
;     for (int o = 1; o < 64; o <<= 1) v += __shfl_xor(v, o);
;     return v;
; __device__ __forceinline__ void prologue(const Args& a, LAS unsigned char* lds, int gw, int NGW, int lane, int wave) {
;     ...
;         for (int m = gw; m < M + MMEM; m += NGW) {
;             const bool is_mem = m >= M; const int row = is_mem ? m - M : m;
;             f32x4 v[4]; float s = 0.f;
; #pragma unroll
;             for (int j = 0; j < 4; ++j) v[j] = nv[j];
;             { const int mn = m + NGW; if (mn < M + MMEM) { const f32x4* xr = (const f32x4*)((mn >= M ? a.in[I_MEM] + (size_t)(mn - M) * D : a.in[I_X] + (size_t)mn * D)) + lane;
; #pragma unroll
;                 for (int j = 0; j < 4; ++j) nv[j] = __builtin_nontemporal_load(xr + 64 * j); } }
; #pragma unroll
;             for (int j = 0; j < 4; ++j) s += (v[j].x * v[j].x + v[j].y * v[j].y) + (v[j].z * v[j].z + v[j].w * v[j].w);
;             s = wave_sum(s);
;             float sc = 1.f;
;             if (is_mem) sc = __builtin_amdgcn_rsqf(s * (1.0f / D) + EPS);
;             else if (lane < 16) slots[(size_t)row * 16 + lane] = lane == 0 ? s : 0.f;
;             v2u* o8 = (v2u*)((is_mem ? MEMN : HB) + (size_t)row * D) + lane;
; #pragma unroll
;             for (int j = 0; j < 4; ++j) { v2u o; o.x = pk2(v[j].x * sc, v[j].y * sc); o.y = pk2(v[j].z * sc, v[j].w * sc); o8[64 * j] = o; }
	v_fmac_f32_e32 v113, v89, v89
	v_fmac_f32_e32 v113, v90, v90
	v_fmac_f32_e32 v113, v91, v91
	v_fmac_f32_e32 v113, v92, v92
	v_fmac_f32_e32 v113, v93, v93
	v_fmac_f32_e32 v113, v94, v94
	v_fmac_f32_e32 v113, v95, v95
	v_fmac_f32_e32 v113, v96, v96
	v_fmac_f32_e32 v113, v97, v97
	v_fmac_f32_e32 v113, v98, v98
	v_fmac_f32_e32 v113, v99, v99
	v_fmac_f32_e32 v113, v100, v100
	v_fmac_f32_e32 v113, v101, v101
	v_fmac_f32_e32 v113, v102, v102
	v_fmac_f32_e32 v113, v103, v103
	global_store_dwordx2 v105, v[24:25], s[12:13]
	global_store_dwordx2 v105, v[26:27], s[12:13] offset:512
	global_store_dwordx2 v105, v[28:29], s[12:13] offset:1024
	global_store_dwordx2 v105, v[30:31], s[12:13] offset:1536
	s_add_u32 s12, s12, 0x400000
	s_addc_u32 s13, s13, 0
	v_add_f32_dpp v114, v110, v110 row_ror:8 row_mask:0xf bank_mask:0xf
	v_add_f32_dpp v115, v111, v111 row_ror:8 row_mask:0xf bank_mask:0xf
	v_add_f32_dpp v116, v112, v112 row_ror:8 row_mask:0xf bank_mask:0xf
	v_add_f32_dpp v117, v113, v113 row_ror:8 row_mask:0xf bank_mask:0xf
	v_add_f32_dpp v110, v114, v114 row_ror:4 row_mask:0xf bank_mask:0xf
	v_add_f32_dpp v111, v115, v115 row_ror:4 row_mask:0xf bank_mask:0xf
	v_add_f32_dpp v112, v116, v116 row_ror:4 row_mask:0xf bank_mask:0xf
	v_add_f32_dpp v113, v117, v117 row_ror:4 row_mask:0xf bank_mask:0xf
	v_add_f32_dpp v114, v110, v110 row_ror:2 row_mask:0xf bank_mask:0xf
	v_add_f32_dpp v115, v111, v111 row_ror:2 row_mask:0xf bank_mask:0xf
	v_add_f32_dpp v116, v112, v112 row_ror:2 row_mask:0xf bank_mask:0xf
	v_add_f32_dpp v117, v113, v113 row_ror:2 row_mask:0xf bank_mask:0xf
	v_add_f32_dpp v110, v114, v114 row_ror:1 row_mask:0xf bank_mask:0xf
	v_add_f32_dpp v111, v115, v115 row_ror:1 row_mask:0xf bank_mask:0xf
	v_add_f32_dpp v112, v116, v116 row_ror:1 row_mask:0xf bank_mask:0xf
	v_add_f32_dpp v113, v117, v117 row_ror:1 row_mask:0xf bank_mask:0xf
	ds_bpermute_b32 v114, v107, v110
	ds_bpermute_b32 v115, v107, v111
	ds_bpermute_b32 v116, v107, v112
	ds_bpermute_b32 v117, v107, v113
	s_waitcnt lgkmcnt(0)
	v_add_f32_e32 v110, v110, v114
	v_add_f32_e32 v111, v111, v115
	v_add_f32_e32 v112, v112, v116
	v_add_f32_e32 v113, v113, v117
	ds_bpermute_b32 v114, v108, v110
	ds_bpermute_b32 v115, v108, v111
	ds_bpermute_b32 v116, v108, v112
	ds_bpermute_b32 v117, v108, v113
	s_waitcnt lgkmcnt(0)
	v_add_f32_e32 v110, v110, v114
	v_add_f32_e32 v111, v111, v115
	v_add_f32_e32 v112, v112, v116
	v_add_f32_e32 v113, v113, v117
	v_cndmask_b32_e64 v110, v109, v110, s[16:17]
	v_cndmask_b32_e64 v111, v109, v111, s[16:17]
	v_cndmask_b32_e64 v112, v109, v112, s[16:17]
	v_cndmask_b32_e64 v113, v109, v113, s[16:17]
	s_and_saveexec_b64 s[18:19], s[4:5]
	global_store_dword v106, v110, s[14:15]
	s_add_u32 s14, s14, 0x20000
	s_addc_u32 s15, s15, 0
	global_store_dword v106, v111, s[14:15]
	s_add_u32 s14, s14, 0x20000
	s_addc_u32 s15, s15, 0
	global_store_dword v106, v112, s[14:15]
	s_add_u32 s14, s14, 0x20000
	s_addc_u32 s15, s15, 0
	global_store_dword v106, v113, s[14:15]
	s_add_u32 s14, s14, 0x20000
	s_addc_u32 s15, s15, 0
	s_mov_b64 exec, s[18:19]
	global_load_dwordx4 v[40:43], v104, s[10:11] nt
	global_load_dwordx4 v[44:47], v104, s[10:11] offset:1024 nt
	global_load_dwordx4 v[48:51], v104, s[10:11] offset:2048 nt
	global_load_dwordx4 v[52:55], v104, s[10:11] offset:3072 nt
	s_add_u32 s10, s10, 0x800000
	s_addc_u32 s11, s11, 0
	global_load_dwordx4 v[56:59], v104, s[10:11] nt
	global_load_dwordx4 v[60:63], v104, s[10:11] offset:1024 nt
	global_load_dwordx4 v[64:67], v104, s[10:11] offset:2048 nt
	global_load_dwordx4 v[68:71], v104, s[10:11] offset:3072 nt
	s_add_u32 s10, s10, 0x800000
	s_addc_u32 s11, s11, 0
	global_load_dwordx4 v[72:75], v104, s[10:11] nt
	global_load_dwordx4 v[76:79], v104, s[10:11] offset:1024 nt
	global_load_dwordx4 v[80:83], v104, s[10:11] offset:2048 nt
	global_load_dwordx4 v[84:87], v104, s[10:11] offset:3072 nt
	s_add_u32 s10, s10, 0x800000
	s_addc_u32 s11, s11, 0
	global_load_dwordx4 v[88:91], v104, s[10:11] nt
	global_load_dwordx4 v[92:95], v104, s[10:11] offset:1024 nt
	global_load_dwordx4 v[96:99], v104, s[10:11] offset:2048 nt
	global_load_dwordx4 v[100:103], v104, s[10:11] offset:3072 nt
	s_add_u32 s10, s10, 0x800000
	s_addc_u32 s11, s11, 0
	s_waitcnt vmcnt(36)
	v_cvt_pk_bf16_f32 v16, v176, v177
	v_cvt_pk_bf16_f32 v17, v178, v179
	v_cvt_pk_bf16_f32 v18, v180, v181
	v_cvt_pk_bf16_f32 v19, v182, v183
	v_cvt_pk_bf16_f32 v20, v184, v185
	v_cvt_pk_bf16_f32 v21, v186, v187
	v_cvt_pk_bf16_f32 v22, v188, v189
	v_cvt_pk_bf16_f32 v23, v190, v191
	v_mul_f32_e32 v110, v176, v176
	v_fmac_f32_e32 v110, v177, v177
	v_fmac_f32_e32 v110, v178, v178
	v_fmac_f32_e32 v110, v179, v179
	v_fmac_f32_e32 v110, v180, v180
	v_fmac_f32_e32 v110, v181, v181
	v_fmac_f32_e32 v110, v182, v182
	v_fmac_f32_e32 v110, v183, v183
	v_fmac_f32_e32 v110, v184, v184
	v_fmac_f32_e32 v110, v185, v185
	v_fmac_f32_e32 v110, v186, v186
	v_fmac_f32_e32 v110, v187, v187
	v_fmac_f32_e32 v110, v188, v188
	v_fmac_f32_e32 v110, v189, v189
	v_fmac_f32_e32 v110, v190, v190
	v_fmac_f32_e32 v110, v191, v191
	global_store_dwordx2 v105, v[16:17], s[12:13]
	global_store_dwordx2 v105, v[18:19], s[12:13] offset:512
	global_store_dwordx2 v105, v[20:21], s[12:13] offset:1024
	global_store_dwordx2 v105, v[22:23], s[12:13] offset:1536
	s_add_u32 s12, s12, 0x400000
	s_addc_u32 s13, s13, 0
	v_cvt_pk_bf16_f32 v24, v192, v193
	v_cvt_pk_bf16_f32 v25, v194, v195
	v_cvt_pk_bf16_f32 v26, v196, v197
	v_cvt_pk_bf16_f32 v27, v198, v199
	v_cvt_pk_bf16_f32 v28, v200, v201
	v_cvt_pk_bf16_f32 v29, v202, v203
	v_cvt_pk_bf16_f32 v30, v204, v205
	v_cvt_pk_bf16_f32 v31, v206, v207
	v_mul_f32_e32 v111, v192, v192
	v_fmac_f32_e32 v111, v193, v193
; __device__ __forceinline__ unsigned pk2(float lo, float hi) { return f2bf(lo) | (f2bf(hi) << 16); }
; #define lane (hw_lane())
; __device__ __forceinline__ float wave_sum(float v) {
; #pragma unroll
;     for (int o = 1; o < 64; o <<= 1) v += __shfl_xor(v, o);
;     return v;
; __device__ __forceinline__ void prologue(const Args& a, LAS unsigned char* lds, int gw, int NGW, int lane, int wave) {
;     ...
;         for (int m = gw; m < M + MMEM; m += NGW) {
;             const bool is_mem = m >= M; const int row = is_mem ? m - M : m;
;             f32x4 v[4]; float s = 0.f;
; #pragma unroll
;             for (int j = 0; j < 4; ++j) v[j] = nv[j];
;             { const int mn = m + NGW; if (mn < M + MMEM) { const f32x4* xr = (const f32x4*)((mn >= M ? a.in[I_MEM] + (size_t)(mn - M) * D : a.in[I_X] + (size_t)mn * D)) + lane;
; #pragma unroll
;                 for (int j = 0; j < 4; ++j) nv[j] = __builtin_nontemporal_load(xr + 64 * j); } }
; #pragma unroll
;             for (int j = 0; j < 4; ++j) s += (v[j].x * v[j].x + v[j].y * v[j].y) + (v[j].z * v[j].z + v[j].w * v[j].w);
;             s = wave_sum(s);
;             float sc = 1.f;
;             if (is_mem) sc = __builtin_amdgcn_rsqf(s * (1.0f / D) + EPS);
;             else if (lane < 16) slots[(size_t)row * 16 + lane] = lane == 0 ? s : 0.f;
;             v2u* o8 = (v2u*)((is_mem ? MEMN : HB) + (size_t)row * D) + lane;
; #pragma unroll
;             for (int j = 0; j < 4; ++j) { v2u o; o.x = pk2(v[j].x * sc, v[j].y * sc); o.y = pk2(v[j].z * sc, v[j].w * sc); o8[64 * j] = o; }
	v_fmac_f32_e32 v111, v194, v194
	v_fmac_f32_e32 v111, v195, v195
	v_fmac_f32_e32 v111, v196, v196
	v_fmac_f32_e32 v111, v197, v197
	v_fmac_f32_e32 v111, v198, v198
	v_fmac_f32_e32 v111, v199, v199
	v_fmac_f32_e32 v111, v200, v200
	v_fmac_f32_e32 v111, v201, v201
	v_fmac_f32_e32 v111, v202, v202
	v_fmac_f32_e32 v111, v203, v203
	v_fmac_f32_e32 v111, v204, v204
	v_fmac_f32_e32 v111, v205, v205
	v_fmac_f32_e32 v111, v206, v206
	v_fmac_f32_e32 v111, v207, v207
	global_store_dwordx2 v105, v[24:25], s[12:13]
	global_store_dwordx2 v105, v[26:27], s[12:13] offset:512
	global_store_dwordx2 v105, v[28:29], s[12:13] offset:1024
	global_store_dwordx2 v105, v[30:31], s[12:13] offset:1536
	s_add_u32 s12, s12, 0x400000
	s_addc_u32 s13, s13, 0
	v_cvt_pk_bf16_f32 v16, v208, v209
	v_cvt_pk_bf16_f32 v17, v210, v211
	v_cvt_pk_bf16_f32 v18, v212, v213
	v_cvt_pk_bf16_f32 v19, v214, v215
	v_cvt_pk_bf16_f32 v20, v216, v217
	v_cvt_pk_bf16_f32 v21, v218, v219
	v_cvt_pk_bf16_f32 v22, v220, v221
	v_cvt_pk_bf16_f32 v23, v222, v223
	v_mul_f32_e32 v112, v208, v208
	v_fmac_f32_e32 v112, v209, v209
	v_fmac_f32_e32 v112, v210, v210
	v_fmac_f32_e32 v112, v211, v211
	v_fmac_f32_e32 v112, v212, v212
	v_fmac_f32_e32 v112, v213, v213
	v_fmac_f32_e32 v112, v214, v214
	v_fmac_f32_e32 v112, v215, v215
	v_fmac_f32_e32 v112, v216, v216
	v_fmac_f32_e32 v112, v217, v217
	v_fmac_f32_e32 v112, v218, v218
	v_fmac_f32_e32 v112, v219, v219
	v_fmac_f32_e32 v112, v220, v220
	v_fmac_f32_e32 v112, v221, v221
	v_fmac_f32_e32 v112, v222, v222
	v_fmac_f32_e32 v112, v223, v223
	global_store_dwordx2 v105, v[16:17], s[12:13]
	global_store_dwordx2 v105, v[18:19], s[12:13] offset:512
	global_store_dwordx2 v105, v[20:21], s[12:13] offset:1024
	global_store_dwordx2 v105, v[22:23], s[12:13] offset:1536
	s_add_u32 s12, s12, 0x400000
	s_addc_u32 s13, s13, 0
	v_cvt_pk_bf16_f32 v24, v224, v225
	v_cvt_pk_bf16_f32 v25, v226, v227
	v_cvt_pk_bf16_f32 v26, v228, v229
	v_cvt_pk_bf16_f32 v27, v230, v231
	v_cvt_pk_bf16_f32 v28, v232, v233
	v_cvt_pk_bf16_f32 v29, v234, v235
	v_cvt_pk_bf16_f32 v30, v236, v237
	v_cvt_pk_bf16_f32 v31, v238, v239
	v_mul_f32_e32 v113, v224, v224
	v_fmac_f32_e32 v113, v225, v225
	v_fmac_f32_e32 v113, v226, v226
	v_fmac_f32_e32 v113, v227, v227
	v_fmac_f32_e32 v113, v228, v228
	v_fmac_f32_e32 v113, v229, v229
	v_fmac_f32_e32 v113, v230, v230
	v_fmac_f32_e32 v113, v231, v231
	v_fmac_f32_e32 v113, v232, v232
	v_fmac_f32_e32 v113, v233, v233
	v_fmac_f32_e32 v113, v234, v234
	v_fmac_f32_e32 v113, v235, v235
	v_fmac_f32_e32 v113, v236, v236
	v_fmac_f32_e32 v113, v237, v237
	v_fmac_f32_e32 v113, v238, v238
	v_fmac_f32_e32 v113, v239, v239
	global_store_dwordx2 v105, v[24:25], s[12:13]
	global_store_dwordx2 v105, v[26:27], s[12:13] offset:512
	global_store_dwordx2 v105, v[28:29], s[12:13] offset:1024
	global_store_dwordx2 v105, v[30:31], s[12:13] offset:1536
	s_add_u32 s12, s12, 0x400000
	s_addc_u32 s13, s13, 0
	v_add_f32_dpp v114, v110, v110 row_ror:8 row_mask:0xf bank_mask:0xf
	v_add_f32_dpp v115, v111, v111 row_ror:8 row_mask:0xf bank_mask:0xf
	v_add_f32_dpp v116, v112, v112 row_ror:8 row_mask:0xf bank_mask:0xf
	v_add_f32_dpp v117, v113, v113 row_ror:8 row_mask:0xf bank_mask:0xf
	v_add_f32_dpp v110, v114, v114 row_ror:4 row_mask:0xf bank_mask:0xf
	v_add_f32_dpp v111, v115, v115 row_ror:4 row_mask:0xf bank_mask:0xf
	v_add_f32_dpp v112, v116, v116 row_ror:4 row_mask:0xf bank_mask:0xf
	v_add_f32_dpp v113, v117, v117 row_ror:4 row_mask:0xf bank_mask:0xf
	v_add_f32_dpp v114, v110, v110 row_ror:2 row_mask:0xf bank_mask:0xf
	v_add_f32_dpp v115, v111, v111 row_ror:2 row_mask:0xf bank_mask:0xf
	v_add_f32_dpp v116, v112, v112 row_ror:2 row_mask:0xf bank_mask:0xf
	v_add_f32_dpp v117, v113, v113 row_ror:2 row_mask:0xf bank_mask:0xf
	v_add_f32_dpp v110, v114, v114 row_ror:1 row_mask:0xf bank_mask:0xf
	v_add_f32_dpp v111, v115, v115 row_ror:1 row_mask:0xf bank_mask:0xf
	v_add_f32_dpp v112, v116, v116 row_ror:1 row_mask:0xf bank_mask:0xf
	v_add_f32_dpp v113, v117, v117 row_ror:1 row_mask:0xf bank_mask:0xf
	ds_bpermute_b32 v114, v107, v110
	ds_bpermute_b32 v115, v107, v111
	ds_bpermute_b32 v116, v107, v112
	ds_bpermute_b32 v117, v107, v113
	s_waitcnt lgkmcnt(0)
	v_add_f32_e32 v110, v110, v114
	v_add_f32_e32 v111, v111, v115
	v_add_f32_e32 v112, v112, v116
	v_add_f32_e32 v113, v113, v117
	ds_bpermute_b32 v114, v108, v110
	ds_bpermute_b32 v115, v108, v111
	ds_bpermute_b32 v116, v108, v112
	ds_bpermute_b32 v117, v108, v113
	s_waitcnt lgkmcnt(0)
	v_add_f32_e32 v110, v110, v114
	v_add_f32_e32 v111, v111, v115
	v_add_f32_e32 v112, v112, v116
	v_add_f32_e32 v113, v113, v117
	v_cndmask_b32_e64 v110, v109, v110, s[16:17]
	v_cndmask_b32_e64 v111, v109, v111, s[16:17]
	v_cndmask_b32_e64 v112, v109, v112, s[16:17]
	v_cndmask_b32_e64 v113, v109, v113, s[16:17]
	s_and_saveexec_b64 s[18:19], s[4:5]
	global_store_dword v106, v110, s[14:15]
	s_add_u32 s14, s14, 0x20000
	s_addc_u32 s15, s15, 0
	global_store_dword v106, v111, s[14:15]
	s_add_u32 s14, s14, 0x20000
	s_addc_u32 s15, s15, 0
	global_store_dword v106, v112, s[14:15]
	s_add_u32 s14, s14, 0x20000
	s_addc_u32 s15, s15, 0
	global_store_dword v106, v113, s[14:15]
	s_add_u32 s14, s14, 0x20000
	s_addc_u32 s15, s15, 0
	s_mov_b64 exec, s[18:19]
	global_load_dwordx4 v[176:179], v104, s[10:11] nt
	global_load_dwordx4 v[180:183], v104, s[10:11] offset:1024 nt
	global_load_dwordx4 v[184:187], v104, s[10:11] offset:2048 nt
	global_load_dwordx4 v[188:191], v104, s[10:11] offset:3072 nt
	s_add_u32 s10, s10, 0x800000
	s_addc_u32 s11, s11, 0
	global_load_dwordx4 v[192:195], v104, s[10:11] nt
	global_load_dwordx4 v[196:199], v104, s[10:11] offset:1024 nt
	global_load_dwordx4 v[200:203], v104, s[10:11] offset:2048 nt
	global_load_dwordx4 v[204:207], v104, s[10:11] offset:3072 nt
	s_add_u32 s10, s10, 0x800000
	s_addc_u32 s11, s11, 0
	global_load_dwordx4 v[208:211], v104, s[10:11] nt
	global_load_dwordx4 v[212:215], v104, s[10:11] offset:1024 nt
	global_load_dwordx4 v[216:219], v104, s[10:11] offset:2048 nt
	global_load_dwordx4 v[220:223], v104, s[10:11] offset:3072 nt
	s_add_u32 s10, s10, 0x800000
	s_addc_u32 s11, s11, 0
	global_load_dwordx4 v[224:227], v104, s[10:11] nt
	global_load_dwordx4 v[228:231], v104, s[10:11] offset:1024 nt
	global_load_dwordx4 v[232:235], v104, s[10:11] offset:2048 nt
	global_load_dwordx4 v[236:239], v104, s[10:11] offset:3072 nt
	s_add_u32 s10, s10, 0x800000
	s_addc_u32 s11, s11, 0
	s_waitcnt vmcnt(36)
; __device__ __forceinline__ unsigned pk2(float lo, float hi) { return f2bf(lo) | (f2bf(hi) << 16); }
; #define lane (hw_lane())
; __device__ __forceinline__ void prologue(const Args& a, LAS unsigned char* lds, int gw, int NGW, int lane, int wave) {
;     ...
;         for (int m = gw; m < M + MMEM; m += NGW) {
;             const bool is_mem = m >= M; const int row = is_mem ? m - M : m;
;             f32x4 v[4]; float s = 0.f;
; #pragma unroll
;             for (int j = 0; j < 4; ++j) v[j] = nv[j];
;             { const int mn = m + NGW; if (mn < M + MMEM) { const f32x4* xr = (const f32x4*)((mn >= M ? a.in[I_MEM] + (size_t)(mn - M) * D : a.in[I_X] + (size_t)mn * D)) + lane;
; #pragma unroll
;                 for (int j = 0; j < 4; ++j) nv[j] = __builtin_nontemporal_load(xr + 64 * j); } }
; #pragma unroll
;             for (int j = 0; j < 4; ++j) s += (v[j].x * v[j].x + v[j].y * v[j].y) + (v[j].z * v[j].z + v[j].w * v[j].w);
;             s = wave_sum(s);
;             float sc = 1.f;
;             if (is_mem) sc = __builtin_amdgcn_rsqf(s * (1.0f / D) + EPS);
;             else if (lane < 16) slots[(size_t)row * 16 + lane] = lane == 0 ? s : 0.f;
;             v2u* o8 = (v2u*)((is_mem ? MEMN : HB) + (size_t)row * D) + lane;
; #pragma unroll
;             for (int j = 0; j < 4; ++j) { v2u o; o.x = pk2(v[j].x * sc, v[j].y * sc); o.y = pk2(v[j].z * sc, v[j].w * sc); o8[64 * j] = o; }
	v_cvt_pk_bf16_f32 v16, v40, v41
	v_cvt_pk_bf16_f32 v17, v42, v43
	v_cvt_pk_bf16_f32 v18, v44, v45
	v_cvt_pk_bf16_f32 v19, v46, v47
	v_cvt_pk_bf16_f32 v20, v48, v49
	v_cvt_pk_bf16_f32 v21, v50, v51
	v_cvt_pk_bf16_f32 v22, v52, v53
	v_cvt_pk_bf16_f32 v23, v54, v55
	v_mul_f32_e32 v110, v40, v40
	v_fmac_f32_e32 v110, v41, v41
	v_fmac_f32_e32 v110, v42, v42
	v_fmac_f32_e32 v110, v43, v43
	v_fmac_f32_e32 v110, v44, v44
	v_fmac_f32_e32 v110, v45, v45
	v_fmac_f32_e32 v110, v46, v46
	v_fmac_f32_e32 v110, v47, v47
	v_fmac_f32_e32 v110, v48, v48
	v_fmac_f32_e32 v110, v49, v49
	v_fmac_f32_e32 v110, v50, v50
	v_fmac_f32_e32 v110, v51, v51
	v_fmac_f32_e32 v110, v52, v52
	v_fmac_f32_e32 v110, v53, v53
	v_fmac_f32_e32 v110, v54, v54
	v_fmac_f32_e32 v110, v55, v55
	global_store_dwordx2 v105, v[16:17], s[12:13]
	global_store_dwordx2 v105, v[18:19], s[12:13] offset:512
	global_store_dwordx2 v105, v[20:21], s[12:13] offset:1024
	global_store_dwordx2 v105, v[22:23], s[12:13] offset:1536
	s_add_u32 s12, s12, 0x400000
	s_addc_u32 s13, s13, 0
	v_cvt_pk_bf16_f32 v24, v56, v57
	v_cvt_pk_bf16_f32 v25, v58, v59
	v_cvt_pk_bf16_f32 v26, v60, v61
	v_cvt_pk_bf16_f32 v27, v62, v63
	v_cvt_pk_bf16_f32 v28, v64, v65
	v_cvt_pk_bf16_f32 v29, v66, v67
	v_cvt_pk_bf16_f32 v30, v68, v69
	v_cvt_pk_bf16_f32 v31, v70, v71
	v_mul_f32_e32 v111, v56, v56
	v_fmac_f32_e32 v111, v57, v57
	v_fmac_f32_e32 v111, v58, v58
	v_fmac_f32_e32 v111, v59, v59
	v_fmac_f32_e32 v111, v60, v60
	v_fmac_f32_e32 v111, v61, v61
	v_fmac_f32_e32 v111, v62, v62
	v_fmac_f32_e32 v111, v63, v63
	v_fmac_f32_e32 v111, v64, v64
	v_fmac_f32_e32 v111, v65, v65
	v_fmac_f32_e32 v111, v66, v66
	v_fmac_f32_e32 v111, v67, v67
	v_fmac_f32_e32 v111, v68, v68
	v_fmac_f32_e32 v111, v69, v69
	v_fmac_f32_e32 v111, v70, v70
	v_fmac_f32_e32 v111, v71, v71
	global_store_dwordx2 v105, v[24:25], s[12:13]
	global_store_dwordx2 v105, v[26:27], s[12:13] offset:512
	global_store_dwordx2 v105, v[28:29], s[12:13] offset:1024
	global_store_dwordx2 v105, v[30:31], s[12:13] offset:1536
	s_add_u32 s12, s12, 0x400000
	s_addc_u32 s13, s13, 0
	v_cvt_pk_bf16_f32 v16, v72, v73
	v_cvt_pk_bf16_f32 v17, v74, v75
	v_cvt_pk_bf16_f32 v18, v76, v77
	v_cvt_pk_bf16_f32 v19, v78, v79
	v_cvt_pk_bf16_f32 v20, v80, v81
	v_cvt_pk_bf16_f32 v21, v82, v83
	v_cvt_pk_bf16_f32 v22, v84, v85
	v_cvt_pk_bf16_f32 v23, v86, v87
	v_mul_f32_e32 v112, v72, v72
	v_fmac_f32_e32 v112, v73, v73
	v_fmac_f32_e32 v112, v74, v74
	v_fmac_f32_e32 v112, v75, v75
	v_fmac_f32_e32 v112, v76, v76
	v_fmac_f32_e32 v112, v77, v77
	v_fmac_f32_e32 v112, v78, v78
	v_fmac_f32_e32 v112, v79, v79
	v_fmac_f32_e32 v112, v80, v80
	v_fmac_f32_e32 v112, v81, v81
	v_fmac_f32_e32 v112, v82, v82
	v_fmac_f32_e32 v112, v83, v83
	v_fmac_f32_e32 v112, v84, v84
	v_fmac_f32_e32 v112, v85, v85
	v_fmac_f32_e32 v112, v86, v86
	v_fmac_f32_e32 v112, v87, v87
	global_store_dwordx2 v105, v[16:17], s[12:13]
	global_store_dwordx2 v105, v[18:19], s[12:13] offset:512
	global_store_dwordx2 v105, v[20:21], s[12:13] offset:1024
	global_store_dwordx2 v105, v[22:23], s[12:13] offset:1536
	s_add_u32 s12, s12, 0x400000
	s_addc_u32 s13, s13, 0
	v_cvt_pk_bf16_f32 v24, v88, v89
	v_cvt_pk_bf16_f32 v25, v90, v91
	v_cvt_pk_bf16_f32 v26, v92, v93
	v_cvt_pk_bf16_f32 v27, v94, v95
	v_cvt_pk_bf16_f32 v28, v96, v97
	v_cvt_pk_bf16_f32 v29, v98, v99
	v_cvt_pk_bf16_f32 v30, v100, v101
	v_cvt_pk_bf16_f32 v31, v102, v103
	v_mul_f32_e32 v113, v88, v88
	v_fmac_f32_e32 v113, v89, v89
	v_fmac_f32_e32 v113, v90, v90
	v_fmac_f32_e32 v113, v91, v91
	v_fmac_f32_e32 v113, v92, v92
	v_fmac_f32_e32 v113, v93, v93
	v_fmac_f32_e32 v113, v94, v94
	v_fmac_f32_e32 v113, v95, v95
	v_fmac_f32_e32 v113, v96, v96
	v_fmac_f32_e32 v113, v97, v97
	v_fmac_f32_e32 v113, v98, v98
	v_fmac_f32_e32 v113, v99, v99
	v_fmac_f32_e32 v113, v100, v100
	v_fmac_f32_e32 v113, v101, v101
	v_fmac_f32_e32 v113, v102, v102
	v_fmac_f32_e32 v113, v103, v103
	global_store_dwordx2 v105, v[24:25], s[12:13]
	global_store_dwordx2 v105, v[26:27], s[12:13] offset:512
	global_store_dwordx2 v105, v[28:29], s[12:13] offset:1024
	global_store_dwordx2 v105, v[30:31], s[12:13] offset:1536
	s_add_u32 s12, s12, 0x400000
	s_addc_u32 s13, s13, 0
	v_add_f32_dpp v114, v110, v110 row_ror:8 row_mask:0xf bank_mask:0xf
	v_add_f32_dpp v115, v111, v111 row_ror:8 row_mask:0xf bank_mask:0xf
	v_add_f32_dpp v116, v112, v112 row_ror:8 row_mask:0xf bank_mask:0xf
	v_add_f32_dpp v117, v113, v113 row_ror:8 row_mask:0xf bank_mask:0xf
	v_add_f32_dpp v110, v114, v114 row_ror:4 row_mask:0xf bank_mask:0xf
	v_add_f32_dpp v111, v115, v115 row_ror:4 row_mask:0xf bank_mask:0xf
	v_add_f32_dpp v112, v116, v116 row_ror:4 row_mask:0xf bank_mask:0xf
	v_add_f32_dpp v113, v117, v117 row_ror:4 row_mask:0xf bank_mask:0xf
	v_add_f32_dpp v114, v110, v110 row_ror:2 row_mask:0xf bank_mask:0xf
	v_add_f32_dpp v115, v111, v111 row_ror:2 row_mask:0xf bank_mask:0xf
	v_add_f32_dpp v116, v112, v112 row_ror:2 row_mask:0xf bank_mask:0xf
	v_add_f32_dpp v117, v113, v113 row_ror:2 row_mask:0xf bank_mask:0xf
	v_add_f32_dpp v110, v114, v114 row_ror:1 row_mask:0xf bank_mask:0xf
	v_add_f32_dpp v111, v115, v115 row_ror:1 row_mask:0xf bank_mask:0xf
	v_add_f32_dpp v112, v116, v116 row_ror:1 row_mask:0xf bank_mask:0xf
	v_add_f32_dpp v113, v117, v117 row_ror:1 row_mask:0xf bank_mask:0xf
	ds_bpermute_b32 v114, v107, v110
	ds_bpermute_b32 v115, v107, v111
	ds_bpermute_b32 v116, v107, v112
	ds_bpermute_b32 v117, v107, v113
	s_waitcnt lgkmcnt(0)
	v_add_f32_e32 v110, v110, v114
	v_add_f32_e32 v111, v111, v115
	v_add_f32_e32 v112, v112, v116
	v_add_f32_e32 v113, v113, v117
	ds_bpermute_b32 v114, v108, v110
	ds_bpermute_b32 v115, v108, v111
	ds_bpermute_b32 v116, v108, v112
	ds_bpermute_b32 v117, v108, v113
	s_waitcnt lgkmcnt(0)
; __device__ __forceinline__ unsigned pk2(float lo, float hi) { return f2bf(lo) | (f2bf(hi) << 16); }
; #define lane (hw_lane())
; __device__ __forceinline__ void prologue(const Args& a, LAS unsigned char* lds, int gw, int NGW, int lane, int wave) {
;     ...
;         for (int m = gw; m < M + MMEM; m += NGW) {
;             const bool is_mem = m >= M; const int row = is_mem ? m - M : m;
;             f32x4 v[4]; float s = 0.f;
; #pragma unroll
;             for (int j = 0; j < 4; ++j) v[j] = nv[j];
;             { const int mn = m + NGW; if (mn < M + MMEM) { const f32x4* xr = (const f32x4*)((mn >= M ? a.in[I_MEM] + (size_t)(mn - M) * D : a.in[I_X] + (size_t)mn * D)) + lane;
; #pragma unroll
;                 for (int j = 0; j < 4; ++j) nv[j] = __builtin_nontemporal_load(xr + 64 * j); } }
; #pragma unroll
;             for (int j = 0; j < 4; ++j) s += (v[j].x * v[j].x + v[j].y * v[j].y) + (v[j].z * v[j].z + v[j].w * v[j].w);
;             s = wave_sum(s);
;             float sc = 1.f;
;             if (is_mem) sc = __builtin_amdgcn_rsqf(s * (1.0f / D) + EPS);
;             else if (lane < 16) slots[(size_t)row * 16 + lane] = lane == 0 ? s : 0.f;
;             v2u* o8 = (v2u*)((is_mem ? MEMN : HB) + (size_t)row * D) + lane;
; #pragma unroll
;             for (int j = 0; j < 4; ++j) { v2u o; o.x = pk2(v[j].x * sc, v[j].y * sc); o.y = pk2(v[j].z * sc, v[j].w * sc); o8[64 * j] = o; }
	v_add_f32_e32 v110, v110, v114
	v_add_f32_e32 v111, v111, v115
	v_add_f32_e32 v112, v112, v116
	v_add_f32_e32 v113, v113, v117
	v_cndmask_b32_e64 v110, v109, v110, s[16:17]
	v_cndmask_b32_e64 v111, v109, v111, s[16:17]
	v_cndmask_b32_e64 v112, v109, v112, s[16:17]
	v_cndmask_b32_e64 v113, v109, v113, s[16:17]
	s_and_saveexec_b64 s[18:19], s[4:5]
	global_store_dword v106, v110, s[14:15]
	s_add_u32 s14, s14, 0x20000
	s_addc_u32 s15, s15, 0
	global_store_dword v106, v111, s[14:15]
	s_add_u32 s14, s14, 0x20000
	s_addc_u32 s15, s15, 0
	global_store_dword v106, v112, s[14:15]
	s_add_u32 s14, s14, 0x20000
	s_addc_u32 s15, s15, 0
	global_store_dword v106, v113, s[14:15]
	s_add_u32 s14, s14, 0x20000
	s_addc_u32 s15, s15, 0
	s_mov_b64 exec, s[18:19]
	global_load_dwordx4 v[40:43], v104, s[10:11] nt
	global_load_dwordx4 v[44:47], v104, s[10:11] offset:1024 nt
	global_load_dwordx4 v[48:51], v104, s[10:11] offset:2048 nt
	global_load_dwordx4 v[52:55], v104, s[10:11] offset:3072 nt
	s_add_u32 s10, s10, 0x800000
	s_addc_u32 s11, s11, 0
	global_load_dwordx4 v[56:59], v104, s[10:11] nt
	global_load_dwordx4 v[60:63], v104, s[10:11] offset:1024 nt
	global_load_dwordx4 v[64:67], v104, s[10:11] offset:2048 nt
	global_load_dwordx4 v[68:71], v104, s[10:11] offset:3072 nt
	s_add_u32 s10, s10, 0x800000
	s_addc_u32 s11, s11, 0
	global_load_dwordx4 v[72:75], v104, s[10:11] nt
	global_load_dwordx4 v[76:79], v104, s[10:11] offset:1024 nt
	global_load_dwordx4 v[80:83], v104, s[10:11] offset:2048 nt
	global_load_dwordx4 v[84:87], v104, s[10:11] offset:3072 nt
	s_add_u32 s10, s10, 0x800000
	s_addc_u32 s11, s11, 0
	global_load_dwordx4 v[88:91], v104, s[10:11] nt
	global_load_dwordx4 v[92:95], v104, s[10:11] offset:1024 nt
	global_load_dwordx4 v[96:99], v104, s[10:11] offset:2048 nt
	global_load_dwordx4 v[100:103], v104, s[10:11] offset:3072 nt
	s_add_u32 s10, s10, 0x800000
	s_addc_u32 s11, s11, 0
	s_waitcnt vmcnt(36)
	v_cvt_pk_bf16_f32 v16, v176, v177
	v_cvt_pk_bf16_f32 v17, v178, v179
	v_cvt_pk_bf16_f32 v18, v180, v181
	v_cvt_pk_bf16_f32 v19, v182, v183
	v_cvt_pk_bf16_f32 v20, v184, v185
	v_cvt_pk_bf16_f32 v21, v186, v187
	v_cvt_pk_bf16_f32 v22, v188, v189
	v_cvt_pk_bf16_f32 v23, v190, v191
	v_mul_f32_e32 v110, v176, v176
	v_fmac_f32_e32 v110, v177, v177
	v_fmac_f32_e32 v110, v178, v178
	v_fmac_f32_e32 v110, v179, v179
	v_fmac_f32_e32 v110, v180, v180
	v_fmac_f32_e32 v110, v181, v181
	v_fmac_f32_e32 v110, v182, v182
	v_fmac_f32_e32 v110, v183, v183
	v_fmac_f32_e32 v110, v184, v184
	v_fmac_f32_e32 v110, v185, v185
	v_fmac_f32_e32 v110, v186, v186
	v_fmac_f32_e32 v110, v187, v187
	v_fmac_f32_e32 v110, v188, v188
	v_fmac_f32_e32 v110, v189, v189
	v_fmac_f32_e32 v110, v190, v190
	v_fmac_f32_e32 v110, v191, v191
	global_store_dwordx2 v105, v[16:17], s[12:13]
	global_store_dwordx2 v105, v[18:19], s[12:13] offset:512
	global_store_dwordx2 v105, v[20:21], s[12:13] offset:1024
	global_store_dwordx2 v105, v[22:23], s[12:13] offset:1536
	s_add_u32 s12, s12, 0x400000
	s_addc_u32 s13, s13, 0
	v_cvt_pk_bf16_f32 v24, v192, v193
	v_cvt_pk_bf16_f32 v25, v194, v195
	v_cvt_pk_bf16_f32 v26, v196, v197
	v_cvt_pk_bf16_f32 v27, v198, v199
	v_cvt_pk_bf16_f32 v28, v200, v201
	v_cvt_pk_bf16_f32 v29, v202, v203
	v_cvt_pk_bf16_f32 v30, v204, v205
	v_cvt_pk_bf16_f32 v31, v206, v207
	v_mul_f32_e32 v111, v192, v192
	v_fmac_f32_e32 v111, v193, v193
	v_fmac_f32_e32 v111, v194, v194
	v_fmac_f32_e32 v111, v195, v195
	v_fmac_f32_e32 v111, v196, v196
	v_fmac_f32_e32 v111, v197, v197
	v_fmac_f32_e32 v111, v198, v198
	v_fmac_f32_e32 v111, v199, v199
	v_fmac_f32_e32 v111, v200, v200
	v_fmac_f32_e32 v111, v201, v201
	v_fmac_f32_e32 v111, v202, v202
	v_fmac_f32_e32 v111, v203, v203
	v_fmac_f32_e32 v111, v204, v204
	v_fmac_f32_e32 v111, v205, v205
	v_fmac_f32_e32 v111, v206, v206
	v_fmac_f32_e32 v111, v207, v207
	global_store_dwordx2 v105, v[24:25], s[12:13]
	global_store_dwordx2 v105, v[26:27], s[12:13] offset:512
	global_store_dwordx2 v105, v[28:29], s[12:13] offset:1024
	global_store_dwordx2 v105, v[30:31], s[12:13] offset:1536
	s_add_u32 s12, s12, 0x400000
	s_addc_u32 s13, s13, 0
	v_cvt_pk_bf16_f32 v16, v208, v209
	v_cvt_pk_bf16_f32 v17, v210, v211
	v_cvt_pk_bf16_f32 v18, v212, v213
	v_cvt_pk_bf16_f32 v19, v214, v215
	v_cvt_pk_bf16_f32 v20, v216, v217
	v_cvt_pk_bf16_f32 v21, v218, v219
	v_cvt_pk_bf16_f32 v22, v220, v221
	v_cvt_pk_bf16_f32 v23, v222, v223
	v_mul_f32_e32 v112, v208, v208
	v_fmac_f32_e32 v112, v209, v209
	v_fmac_f32_e32 v112, v210, v210
	v_fmac_f32_e32 v112, v211, v211
	v_fmac_f32_e32 v112, v212, v212
	v_fmac_f32_e32 v112, v213, v213
	v_fmac_f32_e32 v112, v214, v214
	v_fmac_f32_e32 v112, v215, v215
	v_fmac_f32_e32 v112, v216, v216
	v_fmac_f32_e32 v112, v217, v217
	v_fmac_f32_e32 v112, v218, v218
	v_fmac_f32_e32 v112, v219, v219
	v_fmac_f32_e32 v112, v220, v220
	v_fmac_f32_e32 v112, v221, v221
	v_fmac_f32_e32 v112, v222, v222
	v_fmac_f32_e32 v112, v223, v223
	global_store_dwordx2 v105, v[16:17], s[12:13]
	global_store_dwordx2 v105, v[18:19], s[12:13] offset:512
	global_store_dwordx2 v105, v[20:21], s[12:13] offset:1024
	global_store_dwordx2 v105, v[22:23], s[12:13] offset:1536
	s_add_u32 s12, s12, 0x400000
	s_addc_u32 s13, s13, 0
	v_cvt_pk_bf16_f32 v24, v224, v225
	v_cvt_pk_bf16_f32 v25, v226, v227
	v_cvt_pk_bf16_f32 v26, v228, v229
	v_cvt_pk_bf16_f32 v27, v230, v231
	v_cvt_pk_bf16_f32 v28, v232, v233
	v_cvt_pk_bf16_f32 v29, v234, v235
	v_cvt_pk_bf16_f32 v30, v236, v237
	v_cvt_pk_bf16_f32 v31, v238, v239
	v_mul_f32_e32 v113, v224, v224
	v_fmac_f32_e32 v113, v225, v225
	v_fmac_f32_e32 v113, v226, v226
	v_fmac_f32_e32 v113, v227, v227
	v_fmac_f32_e32 v113, v228, v228
	v_fmac_f32_e32 v113, v229, v229
; __device__ __forceinline__ unsigned pk2(float lo, float hi) { return f2bf(lo) | (f2bf(hi) << 16); }
; #define lane (hw_lane())
; __device__ __forceinline__ void prologue(const Args& a, LAS unsigned char* lds, int gw, int NGW, int lane, int wave) {
;     ...
;         for (int m = gw; m < M + MMEM; m += NGW) {
;             const bool is_mem = m >= M; const int row = is_mem ? m - M : m;
;             f32x4 v[4]; float s = 0.f;
; #pragma unroll
;             for (int j = 0; j < 4; ++j) v[j] = nv[j];
;             { const int mn = m + NGW; if (mn < M + MMEM) { const f32x4* xr = (const f32x4*)((mn >= M ? a.in[I_MEM] + (size_t)(mn - M) * D : a.in[I_X] + (size_t)mn * D)) + lane;
; #pragma unroll
;                 for (int j = 0; j < 4; ++j) nv[j] = __builtin_nontemporal_load(xr + 64 * j); } }
; #pragma unroll
;             for (int j = 0; j < 4; ++j) s += (v[j].x * v[j].x + v[j].y * v[j].y) + (v[j].z * v[j].z + v[j].w * v[j].w);
;             s = wave_sum(s);
;             float sc = 1.f;
;             if (is_mem) sc = __builtin_amdgcn_rsqf(s * (1.0f / D) + EPS);
;             else if (lane < 16) slots[(size_t)row * 16 + lane] = lane == 0 ? s : 0.f;
;             v2u* o8 = (v2u*)((is_mem ? MEMN : HB) + (size_t)row * D) + lane;
; #pragma unroll
;             for (int j = 0; j < 4; ++j) { v2u o; o.x = pk2(v[j].x * sc, v[j].y * sc); o.y = pk2(v[j].z * sc, v[j].w * sc); o8[64 * j] = o; }
	v_fmac_f32_e32 v113, v230, v230
	v_fmac_f32_e32 v113, v231, v231
	v_fmac_f32_e32 v113, v232, v232
	v_fmac_f32_e32 v113, v233, v233
	v_fmac_f32_e32 v113, v234, v234
	v_fmac_f32_e32 v113, v235, v235
	v_fmac_f32_e32 v113, v236, v236
	v_fmac_f32_e32 v113, v237, v237
	v_fmac_f32_e32 v113, v238, v238
	v_fmac_f32_e32 v113, v239, v239
	global_store_dwordx2 v105, v[24:25], s[12:13]
	global_store_dwordx2 v105, v[26:27], s[12:13] offset:512
	global_store_dwordx2 v105, v[28:29], s[12:13] offset:1024
	global_store_dwordx2 v105, v[30:31], s[12:13] offset:1536
	s_add_u32 s12, s12, 0x400000
	s_addc_u32 s13, s13, 0
	v_add_f32_dpp v114, v110, v110 row_ror:8 row_mask:0xf bank_mask:0xf
	v_add_f32_dpp v115, v111, v111 row_ror:8 row_mask:0xf bank_mask:0xf
	v_add_f32_dpp v116, v112, v112 row_ror:8 row_mask:0xf bank_mask:0xf
	v_add_f32_dpp v117, v113, v113 row_ror:8 row_mask:0xf bank_mask:0xf
	v_add_f32_dpp v110, v114, v114 row_ror:4 row_mask:0xf bank_mask:0xf
	v_add_f32_dpp v111, v115, v115 row_ror:4 row_mask:0xf bank_mask:0xf
	v_add_f32_dpp v112, v116, v116 row_ror:4 row_mask:0xf bank_mask:0xf
	v_add_f32_dpp v113, v117, v117 row_ror:4 row_mask:0xf bank_mask:0xf
	v_add_f32_dpp v114, v110, v110 row_ror:2 row_mask:0xf bank_mask:0xf
	v_add_f32_dpp v115, v111, v111 row_ror:2 row_mask:0xf bank_mask:0xf
	v_add_f32_dpp v116, v112, v112 row_ror:2 row_mask:0xf bank_mask:0xf
	v_add_f32_dpp v117, v113, v113 row_ror:2 row_mask:0xf bank_mask:0xf
	v_add_f32_dpp v110, v114, v114 row_ror:1 row_mask:0xf bank_mask:0xf
	v_add_f32_dpp v111, v115, v115 row_ror:1 row_mask:0xf bank_mask:0xf
	v_add_f32_dpp v112, v116, v116 row_ror:1 row_mask:0xf bank_mask:0xf
	v_add_f32_dpp v113, v117, v117 row_ror:1 row_mask:0xf bank_mask:0xf
	ds_bpermute_b32 v114, v107, v110
	ds_bpermute_b32 v115, v107, v111
	ds_bpermute_b32 v116, v107, v112
	ds_bpermute_b32 v117, v107, v113
	s_waitcnt lgkmcnt(0)
	v_add_f32_e32 v110, v110, v114
	v_add_f32_e32 v111, v111, v115
	v_add_f32_e32 v112, v112, v116
	v_add_f32_e32 v113, v113, v117
	ds_bpermute_b32 v114, v108, v110
	ds_bpermute_b32 v115, v108, v111
	ds_bpermute_b32 v116, v108, v112
	ds_bpermute_b32 v117, v108, v113
	s_waitcnt lgkmcnt(0)
	v_add_f32_e32 v110, v110, v114
	v_add_f32_e32 v111, v111, v115
	v_add_f32_e32 v112, v112, v116
	v_add_f32_e32 v113, v113, v117
	v_cndmask_b32_e64 v110, v109, v110, s[16:17]
	v_cndmask_b32_e64 v111, v109, v111, s[16:17]
	v_cndmask_b32_e64 v112, v109, v112, s[16:17]
	v_cndmask_b32_e64 v113, v109, v113, s[16:17]
	s_and_saveexec_b64 s[18:19], s[4:5]
	global_store_dword v106, v110, s[14:15]
	s_add_u32 s14, s14, 0x20000
	s_addc_u32 s15, s15, 0
	global_store_dword v106, v111, s[14:15]
	s_add_u32 s14, s14, 0x20000
	s_addc_u32 s15, s15, 0
	global_store_dword v106, v112, s[14:15]
	s_add_u32 s14, s14, 0x20000
	s_addc_u32 s15, s15, 0
	global_store_dword v106, v113, s[14:15]
	s_add_u32 s14, s14, 0x20000
	s_addc_u32 s15, s15, 0
	s_mov_b64 exec, s[18:19]
	global_load_dwordx4 v[176:179], v104, s[10:11] nt
	global_load_dwordx4 v[180:183], v104, s[10:11] offset:1024 nt
	global_load_dwordx4 v[184:187], v104, s[10:11] offset:2048 nt
	global_load_dwordx4 v[188:191], v104, s[10:11] offset:3072 nt
	s_add_u32 s10, s10, 0x800000
	s_addc_u32 s11, s11, 0
	global_load_dwordx4 v[192:195], v104, s[10:11] nt
	global_load_dwordx4 v[196:199], v104, s[10:11] offset:1024 nt
	global_load_dwordx4 v[200:203], v104, s[10:11] offset:2048 nt
	global_load_dwordx4 v[204:207], v104, s[10:11] offset:3072 nt
	s_add_u32 s10, s10, 0x800000
	s_addc_u32 s11, s11, 0
	global_load_dwordx4 v[208:211], v104, s[10:11] nt
	global_load_dwordx4 v[212:215], v104, s[10:11] offset:1024 nt
	global_load_dwordx4 v[216:219], v104, s[10:11] offset:2048 nt
	global_load_dwordx4 v[220:223], v104, s[10:11] offset:3072 nt
	s_add_u32 s10, s10, 0x800000
	s_addc_u32 s11, s11, 0
	global_load_dwordx4 v[224:227], v104, s[10:11] nt
	global_load_dwordx4 v[228:231], v104, s[10:11] offset:1024 nt
	global_load_dwordx4 v[232:235], v104, s[10:11] offset:2048 nt
	global_load_dwordx4 v[236:239], v104, s[10:11] offset:3072 nt
	s_add_u32 s10, s10, 0x800000
	s_addc_u32 s11, s11, 0
	s_waitcnt vmcnt(36)
	v_cvt_pk_bf16_f32 v16, v40, v41
	v_cvt_pk_bf16_f32 v17, v42, v43
	v_cvt_pk_bf16_f32 v18, v44, v45
	v_cvt_pk_bf16_f32 v19, v46, v47
	v_cvt_pk_bf16_f32 v20, v48, v49
	v_cvt_pk_bf16_f32 v21, v50, v51
	v_cvt_pk_bf16_f32 v22, v52, v53
	v_cvt_pk_bf16_f32 v23, v54, v55
	v_mul_f32_e32 v110, v40, v40
	v_fmac_f32_e32 v110, v41, v41
	v_fmac_f32_e32 v110, v42, v42
	v_fmac_f32_e32 v110, v43, v43
	v_fmac_f32_e32 v110, v44, v44
	v_fmac_f32_e32 v110, v45, v45
	v_fmac_f32_e32 v110, v46, v46
	v_fmac_f32_e32 v110, v47, v47
	v_fmac_f32_e32 v110, v48, v48
	v_fmac_f32_e32 v110, v49, v49
	v_fmac_f32_e32 v110, v50, v50
	v_fmac_f32_e32 v110, v51, v51
	v_fmac_f32_e32 v110, v52, v52
	v_fmac_f32_e32 v110, v53, v53
	v_fmac_f32_e32 v110, v54, v54
	v_fmac_f32_e32 v110, v55, v55
	global_store_dwordx2 v105, v[16:17], s[12:13]
	global_store_dwordx2 v105, v[18:19], s[12:13] offset:512
	global_store_dwordx2 v105, v[20:21], s[12:13] offset:1024
	global_store_dwordx2 v105, v[22:23], s[12:13] offset:1536
	s_add_u32 s12, s12, 0x400000
	s_addc_u32 s13, s13, 0
	v_cvt_pk_bf16_f32 v24, v56, v57
	v_cvt_pk_bf16_f32 v25, v58, v59
	v_cvt_pk_bf16_f32 v26, v60, v61
	v_cvt_pk_bf16_f32 v27, v62, v63
	v_cvt_pk_bf16_f32 v28, v64, v65
	v_cvt_pk_bf16_f32 v29, v66, v67
	v_cvt_pk_bf16_f32 v30, v68, v69
	v_cvt_pk_bf16_f32 v31, v70, v71
	v_mul_f32_e32 v111, v56, v56
	v_fmac_f32_e32 v111, v57, v57
	v_fmac_f32_e32 v111, v58, v58
	v_fmac_f32_e32 v111, v59, v59
	v_fmac_f32_e32 v111, v60, v60
	v_fmac_f32_e32 v111, v61, v61
	v_fmac_f32_e32 v111, v62, v62
	v_fmac_f32_e32 v111, v63, v63
; __device__ __forceinline__ unsigned pk2(float lo, float hi) { return f2bf(lo) | (f2bf(hi) << 16); }
; #define lane (hw_lane())
; __device__ __forceinline__ void prologue(const Args& a, LAS unsigned char* lds, int gw, int NGW, int lane, int wave) {
;     ...
;         for (int m = gw; m < M + MMEM; m += NGW) {
;             const bool is_mem = m >= M; const int row = is_mem ? m - M : m;
;             f32x4 v[4]; float s = 0.f;
; #pragma unroll
;             for (int j = 0; j < 4; ++j) v[j] = nv[j];
;             { const int mn = m + NGW; if (mn < M + MMEM) { const f32x4* xr = (const f32x4*)((mn >= M ? a.in[I_MEM] + (size_t)(mn - M) * D : a.in[I_X] + (size_t)mn * D)) + lane;
; #pragma unroll
;                 for (int j = 0; j < 4; ++j) nv[j] = __builtin_nontemporal_load(xr + 64 * j); } }
; #pragma unroll
;             for (int j = 0; j < 4; ++j) s += (v[j].x * v[j].x + v[j].y * v[j].y) + (v[j].z * v[j].z + v[j].w * v[j].w);
;             s = wave_sum(s);
;             float sc = 1.f;
;             if (is_mem) sc = __builtin_amdgcn_rsqf(s * (1.0f / D) + EPS);
;             else if (lane < 16) slots[(size_t)row * 16 + lane] = lane == 0 ? s : 0.f;
;             v2u* o8 = (v2u*)((is_mem ? MEMN : HB) + (size_t)row * D) + lane;
; #pragma unroll
;             for (int j = 0; j < 4; ++j) { v2u o; o.x = pk2(v[j].x * sc, v[j].y * sc); o.y = pk2(v[j].z * sc, v[j].w * sc); o8[64 * j] = o; }
	v_fmac_f32_e32 v111, v64, v64
	v_fmac_f32_e32 v111, v65, v65
	v_fmac_f32_e32 v111, v66, v66
	v_fmac_f32_e32 v111, v67, v67
	v_fmac_f32_e32 v111, v68, v68
	v_fmac_f32_e32 v111, v69, v69
	v_fmac_f32_e32 v111, v70, v70
	v_fmac_f32_e32 v111, v71, v71
	global_store_dwordx2 v105, v[24:25], s[12:13]
	global_store_dwordx2 v105, v[26:27], s[12:13] offset:512
	global_store_dwordx2 v105, v[28:29], s[12:13] offset:1024
	global_store_dwordx2 v105, v[30:31], s[12:13] offset:1536
	s_add_u32 s12, s12, 0x400000
	s_addc_u32 s13, s13, 0
	v_cvt_pk_bf16_f32 v16, v72, v73
	v_cvt_pk_bf16_f32 v17, v74, v75
	v_cvt_pk_bf16_f32 v18, v76, v77
	v_cvt_pk_bf16_f32 v19, v78, v79
	v_cvt_pk_bf16_f32 v20, v80, v81
	v_cvt_pk_bf16_f32 v21, v82, v83
	v_cvt_pk_bf16_f32 v22, v84, v85
	v_cvt_pk_bf16_f32 v23, v86, v87
	v_mul_f32_e32 v112, v72, v72
	v_fmac_f32_e32 v112, v73, v73
	v_fmac_f32_e32 v112, v74, v74
	v_fmac_f32_e32 v112, v75, v75
	v_fmac_f32_e32 v112, v76, v76
	v_fmac_f32_e32 v112, v77, v77
	v_fmac_f32_e32 v112, v78, v78
	v_fmac_f32_e32 v112, v79, v79
	v_fmac_f32_e32 v112, v80, v80
	v_fmac_f32_e32 v112, v81, v81
	v_fmac_f32_e32 v112, v82, v82
	v_fmac_f32_e32 v112, v83, v83
	v_fmac_f32_e32 v112, v84, v84
	v_fmac_f32_e32 v112, v85, v85
	v_fmac_f32_e32 v112, v86, v86
	v_fmac_f32_e32 v112, v87, v87
	global_store_dwordx2 v105, v[16:17], s[12:13]
	global_store_dwordx2 v105, v[18:19], s[12:13] offset:512
	global_store_dwordx2 v105, v[20:21], s[12:13] offset:1024
	global_store_dwordx2 v105, v[22:23], s[12:13] offset:1536
	s_add_u32 s12, s12, 0x400000
	s_addc_u32 s13, s13, 0
	v_cvt_pk_bf16_f32 v24, v88, v89
	v_cvt_pk_bf16_f32 v25, v90, v91
	v_cvt_pk_bf16_f32 v26, v92, v93
	v_cvt_pk_bf16_f32 v27, v94, v95
	v_cvt_pk_bf16_f32 v28, v96, v97
	v_cvt_pk_bf16_f32 v29, v98, v99
	v_cvt_pk_bf16_f32 v30, v100, v101
	v_cvt_pk_bf16_f32 v31, v102, v103
	v_mul_f32_e32 v113, v88, v88
	v_fmac_f32_e32 v113, v89, v89
	v_fmac_f32_e32 v113, v90, v90
	v_fmac_f32_e32 v113, v91, v91
	v_fmac_f32_e32 v113, v92, v92
	v_fmac_f32_e32 v113, v93, v93
	v_fmac_f32_e32 v113, v94, v94
	v_fmac_f32_e32 v113, v95, v95
	v_fmac_f32_e32 v113, v96, v96
	v_fmac_f32_e32 v113, v97, v97
	v_fmac_f32_e32 v113, v98, v98
	v_fmac_f32_e32 v113, v99, v99
	v_fmac_f32_e32 v113, v100, v100
	v_fmac_f32_e32 v113, v101, v101
	v_fmac_f32_e32 v113, v102, v102
	v_fmac_f32_e32 v113, v103, v103
	global_store_dwordx2 v105, v[24:25], s[12:13]
	global_store_dwordx2 v105, v[26:27], s[12:13] offset:512
	global_store_dwordx2 v105, v[28:29], s[12:13] offset:1024
	global_store_dwordx2 v105, v[30:31], s[12:13] offset:1536
	s_add_u32 s12, s12, 0x400000
	s_addc_u32 s13, s13, 0
	v_add_f32_dpp v114, v110, v110 row_ror:8 row_mask:0xf bank_mask:0xf
	v_add_f32_dpp v115, v111, v111 row_ror:8 row_mask:0xf bank_mask:0xf
	v_add_f32_dpp v116, v112, v112 row_ror:8 row_mask:0xf bank_mask:0xf
	v_add_f32_dpp v117, v113, v113 row_ror:8 row_mask:0xf bank_mask:0xf
	v_add_f32_dpp v110, v114, v114 row_ror:4 row_mask:0xf bank_mask:0xf
	v_add_f32_dpp v111, v115, v115 row_ror:4 row_mask:0xf bank_mask:0xf
	v_add_f32_dpp v112, v116, v116 row_ror:4 row_mask:0xf bank_mask:0xf
	v_add_f32_dpp v113, v117, v117 row_ror:4 row_mask:0xf bank_mask:0xf
	v_add_f32_dpp v114, v110, v110 row_ror:2 row_mask:0xf bank_mask:0xf
	v_add_f32_dpp v115, v111, v111 row_ror:2 row_mask:0xf bank_mask:0xf
	v_add_f32_dpp v116, v112, v112 row_ror:2 row_mask:0xf bank_mask:0xf
	v_add_f32_dpp v117, v113, v113 row_ror:2 row_mask:0xf bank_mask:0xf
	v_add_f32_dpp v110, v114, v114 row_ror:1 row_mask:0xf bank_mask:0xf
	v_add_f32_dpp v111, v115, v115 row_ror:1 row_mask:0xf bank_mask:0xf
	v_add_f32_dpp v112, v116, v116 row_ror:1 row_mask:0xf bank_mask:0xf
	v_add_f32_dpp v113, v117, v117 row_ror:1 row_mask:0xf bank_mask:0xf
	ds_bpermute_b32 v114, v107, v110
	ds_bpermute_b32 v115, v107, v111
	ds_bpermute_b32 v116, v107, v112
	ds_bpermute_b32 v117, v107, v113
	s_waitcnt lgkmcnt(0)
	v_add_f32_e32 v110, v110, v114
	v_add_f32_e32 v111, v111, v115
	v_add_f32_e32 v112, v112, v116
	v_add_f32_e32 v113, v113, v117
	ds_bpermute_b32 v114, v108, v110
	ds_bpermute_b32 v115, v108, v111
	ds_bpermute_b32 v116, v108, v112
	ds_bpermute_b32 v117, v108, v113
	s_waitcnt lgkmcnt(0)
	v_add_f32_e32 v110, v110, v114
	v_add_f32_e32 v111, v111, v115
	v_add_f32_e32 v112, v112, v116
	v_add_f32_e32 v113, v113, v117
	v_cndmask_b32_e64 v110, v109, v110, s[16:17]
	v_cndmask_b32_e64 v111, v109, v111, s[16:17]
	v_cndmask_b32_e64 v112, v109, v112, s[16:17]
	v_cndmask_b32_e64 v113, v109, v113, s[16:17]
	s_and_saveexec_b64 s[18:19], s[4:5]
	global_store_dword v106, v110, s[14:15]
	s_add_u32 s14, s14, 0x20000
	s_addc_u32 s15, s15, 0
	global_store_dword v106, v111, s[14:15]
	s_add_u32 s14, s14, 0x20000
	s_addc_u32 s15, s15, 0
	global_store_dword v106, v112, s[14:15]
	s_add_u32 s14, s14, 0x20000
	s_addc_u32 s15, s15, 0
	global_store_dword v106, v113, s[14:15]
	s_add_u32 s14, s14, 0x20000
	s_addc_u32 s15, s15, 0
	s_mov_b64 exec, s[18:19]
	s_waitcnt vmcnt(20)
; __device__ __forceinline__ unsigned pk2(float lo, float hi) { return f2bf(lo) | (f2bf(hi) << 16); }
; #define lane (hw_lane())
; __device__ __forceinline__ void prologue(const Args& a, LAS unsigned char* lds, int gw, int NGW, int lane, int wave) {
;     ...
;         for (int m = gw; m < M + MMEM; m += NGW) {
;             const bool is_mem = m >= M; const int row = is_mem ? m - M : m;
;             f32x4 v[4]; float s = 0.f;
; #pragma unroll
;             for (int j = 0; j < 4; ++j) v[j] = nv[j];
;             { const int mn = m + NGW; if (mn < M + MMEM) { const f32x4* xr = (const f32x4*)((mn >= M ? a.in[I_MEM] + (size_t)(mn - M) * D : a.in[I_X] + (size_t)mn * D)) + lane;
; #pragma unroll
;                 for (int j = 0; j < 4; ++j) nv[j] = __builtin_nontemporal_load(xr + 64 * j); } }
; #pragma unroll
;             for (int j = 0; j < 4; ++j) s += (v[j].x * v[j].x + v[j].y * v[j].y) + (v[j].z * v[j].z + v[j].w * v[j].w);
;             s = wave_sum(s);
;             float sc = 1.f;
;             if (is_mem) sc = __builtin_amdgcn_rsqf(s * (1.0f / D) + EPS);
;             else if (lane < 16) slots[(size_t)row * 16 + lane] = lane == 0 ? s : 0.f;
;             v2u* o8 = (v2u*)((is_mem ? MEMN : HB) + (size_t)row * D) + lane;
; #pragma unroll
;             for (int j = 0; j < 4; ++j) { v2u o; o.x = pk2(v[j].x * sc, v[j].y * sc); o.y = pk2(v[j].z * sc, v[j].w * sc); o8[64 * j] = o; }
	v_cvt_pk_bf16_f32 v16, v176, v177
	v_cvt_pk_bf16_f32 v17, v178, v179
	v_cvt_pk_bf16_f32 v18, v180, v181
	v_cvt_pk_bf16_f32 v19, v182, v183
	v_cvt_pk_bf16_f32 v20, v184, v185
	v_cvt_pk_bf16_f32 v21, v186, v187
	v_cvt_pk_bf16_f32 v22, v188, v189
	v_cvt_pk_bf16_f32 v23, v190, v191
	v_mul_f32_e32 v110, v176, v176
	v_fmac_f32_e32 v110, v177, v177
	v_fmac_f32_e32 v110, v178, v178
	v_fmac_f32_e32 v110, v179, v179
	v_fmac_f32_e32 v110, v180, v180
	v_fmac_f32_e32 v110, v181, v181
	v_fmac_f32_e32 v110, v182, v182
	v_fmac_f32_e32 v110, v183, v183
	v_fmac_f32_e32 v110, v184, v184
	v_fmac_f32_e32 v110, v185, v185
	v_fmac_f32_e32 v110, v186, v186
	v_fmac_f32_e32 v110, v187, v187
	v_fmac_f32_e32 v110, v188, v188
	v_fmac_f32_e32 v110, v189, v189
	v_fmac_f32_e32 v110, v190, v190
	v_fmac_f32_e32 v110, v191, v191
	global_store_dwordx2 v105, v[16:17], s[12:13]
	global_store_dwordx2 v105, v[18:19], s[12:13] offset:512
	global_store_dwordx2 v105, v[20:21], s[12:13] offset:1024
	global_store_dwordx2 v105, v[22:23], s[12:13] offset:1536
	s_add_u32 s12, s12, 0x400000
	s_addc_u32 s13, s13, 0
	v_cvt_pk_bf16_f32 v24, v192, v193
	v_cvt_pk_bf16_f32 v25, v194, v195
	v_cvt_pk_bf16_f32 v26, v196, v197
	v_cvt_pk_bf16_f32 v27, v198, v199
	v_cvt_pk_bf16_f32 v28, v200, v201
	v_cvt_pk_bf16_f32 v29, v202, v203
	v_cvt_pk_bf16_f32 v30, v204, v205
	v_cvt_pk_bf16_f32 v31, v206, v207
	v_mul_f32_e32 v111, v192, v192
	v_fmac_f32_e32 v111, v193, v193
	v_fmac_f32_e32 v111, v194, v194
	v_fmac_f32_e32 v111, v195, v195
	v_fmac_f32_e32 v111, v196, v196
	v_fmac_f32_e32 v111, v197, v197
	v_fmac_f32_e32 v111, v198, v198
	v_fmac_f32_e32 v111, v199, v199
	v_fmac_f32_e32 v111, v200, v200
	v_fmac_f32_e32 v111, v201, v201
	v_fmac_f32_e32 v111, v202, v202
	v_fmac_f32_e32 v111, v203, v203
	v_fmac_f32_e32 v111, v204, v204
	v_fmac_f32_e32 v111, v205, v205
	v_fmac_f32_e32 v111, v206, v206
	v_fmac_f32_e32 v111, v207, v207
	global_store_dwordx2 v105, v[24:25], s[12:13]
	global_store_dwordx2 v105, v[26:27], s[12:13] offset:512
	global_store_dwordx2 v105, v[28:29], s[12:13] offset:1024
	global_store_dwordx2 v105, v[30:31], s[12:13] offset:1536
	s_add_u32 s12, s12, 0x400000
	s_addc_u32 s13, s13, 0
	v_cvt_pk_bf16_f32 v16, v208, v209
	v_cvt_pk_bf16_f32 v17, v210, v211
	v_cvt_pk_bf16_f32 v18, v212, v213
	v_cvt_pk_bf16_f32 v19, v214, v215
	v_cvt_pk_bf16_f32 v20, v216, v217
	v_cvt_pk_bf16_f32 v21, v218, v219
	v_cvt_pk_bf16_f32 v22, v220, v221
	v_cvt_pk_bf16_f32 v23, v222, v223
	v_mul_f32_e32 v112, v208, v208
	v_fmac_f32_e32 v112, v209, v209
	v_fmac_f32_e32 v112, v210, v210
	v_fmac_f32_e32 v112, v211, v211
	v_fmac_f32_e32 v112, v212, v212
	v_fmac_f32_e32 v112, v213, v213
	v_fmac_f32_e32 v112, v214, v214
	v_fmac_f32_e32 v112, v215, v215
	v_fmac_f32_e32 v112, v216, v216
	v_fmac_f32_e32 v112, v217, v217
	v_fmac_f32_e32 v112, v218, v218
	v_fmac_f32_e32 v112, v219, v219
	v_fmac_f32_e32 v112, v220, v220
	v_fmac_f32_e32 v112, v221, v221
	v_fmac_f32_e32 v112, v222, v222
	v_fmac_f32_e32 v112, v223, v223
	global_store_dwordx2 v105, v[16:17], s[12:13]
	global_store_dwordx2 v105, v[18:19], s[12:13] offset:512
	global_store_dwordx2 v105, v[20:21], s[12:13] offset:1024
	global_store_dwordx2 v105, v[22:23], s[12:13] offset:1536
	s_add_u32 s12, s12, 0x400000
	s_addc_u32 s13, s13, 0
	v_cvt_pk_bf16_f32 v24, v224, v225
	v_cvt_pk_bf16_f32 v25, v226, v227
	v_cvt_pk_bf16_f32 v26, v228, v229
	v_cvt_pk_bf16_f32 v27, v230, v231
	v_cvt_pk_bf16_f32 v28, v232, v233
	v_cvt_pk_bf16_f32 v29, v234, v235
	v_cvt_pk_bf16_f32 v30, v236, v237
	v_cvt_pk_bf16_f32 v31, v238, v239
	v_mul_f32_e32 v113, v224, v224
	v_fmac_f32_e32 v113, v225, v225
	v_fmac_f32_e32 v113, v226, v226
	v_fmac_f32_e32 v113, v227, v227
	v_fmac_f32_e32 v113, v228, v228
	v_fmac_f32_e32 v113, v229, v229
	v_fmac_f32_e32 v113, v230, v230
	v_fmac_f32_e32 v113, v231, v231
	v_fmac_f32_e32 v113, v232, v232
	v_fmac_f32_e32 v113, v233, v233
	v_fmac_f32_e32 v113, v234, v234
	v_fmac_f32_e32 v113, v235, v235
	v_fmac_f32_e32 v113, v236, v236
	v_fmac_f32_e32 v113, v237, v237
	v_fmac_f32_e32 v113, v238, v238
	v_fmac_f32_e32 v113, v239, v239
	global_store_dwordx2 v105, v[24:25], s[12:13]
	global_store_dwordx2 v105, v[26:27], s[12:13] offset:512
	global_store_dwordx2 v105, v[28:29], s[12:13] offset:1024
	global_store_dwordx2 v105, v[30:31], s[12:13] offset:1536
	s_add_u32 s12, s12, 0x400000
	s_addc_u32 s13, s13, 0
	v_add_f32_dpp v114, v110, v110 row_ror:8 row_mask:0xf bank_mask:0xf
	v_add_f32_dpp v115, v111, v111 row_ror:8 row_mask:0xf bank_mask:0xf
	v_add_f32_dpp v116, v112, v112 row_ror:8 row_mask:0xf bank_mask:0xf
	v_add_f32_dpp v117, v113, v113 row_ror:8 row_mask:0xf bank_mask:0xf
	v_add_f32_dpp v110, v114, v114 row_ror:4 row_mask:0xf bank_mask:0xf
	v_add_f32_dpp v111, v115, v115 row_ror:4 row_mask:0xf bank_mask:0xf
	v_add_f32_dpp v112, v116, v116 row_ror:4 row_mask:0xf bank_mask:0xf
	v_add_f32_dpp v113, v117, v117 row_ror:4 row_mask:0xf bank_mask:0xf
	v_add_f32_dpp v114, v110, v110 row_ror:2 row_mask:0xf bank_mask:0xf
	v_add_f32_dpp v115, v111, v111 row_ror:2 row_mask:0xf bank_mask:0xf
	v_add_f32_dpp v116, v112, v112 row_ror:2 row_mask:0xf bank_mask:0xf
	v_add_f32_dpp v117, v113, v113 row_ror:2 row_mask:0xf bank_mask:0xf
	v_add_f32_dpp v110, v114, v114 row_ror:1 row_mask:0xf bank_mask:0xf
	v_add_f32_dpp v111, v115, v115 row_ror:1 row_mask:0xf bank_mask:0xf
	v_add_f32_dpp v112, v116, v116 row_ror:1 row_mask:0xf bank_mask:0xf
	v_add_f32_dpp v113, v117, v117 row_ror:1 row_mask:0xf bank_mask:0xf
	ds_bpermute_b32 v114, v107, v110
	ds_bpermute_b32 v115, v107, v111
	ds_bpermute_b32 v116, v107, v112
	ds_bpermute_b32 v117, v107, v113
	s_waitcnt lgkmcnt(0)
	v_add_f32_e32 v110, v110, v114
	v_add_f32_e32 v111, v111, v115
	v_add_f32_e32 v112, v112, v116
	v_add_f32_e32 v113, v113, v117
	ds_bpermute_b32 v114, v108, v110
	ds_bpermute_b32 v115, v108, v111
	ds_bpermute_b32 v116, v108, v112
	ds_bpermute_b32 v117, v108, v113
	s_waitcnt lgkmcnt(0)
	v_add_f32_e32 v110, v110, v114
	v_add_f32_e32 v111, v111, v115
	v_add_f32_e32 v112, v112, v116
	v_add_f32_e32 v113, v113, v117
	v_cndmask_b32_e64 v110, v109, v110, s[16:17]
	v_cndmask_b32_e64 v111, v109, v111, s[16:17]
	v_cndmask_b32_e64 v112, v109, v112, s[16:17]
	v_cndmask_b32_e64 v113, v109, v113, s[16:17]
	s_and_saveexec_b64 s[18:19], s[4:5]
	global_store_dword v106, v110, s[14:15]
	s_add_u32 s14, s14, 0x20000
	s_addc_u32 s15, s15, 0
	global_store_dword v106, v111, s[14:15]
	s_add_u32 s14, s14, 0x20000
	s_addc_u32 s15, s15, 0
	global_store_dword v106, v112, s[14:15]
	s_add_u32 s14, s14, 0x20000
	s_addc_u32 s15, s15, 0
	global_store_dword v106, v113, s[14:15]
	s_add_u32 s14, s14, 0x20000
	s_addc_u32 s15, s15, 0
	s_mov_b64 exec, s[18:19]
.Lxh_done:
	s_lshl_b32 s98, s38, 5
	s_add_i32 s72, s72, s98
